# roped GEMM epilogues (diff / retention in-proj): 4 rope-table loads per row block issued together instead of 3 dependent round trips
# baseline (speedup 1.0000x reference)
;     template <int NQ> __device__ __forceinline__ void roped(const float* rope, const f32x4 (&acc)[2][2][4][2], int row0, bool is_ctx, int rowb  , int axis, int j0,
;                                                              bf16_t* dst, int ld, int c1, int dx2, float sc, int cz  ) const {
;     ...
;                 if (!is_ctx) { const int t = row - rowb, pos = axis ? (t & 63) : (t >> 6); const f32x4* tp = (const f32x4*)(rope + (size_t)(pos * NQ + j0) * 2);
; #pragma unroll
;                     for (int q = 0; q < 4; ++q) { const f32x4 cs = tp[q];
; #pragma unroll
;                         for (int hh = 0; hh < 2; ++hh) { const int e = 2 * q + hh; const float c = hh ? cs[2] : cs[0], s = hh ? cs[3] : cs[1];
;                             const float x1 = acc[ai][0][m][e >> 2][e & 3], x2 = acc[ai][1][m][e >> 2][e & 3];
;                             y1[e] = (x1 * c - x2 * s) * sc; y2[e] = (x2 * c + x1 * s) * sc; } }
;     __device__ __forceinline__ void operator()(const f32x4 (&acc)[2][2][4][2], const Unit& u, int wr, int wc, int fr, int fq) const {
;     ...
;             if (u.pn < 8) { const int axis = wc >> 1, j0 = (wc & 1) * 32 + 8 * fq;
;                 if (u.pn < 4) roped<64>(rope, acc, row0, is_ctx, rowb, axis, j0, (bf16_t*)BIG, 1024, u.pn * 256 + axis * 128 + j0, 64, 1.f, -1);
;                 else roped<64>(rope, acc, row0, is_ctx, rowb, axis, j0, (bf16_t*)(BIG + U1), 1024, (u.pn - 4) * 256 + axis * 128 + j0, 64, 0.0625f, -1);
.LBB0_276:
	s_andn2_b64 vcc, exec, s[10:11]
	s_cbranch_vccnz .LBB0_345
	v_readlane_b32 s10, v255, 27
	s_lshl_b32 s36, s95, 8
	s_cmp_gt_i32 s95, 3
	v_lshl_add_u32 v144, v204, 3, s10
	s_mov_b64 s[10:11], -1
	s_cbranch_scc0 .LBB0_311
	s_and_b64 vcc, exec, s[56:57]
	s_cbranch_vccz .LBB0_280
	v_subrev_u32_e32 v128, s61, v166
	v_and_b32_e32 v129, 63, v205
	v_lshrrev_b32_e32 v128, 6, v128
	v_cndmask_b32_e64 v128, v129, v128, s[6:7]
	v_lshl_add_u32 v128, v128, 6, v144
	v_ashrrev_i32_e32 v129, 31, v128
	v_lshl_add_u64 v[138:139], v[128:129], 3, s[30:31]
	flat_load_dwordx4 v[128:131], v[138:139]
	flat_load_dwordx4 v[168:171], v[138:139] offset:48
	flat_load_dwordx4 v[208:211], v[138:139] offset:16
	flat_load_dwordx4 v[212:215], v[138:139] offset:32
	s_mov_b64 s[10:11], 0
	s_waitcnt vmcnt(0) lgkmcnt(0)
	v_mov_b32_e32 v140, v128
	v_mov_b32_e32 v141, v130
	v_mov_b32_e32 v130, v129
	v_pk_mul_f32 v[132:133], v[116:117], v[140:141]
	v_pk_mul_f32 v[128:129], v[116:117], v[130:131]
	v_pk_fma_f32 v[130:131], v[124:125], v[130:131], v[132:133]
	v_mov_b32_e32 v132, v208
	v_mov_b32_e32 v133, v209
	v_mov_b32_e32 v134, v210
	v_mov_b32_e32 v135, v211
	v_mul_f32_e32 v178, v122, v168
	v_mul_f32_e32 v180, v114, v169
	v_pk_mul_f32 v[130:131], v[130:131], s[76:77] op_sel_hi:[1,0]
	s_waitcnt vmcnt(0) lgkmcnt(0)
	v_mov_b32_e32 v142, v132
	v_mov_b32_e32 v143, v134
	v_mov_b32_e32 v134, v133
	v_pk_mul_f32 v[132:133], v[118:119], v[142:143]
	v_pk_mul_f32 v[172:173], v[118:119], v[134:135]
	v_pk_fma_f32 v[132:133], v[126:127], v[134:135], v[132:133]
	v_mov_b32_e32 v134, v212
	v_mov_b32_e32 v135, v213
	v_mov_b32_e32 v136, v214
	v_mov_b32_e32 v137, v215
	v_pk_mul_f32 v[132:133], v[132:133], s[76:77] op_sel_hi:[1,0]
	v_pk_fma_f32 v[138:139], v[126:127], v[142:143], v[172:173] neg_lo:[0,0,1] neg_hi:[0,0,1]
	s_waitcnt vmcnt(0) lgkmcnt(0)
	v_mov_b32_e32 v174, v134
	v_mov_b32_e32 v175, v136
	v_mov_b32_e32 v136, v135
	v_pk_mul_f32 v[134:135], v[112:113], v[174:175]
	v_pk_mul_f32 v[176:177], v[112:113], v[136:137]
	v_pk_fma_f32 v[134:135], v[120:121], v[136:137], v[134:135]
	v_mov_b32_e32 v136, v114
	v_mov_b32_e32 v137, v122
	v_pk_mul_f32 v[136:137], v[136:137], v[168:169]
	v_pk_mul_f32 v[134:135], v[134:135], s[76:77] op_sel_hi:[1,0]
	v_add_f32_e32 v136, v137, v136
	v_mul_f32_e32 v159, 0x3d800000, v136
	v_mov_b32_e32 v136, v123
	v_mov_b32_e32 v137, v115
	v_pk_mul_f32 v[136:137], v[136:137], v[170:171]
	s_nop 0
	v_mov_b32_e32 v179, v136
	v_mov_b32_e32 v181, v137
	v_pk_fma_f32 v[136:137], v[124:125], v[140:141], v[128:129] neg_lo:[0,0,1] neg_hi:[0,0,1]
	v_mov_b32_e32 v128, v115
	v_mov_b32_e32 v129, v123
	v_pk_mul_f32 v[128:129], v[128:129], v[170:171]
	v_pk_fma_f32 v[140:141], v[120:121], v[174:175], v[176:177] neg_lo:[0,0,1] neg_hi:[0,0,1]
	v_pk_add_f32 v[142:143], v[178:179], v[180:181] neg_lo:[0,1] neg_hi:[0,1]
	v_add_f32_e32 v167, v129, v128

; __device__ __forceinline__ u32x4 pack8(const float* v) { u32x4 w; w.x = cvt_pk_bf16(v[0], v[1]); w.y = cvt_pk_bf16(v[2], v[3]); w.z = cvt_pk_bf16(v[4], v[5]); w.w = cvt_pk_bf16(v[6], v[7]); return w; }
;     template <int NQ> __device__ __forceinline__ void roped(const float* rope, const f32x4 (&acc)[2][2][4][2], int row0, bool is_ctx, int rowb  , int axis, int j0,
;                                                              bf16_t* dst, int ld, int c1, int dx2, float sc, int cz  ) const {
;     ...
;                 if (!is_ctx) { const int t = row - rowb, pos = axis ? (t & 63) : (t >> 6); const f32x4* tp = (const f32x4*)(rope + (size_t)(pos * NQ + j0) * 2);
; #pragma unroll
;                     for (int q = 0; q < 4; ++q) { const f32x4 cs = tp[q];
; #pragma unroll
;                         for (int hh = 0; hh < 2; ++hh) { const int e = 2 * q + hh; const float c = hh ? cs[2] : cs[0], s = hh ? cs[3] : cs[1];
;                             const float x1 = acc[ai][0][m][e >> 2][e & 3], x2 = acc[ai][1][m][e >> 2][e & 3];
;                             y1[e] = (x1 * c - x2 * s) * sc; y2[e] = (x2 * c + x1 * s) * sc; } }
;                 } else {
; #pragma unroll
;                     for (int e = 0; e < 8; ++e) { y1[e] = acc[ai][0][m][e >> 2][e & 3] * sc; y2[e] = acc[ai][1][m][e >> 2][e & 3] * sc; }
;                 }
;                 bf16_t* rp = dst + (size_t)row * ld;
;                 *(u32x4*)(rp + c1) = pack8(y1); *(u32x4*)(rp + c1 + dx2) = pack8(y2);
.LBB0_282:
	s_add_i32 s10, s63, s36
	v_add_u32_e32 v128, s10, v144
	v_readlane_b32 s10, v255, 1
	v_ashrrev_i32_e32 v129, 31, v128
	v_readlane_b32 s11, v255, 2
	v_mul_f32_e32 v170, 0x3d800000, v167
	v_ashrrev_i32_e32 v167, 31, v166
	v_lshl_add_u64 v[128:129], v[128:129], 1, s[10:11]
	v_pk_mul_f32 v[142:143], v[142:143], s[76:77] op_sel_hi:[1,0]
	v_pk_mul_f32 v[140:141], v[140:141], s[76:77] op_sel_hi:[1,0]
	v_pk_mul_f32 v[138:139], v[138:139], s[76:77] op_sel_hi:[1,0]
	v_pk_mul_f32 v[136:137], v[136:137], s[76:77] op_sel_hi:[1,0]
	v_lshlrev_b64 v[168:169], 11, v[166:167]
	v_cvt_pk_bf16_f32 v136, v136, v137
	v_cvt_pk_bf16_f32 v137, v138, v139
	v_cvt_pk_bf16_f32 v138, v140, v141
	v_cvt_pk_bf16_f32 v139, v142, v143
	v_lshl_add_u64 v[140:141], v[128:129], 0, v[168:169]
	v_cvt_pk_bf16_f32 v130, v130, v131
	v_cvt_pk_bf16_f32 v131, v132, v133
	v_cvt_pk_bf16_f32 v132, v134, v135
	v_cvt_pk_bf16_f32 v133, v159, v170
	flat_store_dwordx4 v[140:141], v[136:139]
	flat_store_dwordx4 v[140:141], v[130:133] offset:128
	s_andn2_b64 vcc, exec, s[56:57]
	s_mov_b64 s[14:15], -1
	v_cndmask_b32_e64 v131, 0, 1, s[56:57]
	v_add_u32_e32 v130, 16, v166
	v_cmp_ne_u32_e64 s[10:11], 1, v131
	s_cbranch_vccnz .LBB0_284
	v_subrev_u32_e32 v131, s61, v130
	v_and_b32_e32 v132, 63, v130
	v_lshrrev_b32_e32 v131, 6, v131
	v_cndmask_b32_e64 v131, v132, v131, s[6:7]
	v_lshl_add_u32 v132, v131, 6, v144
	v_ashrrev_i32_e32 v133, 31, v132
	v_lshl_add_u64 v[140:141], v[132:133], 3, s[30:31]
	flat_load_dwordx4 v[132:135], v[140:141]
	flat_load_dwordx4 v[168:171], v[140:141] offset:48
	flat_load_dwordx4 v[208:211], v[140:141] offset:16
	flat_load_dwordx4 v[212:215], v[140:141] offset:32
	s_mov_b64 s[14:15], 0
	s_waitcnt vmcnt(0) lgkmcnt(0)
	v_mov_b32_e32 v142, v132
	v_mov_b32_e32 v143, v134
	v_mov_b32_e32 v134, v133
	v_pk_mul_f32 v[132:133], v[100:101], v[142:143]
	v_pk_mul_f32 v[172:173], v[100:101], v[134:135]
	v_pk_fma_f32 v[132:133], v[108:109], v[134:135], v[132:133]
	v_mov_b32_e32 v134, v208
	v_mov_b32_e32 v135, v209
	v_mov_b32_e32 v136, v210
	v_mov_b32_e32 v137, v211
	v_mul_f32_e32 v182, v106, v168
	v_mul_f32_e32 v184, v98, v169
	v_pk_mul_f32 v[132:133], v[132:133], s[76:77] op_sel_hi:[1,0]
	s_waitcnt vmcnt(0) lgkmcnt(0)
	v_mov_b32_e32 v174, v134
	v_mov_b32_e32 v175, v136
	v_mov_b32_e32 v136, v135
	v_pk_mul_f32 v[134:135], v[102:103], v[174:175]
	v_pk_mul_f32 v[176:177], v[102:103], v[136:137]
	v_pk_fma_f32 v[134:135], v[110:111], v[136:137], v[134:135]
	v_mov_b32_e32 v136, v212
	v_mov_b32_e32 v137, v213
	v_mov_b32_e32 v138, v214
	v_mov_b32_e32 v139, v215
	v_pk_mul_f32 v[134:135], v[134:135], s[76:77] op_sel_hi:[1,0]
	v_pk_fma_f32 v[140:141], v[110:111], v[174:175], v[176:177] neg_lo:[0,0,1] neg_hi:[0,0,1]
	s_waitcnt vmcnt(0) lgkmcnt(0)
	v_mov_b32_e32 v178, v136
	v_mov_b32_e32 v179, v138
	v_mov_b32_e32 v138, v137
	v_pk_mul_f32 v[136:137], v[96:97], v[178:179]
	v_pk_mul_f32 v[180:181], v[96:97], v[138:139]
	v_pk_fma_f32 v[136:137], v[104:105], v[138:139], v[136:137]
	v_mov_b32_e32 v138, v98
	v_mov_b32_e32 v139, v106
	v_pk_mul_f32 v[138:139], v[138:139], v[168:169]
	v_pk_mul_f32 v[136:137], v[136:137], s[76:77] op_sel_hi:[1,0]
	v_add_f32_e32 v131, v139, v138
	v_mov_b32_e32 v138, v107
	v_mov_b32_e32 v139, v99
	v_pk_mul_f32 v[138:139], v[138:139], v[170:171]
	v_mul_f32_e32 v159, 0x3d800000, v131
	v_mov_b32_e32 v183, v138
	v_mov_b32_e32 v185, v139
	v_pk_fma_f32 v[138:139], v[108:109], v[142:143], v[172:173] neg_lo:[0,0,1] neg_hi:[0,0,1]
	v_mov_b32_e32 v172, v99
	v_mov_b32_e32 v173, v107
	v_pk_mul_f32 v[170:171], v[172:173], v[170:171]
	v_pk_fma_f32 v[142:143], v[104:105], v[178:179], v[180:181] neg_lo:[0,0,1] neg_hi:[0,0,1]
	v_pk_add_f32 v[168:169], v[182:183], v[184:185] neg_lo:[0,1] neg_hi:[0,1]
	v_add_f32_e32 v131, v171, v170

; __device__ __forceinline__ u32x4 pack8(const float* v) { u32x4 w; w.x = cvt_pk_bf16(v[0], v[1]); w.y = cvt_pk_bf16(v[2], v[3]); w.z = cvt_pk_bf16(v[4], v[5]); w.w = cvt_pk_bf16(v[6], v[7]); return w; }
;     template <int NQ> __device__ __forceinline__ void roped(const float* rope, const f32x4 (&acc)[2][2][4][2], int row0, bool is_ctx, int rowb  , int axis, int j0,
;                                                              bf16_t* dst, int ld, int c1, int dx2, float sc, int cz  ) const {
;     ...
;                 if (!is_ctx) { const int t = row - rowb, pos = axis ? (t & 63) : (t >> 6); const f32x4* tp = (const f32x4*)(rope + (size_t)(pos * NQ + j0) * 2);
; #pragma unroll
;                     for (int q = 0; q < 4; ++q) { const f32x4 cs = tp[q];
; #pragma unroll
;                         for (int hh = 0; hh < 2; ++hh) { const int e = 2 * q + hh; const float c = hh ? cs[2] : cs[0], s = hh ? cs[3] : cs[1];
;                             const float x1 = acc[ai][0][m][e >> 2][e & 3], x2 = acc[ai][1][m][e >> 2][e & 3];
;                             y1[e] = (x1 * c - x2 * s) * sc; y2[e] = (x2 * c + x1 * s) * sc; } }
;                 } else {
; #pragma unroll
;                     for (int e = 0; e < 8; ++e) { y1[e] = acc[ai][0][m][e >> 2][e & 3] * sc; y2[e] = acc[ai][1][m][e >> 2][e & 3] * sc; }
;                 }
;                 bf16_t* rp = dst + (size_t)row * ld;
;                 *(u32x4*)(rp + c1) = pack8(y1); *(u32x4*)(rp + c1 + dx2) = pack8(y2);
.LBB0_286:
	v_mul_f32_e32 v167, 0x3d800000, v131
	v_ashrrev_i32_e32 v131, 31, v130
	v_pk_mul_f32 v[168:169], v[168:169], s[76:77] op_sel_hi:[1,0]
	v_pk_mul_f32 v[142:143], v[142:143], s[76:77] op_sel_hi:[1,0]
	v_pk_mul_f32 v[140:141], v[140:141], s[76:77] op_sel_hi:[1,0]
	v_pk_mul_f32 v[138:139], v[138:139], s[76:77] op_sel_hi:[1,0]
	v_lshlrev_b64 v[130:131], 11, v[130:131]
	v_cvt_pk_bf16_f32 v138, v138, v139
	v_cvt_pk_bf16_f32 v139, v140, v141
	v_cvt_pk_bf16_f32 v140, v142, v143
	v_cvt_pk_bf16_f32 v141, v168, v169
	v_lshl_add_u64 v[142:143], v[128:129], 0, v[130:131]
	v_cvt_pk_bf16_f32 v130, v132, v133
	v_cvt_pk_bf16_f32 v131, v134, v135
	v_cvt_pk_bf16_f32 v132, v136, v137
	v_cvt_pk_bf16_f32 v133, v159, v167
	flat_store_dwordx4 v[142:143], v[138:141]
	flat_store_dwordx4 v[142:143], v[130:133] offset:128
	s_and_b64 vcc, exec, s[10:11]
	s_mov_b64 s[14:15], -1
	v_add_u32_e32 v130, 32, v166
	s_cbranch_vccnz .LBB0_288
	v_subrev_u32_e32 v131, s61, v130
	v_and_b32_e32 v132, 63, v130
	v_lshrrev_b32_e32 v131, 6, v131
	v_cndmask_b32_e64 v131, v132, v131, s[6:7]
	v_lshl_add_u32 v132, v131, 6, v144
	v_ashrrev_i32_e32 v133, 31, v132
	v_lshl_add_u64 v[140:141], v[132:133], 3, s[30:31]
	flat_load_dwordx4 v[132:135], v[140:141]
	flat_load_dwordx4 v[168:171], v[140:141] offset:48
	flat_load_dwordx4 v[208:211], v[140:141] offset:16
	flat_load_dwordx4 v[212:215], v[140:141] offset:32
	s_mov_b64 s[14:15], 0
	s_waitcnt vmcnt(0) lgkmcnt(0)
	v_mov_b32_e32 v142, v132
	v_mov_b32_e32 v143, v134
	v_mov_b32_e32 v134, v133
	v_pk_mul_f32 v[132:133], v[84:85], v[142:143]
	v_pk_mul_f32 v[172:173], v[84:85], v[134:135]
	v_pk_fma_f32 v[132:133], v[92:93], v[134:135], v[132:133]
	v_mov_b32_e32 v134, v208
	v_mov_b32_e32 v135, v209
	v_mov_b32_e32 v136, v210
	v_mov_b32_e32 v137, v211
	v_mul_f32_e32 v182, v90, v168
	v_mul_f32_e32 v184, v82, v169
	v_pk_mul_f32 v[132:133], v[132:133], s[76:77] op_sel_hi:[1,0]
	s_waitcnt vmcnt(0) lgkmcnt(0)
	v_mov_b32_e32 v174, v134
	v_mov_b32_e32 v175, v136
	v_mov_b32_e32 v136, v135
	v_pk_mul_f32 v[134:135], v[86:87], v[174:175]
	v_pk_mul_f32 v[176:177], v[86:87], v[136:137]
	v_pk_fma_f32 v[134:135], v[94:95], v[136:137], v[134:135]
	v_mov_b32_e32 v136, v212
	v_mov_b32_e32 v137, v213
	v_mov_b32_e32 v138, v214
	v_mov_b32_e32 v139, v215
	v_pk_mul_f32 v[134:135], v[134:135], s[76:77] op_sel_hi:[1,0]
	v_pk_fma_f32 v[140:141], v[94:95], v[174:175], v[176:177] neg_lo:[0,0,1] neg_hi:[0,0,1]
	s_waitcnt vmcnt(0) lgkmcnt(0)
	v_mov_b32_e32 v178, v136
	v_mov_b32_e32 v179, v138
	v_mov_b32_e32 v138, v137
	v_pk_mul_f32 v[136:137], v[80:81], v[178:179]
	v_pk_mul_f32 v[180:181], v[80:81], v[138:139]
	v_pk_fma_f32 v[136:137], v[88:89], v[138:139], v[136:137]
	v_mov_b32_e32 v138, v82
	v_mov_b32_e32 v139, v90
	v_pk_mul_f32 v[138:139], v[138:139], v[168:169]
	v_pk_mul_f32 v[136:137], v[136:137], s[76:77] op_sel_hi:[1,0]
	v_add_f32_e32 v131, v139, v138
	v_mov_b32_e32 v138, v91
	v_mov_b32_e32 v139, v83
	v_pk_mul_f32 v[138:139], v[138:139], v[170:171]
	v_mul_f32_e32 v159, 0x3d800000, v131
	v_mov_b32_e32 v183, v138
	v_mov_b32_e32 v185, v139
	v_pk_fma_f32 v[138:139], v[92:93], v[142:143], v[172:173] neg_lo:[0,0,1] neg_hi:[0,0,1]
	v_mov_b32_e32 v172, v83
	v_mov_b32_e32 v173, v91
	v_pk_mul_f32 v[170:171], v[172:173], v[170:171]
	v_pk_fma_f32 v[142:143], v[88:89], v[178:179], v[180:181] neg_lo:[0,0,1] neg_hi:[0,0,1]
	v_pk_add_f32 v[168:169], v[182:183], v[184:185] neg_lo:[0,1] neg_hi:[0,1]
	v_add_f32_e32 v131, v171, v170

; __device__ __forceinline__ u32x4 pack8(const float* v) { u32x4 w; w.x = cvt_pk_bf16(v[0], v[1]); w.y = cvt_pk_bf16(v[2], v[3]); w.z = cvt_pk_bf16(v[4], v[5]); w.w = cvt_pk_bf16(v[6], v[7]); return w; }
;     template <int NQ> __device__ __forceinline__ void roped(const float* rope, const f32x4 (&acc)[2][2][4][2], int row0, bool is_ctx, int rowb  , int axis, int j0,
;                                                              bf16_t* dst, int ld, int c1, int dx2, float sc, int cz  ) const {
;     ...
;                 if (!is_ctx) { const int t = row - rowb, pos = axis ? (t & 63) : (t >> 6); const f32x4* tp = (const f32x4*)(rope + (size_t)(pos * NQ + j0) * 2);
; #pragma unroll
;                     for (int q = 0; q < 4; ++q) { const f32x4 cs = tp[q];
; #pragma unroll
;                         for (int hh = 0; hh < 2; ++hh) { const int e = 2 * q + hh; const float c = hh ? cs[2] : cs[0], s = hh ? cs[3] : cs[1];
;                             const float x1 = acc[ai][0][m][e >> 2][e & 3], x2 = acc[ai][1][m][e >> 2][e & 3];
;                             y1[e] = (x1 * c - x2 * s) * sc; y2[e] = (x2 * c + x1 * s) * sc; } }
;                 } else {
; #pragma unroll
;                     for (int e = 0; e < 8; ++e) { y1[e] = acc[ai][0][m][e >> 2][e & 3] * sc; y2[e] = acc[ai][1][m][e >> 2][e & 3] * sc; }
;                 }
;                 bf16_t* rp = dst + (size_t)row * ld;
;                 *(u32x4*)(rp + c1) = pack8(y1); *(u32x4*)(rp + c1 + dx2) = pack8(y2);
.LBB0_290:
	v_mul_f32_e32 v167, 0x3d800000, v131
	v_ashrrev_i32_e32 v131, 31, v130
	v_pk_mul_f32 v[168:169], v[168:169], s[76:77] op_sel_hi:[1,0]
	v_pk_mul_f32 v[142:143], v[142:143], s[76:77] op_sel_hi:[1,0]
	v_pk_mul_f32 v[140:141], v[140:141], s[76:77] op_sel_hi:[1,0]
	v_pk_mul_f32 v[138:139], v[138:139], s[76:77] op_sel_hi:[1,0]
	v_lshlrev_b64 v[130:131], 11, v[130:131]
	v_cvt_pk_bf16_f32 v138, v138, v139
	v_cvt_pk_bf16_f32 v139, v140, v141
	v_cvt_pk_bf16_f32 v140, v142, v143
	v_cvt_pk_bf16_f32 v141, v168, v169
	v_lshl_add_u64 v[142:143], v[128:129], 0, v[130:131]
	v_cvt_pk_bf16_f32 v130, v132, v133
	v_cvt_pk_bf16_f32 v131, v134, v135
	v_cvt_pk_bf16_f32 v132, v136, v137
	v_cvt_pk_bf16_f32 v133, v159, v167
	flat_store_dwordx4 v[142:143], v[138:141]
	flat_store_dwordx4 v[142:143], v[130:133] offset:128
	s_and_b64 vcc, exec, s[10:11]
	s_mov_b64 s[14:15], -1
	v_add_u32_e32 v130, 48, v166
	s_cbranch_vccnz .LBB0_292
	v_subrev_u32_e32 v131, s61, v130
	v_and_b32_e32 v132, 63, v130
	v_lshrrev_b32_e32 v131, 6, v131
	v_cndmask_b32_e64 v131, v132, v131, s[6:7]
	v_lshl_add_u32 v132, v131, 6, v144
	v_ashrrev_i32_e32 v133, 31, v132
	v_lshl_add_u64 v[140:141], v[132:133], 3, s[30:31]
	flat_load_dwordx4 v[132:135], v[140:141]
	flat_load_dwordx4 v[168:171], v[140:141] offset:48
	flat_load_dwordx4 v[208:211], v[140:141] offset:16
	flat_load_dwordx4 v[212:215], v[140:141] offset:32
	s_mov_b64 s[14:15], 0
	s_waitcnt vmcnt(0) lgkmcnt(0)
	v_mov_b32_e32 v142, v132
	v_mov_b32_e32 v143, v134
	v_mov_b32_e32 v134, v133
	v_pk_mul_f32 v[132:133], v[68:69], v[142:143]
	v_pk_mul_f32 v[172:173], v[68:69], v[134:135]
	v_pk_fma_f32 v[132:133], v[76:77], v[134:135], v[132:133]
	v_mov_b32_e32 v134, v208
	v_mov_b32_e32 v135, v209
	v_mov_b32_e32 v136, v210
	v_mov_b32_e32 v137, v211
	v_mul_f32_e32 v182, v74, v168
	v_mul_f32_e32 v184, v66, v169
	v_pk_mul_f32 v[132:133], v[132:133], s[76:77] op_sel_hi:[1,0]
	s_waitcnt vmcnt(0) lgkmcnt(0)
	v_mov_b32_e32 v174, v134
	v_mov_b32_e32 v175, v136
	v_mov_b32_e32 v136, v135
	v_pk_mul_f32 v[134:135], v[70:71], v[174:175]
	v_pk_mul_f32 v[176:177], v[70:71], v[136:137]
	v_pk_fma_f32 v[134:135], v[78:79], v[136:137], v[134:135]
	v_mov_b32_e32 v136, v212
	v_mov_b32_e32 v137, v213
	v_mov_b32_e32 v138, v214
	v_mov_b32_e32 v139, v215
	v_pk_mul_f32 v[134:135], v[134:135], s[76:77] op_sel_hi:[1,0]
	v_pk_fma_f32 v[140:141], v[78:79], v[174:175], v[176:177] neg_lo:[0,0,1] neg_hi:[0,0,1]
	s_waitcnt vmcnt(0) lgkmcnt(0)
	v_mov_b32_e32 v178, v136
	v_mov_b32_e32 v179, v138
	v_mov_b32_e32 v138, v137
	v_pk_mul_f32 v[136:137], v[64:65], v[178:179]
	v_pk_mul_f32 v[180:181], v[64:65], v[138:139]
	v_pk_fma_f32 v[136:137], v[72:73], v[138:139], v[136:137]
	v_mov_b32_e32 v138, v66
	v_mov_b32_e32 v139, v74
	v_pk_mul_f32 v[138:139], v[138:139], v[168:169]
	v_pk_mul_f32 v[136:137], v[136:137], s[76:77] op_sel_hi:[1,0]
	v_add_f32_e32 v131, v139, v138
	v_mov_b32_e32 v138, v75
	v_mov_b32_e32 v139, v67
	v_pk_mul_f32 v[138:139], v[138:139], v[170:171]
	v_mul_f32_e32 v159, 0x3d800000, v131
	v_mov_b32_e32 v183, v138
	v_mov_b32_e32 v185, v139
	v_pk_fma_f32 v[138:139], v[76:77], v[142:143], v[172:173] neg_lo:[0,0,1] neg_hi:[0,0,1]
	v_mov_b32_e32 v172, v67
	v_mov_b32_e32 v173, v75
	v_pk_mul_f32 v[170:171], v[172:173], v[170:171]
	v_pk_fma_f32 v[142:143], v[72:73], v[178:179], v[180:181] neg_lo:[0,0,1] neg_hi:[0,0,1]
	v_pk_add_f32 v[168:169], v[182:183], v[184:185] neg_lo:[0,1] neg_hi:[0,1]
	v_add_f32_e32 v131, v171, v170

; __device__ __forceinline__ u32x4 pack8(const float* v) { u32x4 w; w.x = cvt_pk_bf16(v[0], v[1]); w.y = cvt_pk_bf16(v[2], v[3]); w.z = cvt_pk_bf16(v[4], v[5]); w.w = cvt_pk_bf16(v[6], v[7]); return w; }
;     template <int NQ> __device__ __forceinline__ void roped(const float* rope, const f32x4 (&acc)[2][2][4][2], int row0, bool is_ctx, int rowb  , int axis, int j0,
;                                                              bf16_t* dst, int ld, int c1, int dx2, float sc, int cz  ) const {
;     ...
;                 if (!is_ctx) { const int t = row - rowb, pos = axis ? (t & 63) : (t >> 6); const f32x4* tp = (const f32x4*)(rope + (size_t)(pos * NQ + j0) * 2);
; #pragma unroll
;                     for (int q = 0; q < 4; ++q) { const f32x4 cs = tp[q];
; #pragma unroll
;                         for (int hh = 0; hh < 2; ++hh) { const int e = 2 * q + hh; const float c = hh ? cs[2] : cs[0], s = hh ? cs[3] : cs[1];
;                             const float x1 = acc[ai][0][m][e >> 2][e & 3], x2 = acc[ai][1][m][e >> 2][e & 3];
;                             y1[e] = (x1 * c - x2 * s) * sc; y2[e] = (x2 * c + x1 * s) * sc; } }
;                 } else {
; #pragma unroll
;                     for (int e = 0; e < 8; ++e) { y1[e] = acc[ai][0][m][e >> 2][e & 3] * sc; y2[e] = acc[ai][1][m][e >> 2][e & 3] * sc; }
;                 }
;                 bf16_t* rp = dst + (size_t)row * ld;
;                 *(u32x4*)(rp + c1) = pack8(y1); *(u32x4*)(rp + c1 + dx2) = pack8(y2);
.LBB0_294:
	v_mul_f32_e32 v167, 0x3d800000, v131
	v_ashrrev_i32_e32 v131, 31, v130
	v_pk_mul_f32 v[168:169], v[168:169], s[76:77] op_sel_hi:[1,0]
	v_pk_mul_f32 v[142:143], v[142:143], s[76:77] op_sel_hi:[1,0]
	v_pk_mul_f32 v[140:141], v[140:141], s[76:77] op_sel_hi:[1,0]
	v_pk_mul_f32 v[138:139], v[138:139], s[76:77] op_sel_hi:[1,0]
	v_lshlrev_b64 v[130:131], 11, v[130:131]
	v_cvt_pk_bf16_f32 v138, v138, v139
	v_cvt_pk_bf16_f32 v139, v140, v141
	v_cvt_pk_bf16_f32 v140, v142, v143
	v_cvt_pk_bf16_f32 v141, v168, v169
	v_lshl_add_u64 v[142:143], v[128:129], 0, v[130:131]
	v_cvt_pk_bf16_f32 v130, v132, v133
	v_cvt_pk_bf16_f32 v131, v134, v135
	v_cvt_pk_bf16_f32 v132, v136, v137
	v_cvt_pk_bf16_f32 v133, v159, v167
	flat_store_dwordx4 v[142:143], v[138:141]
	flat_store_dwordx4 v[142:143], v[130:133] offset:128
	s_and_b64 vcc, exec, s[10:11]
	s_mov_b64 s[14:15], -1
	v_add_u32_e32 v130, 0x80, v166
	s_cbranch_vccnz .LBB0_296
	v_subrev_u32_e32 v131, s61, v130
	v_and_b32_e32 v132, 63, v205
	v_lshrrev_b32_e32 v131, 6, v131
	v_cndmask_b32_e64 v131, v132, v131, s[6:7]
	v_lshl_add_u32 v132, v131, 6, v144
	v_ashrrev_i32_e32 v133, 31, v132
	v_lshl_add_u64 v[140:141], v[132:133], 3, s[30:31]
	flat_load_dwordx4 v[132:135], v[140:141]
	flat_load_dwordx4 v[168:171], v[140:141] offset:48
	flat_load_dwordx4 v[208:211], v[140:141] offset:16
	flat_load_dwordx4 v[212:215], v[140:141] offset:32
	s_mov_b64 s[14:15], 0
	s_waitcnt vmcnt(0) lgkmcnt(0)
	v_mov_b32_e32 v142, v132
	v_mov_b32_e32 v143, v134
	v_mov_b32_e32 v134, v133
	v_pk_mul_f32 v[132:133], v[52:53], v[142:143]
	v_pk_mul_f32 v[172:173], v[52:53], v[134:135]
	v_pk_fma_f32 v[132:133], v[60:61], v[134:135], v[132:133]
	v_mov_b32_e32 v134, v208
	v_mov_b32_e32 v135, v209
	v_mov_b32_e32 v136, v210
	v_mov_b32_e32 v137, v211
	v_mul_f32_e32 v182, v58, v168
	v_mul_f32_e32 v184, v50, v169
	v_pk_mul_f32 v[132:133], v[132:133], s[76:77] op_sel_hi:[1,0]
	s_waitcnt vmcnt(0) lgkmcnt(0)
	v_mov_b32_e32 v174, v134
	v_mov_b32_e32 v175, v136
	v_mov_b32_e32 v136, v135
	v_pk_mul_f32 v[134:135], v[54:55], v[174:175]
	v_pk_mul_f32 v[176:177], v[54:55], v[136:137]
	v_pk_fma_f32 v[134:135], v[62:63], v[136:137], v[134:135]
	v_mov_b32_e32 v136, v212
	v_mov_b32_e32 v137, v213
	v_mov_b32_e32 v138, v214
	v_mov_b32_e32 v139, v215
	v_pk_mul_f32 v[134:135], v[134:135], s[76:77] op_sel_hi:[1,0]
	v_pk_fma_f32 v[140:141], v[62:63], v[174:175], v[176:177] neg_lo:[0,0,1] neg_hi:[0,0,1]
	s_waitcnt vmcnt(0) lgkmcnt(0)
	v_mov_b32_e32 v178, v136
	v_mov_b32_e32 v179, v138
	v_mov_b32_e32 v138, v137
	v_pk_mul_f32 v[136:137], v[48:49], v[178:179]
	v_pk_mul_f32 v[180:181], v[48:49], v[138:139]
	v_pk_fma_f32 v[136:137], v[56:57], v[138:139], v[136:137]
	v_mov_b32_e32 v138, v50
	v_mov_b32_e32 v139, v58
	v_pk_mul_f32 v[138:139], v[138:139], v[168:169]
	v_pk_mul_f32 v[136:137], v[136:137], s[76:77] op_sel_hi:[1,0]
	v_add_f32_e32 v131, v139, v138
	v_mov_b32_e32 v138, v59
	v_mov_b32_e32 v139, v51
	v_pk_mul_f32 v[138:139], v[138:139], v[170:171]
	v_mul_f32_e32 v159, 0x3d800000, v131
	v_mov_b32_e32 v183, v138
	v_mov_b32_e32 v185, v139
	v_pk_fma_f32 v[138:139], v[60:61], v[142:143], v[172:173] neg_lo:[0,0,1] neg_hi:[0,0,1]
	v_mov_b32_e32 v172, v51
	v_mov_b32_e32 v173, v59
	v_pk_mul_f32 v[170:171], v[172:173], v[170:171]
	v_pk_fma_f32 v[142:143], v[56:57], v[178:179], v[180:181] neg_lo:[0,0,1] neg_hi:[0,0,1]
	v_pk_add_f32 v[168:169], v[182:183], v[184:185] neg_lo:[0,1] neg_hi:[0,1]
	v_add_f32_e32 v131, v171, v170

; __device__ __forceinline__ u32x4 pack8(const float* v) { u32x4 w; w.x = cvt_pk_bf16(v[0], v[1]); w.y = cvt_pk_bf16(v[2], v[3]); w.z = cvt_pk_bf16(v[4], v[5]); w.w = cvt_pk_bf16(v[6], v[7]); return w; }
;     template <int NQ> __device__ __forceinline__ void roped(const float* rope, const f32x4 (&acc)[2][2][4][2], int row0, bool is_ctx, int rowb  , int axis, int j0,
;                                                              bf16_t* dst, int ld, int c1, int dx2, float sc, int cz  ) const {
;     ...
;                 if (!is_ctx) { const int t = row - rowb, pos = axis ? (t & 63) : (t >> 6); const f32x4* tp = (const f32x4*)(rope + (size_t)(pos * NQ + j0) * 2);
; #pragma unroll
;                     for (int q = 0; q < 4; ++q) { const f32x4 cs = tp[q];
; #pragma unroll
;                         for (int hh = 0; hh < 2; ++hh) { const int e = 2 * q + hh; const float c = hh ? cs[2] : cs[0], s = hh ? cs[3] : cs[1];
;                             const float x1 = acc[ai][0][m][e >> 2][e & 3], x2 = acc[ai][1][m][e >> 2][e & 3];
;                             y1[e] = (x1 * c - x2 * s) * sc; y2[e] = (x2 * c + x1 * s) * sc; } }
;                 } else {
; #pragma unroll
;                     for (int e = 0; e < 8; ++e) { y1[e] = acc[ai][0][m][e >> 2][e & 3] * sc; y2[e] = acc[ai][1][m][e >> 2][e & 3] * sc; }
;                 }
;                 bf16_t* rp = dst + (size_t)row * ld;
;                 *(u32x4*)(rp + c1) = pack8(y1); *(u32x4*)(rp + c1 + dx2) = pack8(y2);
.LBB0_298:
	v_mul_f32_e32 v167, 0x3d800000, v131
	v_ashrrev_i32_e32 v131, 31, v130
	v_pk_mul_f32 v[168:169], v[168:169], s[76:77] op_sel_hi:[1,0]
	v_pk_mul_f32 v[142:143], v[142:143], s[76:77] op_sel_hi:[1,0]
	v_pk_mul_f32 v[140:141], v[140:141], s[76:77] op_sel_hi:[1,0]
	v_pk_mul_f32 v[138:139], v[138:139], s[76:77] op_sel_hi:[1,0]
	v_lshlrev_b64 v[130:131], 11, v[130:131]
	v_cvt_pk_bf16_f32 v138, v138, v139
	v_cvt_pk_bf16_f32 v139, v140, v141
	v_cvt_pk_bf16_f32 v140, v142, v143
	v_cvt_pk_bf16_f32 v141, v168, v169
	v_lshl_add_u64 v[142:143], v[128:129], 0, v[130:131]
	v_cvt_pk_bf16_f32 v130, v132, v133
	v_cvt_pk_bf16_f32 v131, v134, v135
	v_cvt_pk_bf16_f32 v132, v136, v137
	v_cvt_pk_bf16_f32 v133, v159, v167
	flat_store_dwordx4 v[142:143], v[138:141]
	flat_store_dwordx4 v[142:143], v[130:133] offset:128
	s_and_b64 vcc, exec, s[10:11]
	s_mov_b64 s[14:15], -1
	v_add_u32_e32 v130, 0x90, v166
	s_cbranch_vccnz .LBB0_300
	v_subrev_u32_e32 v131, s61, v130
	v_and_b32_e32 v132, 63, v130
	v_lshrrev_b32_e32 v131, 6, v131
	v_cndmask_b32_e64 v131, v132, v131, s[6:7]
	v_lshl_add_u32 v132, v131, 6, v144
	v_ashrrev_i32_e32 v133, 31, v132
	v_lshl_add_u64 v[140:141], v[132:133], 3, s[30:31]
	flat_load_dwordx4 v[132:135], v[140:141]
	flat_load_dwordx4 v[168:171], v[140:141] offset:48
	flat_load_dwordx4 v[208:211], v[140:141] offset:16
	flat_load_dwordx4 v[212:215], v[140:141] offset:32
	s_mov_b64 s[14:15], 0
	s_waitcnt vmcnt(0) lgkmcnt(0)
	v_mov_b32_e32 v142, v132
	v_mov_b32_e32 v143, v134
	v_mov_b32_e32 v134, v133
	v_pk_mul_f32 v[132:133], v[36:37], v[142:143]
	v_pk_mul_f32 v[172:173], v[36:37], v[134:135]
	v_pk_fma_f32 v[132:133], v[44:45], v[134:135], v[132:133]
	v_mov_b32_e32 v134, v208
	v_mov_b32_e32 v135, v209
	v_mov_b32_e32 v136, v210
	v_mov_b32_e32 v137, v211
	v_mul_f32_e32 v182, v42, v168
	v_mul_f32_e32 v184, v34, v169
	v_pk_mul_f32 v[132:133], v[132:133], s[76:77] op_sel_hi:[1,0]
	s_waitcnt vmcnt(0) lgkmcnt(0)
	v_mov_b32_e32 v174, v134
	v_mov_b32_e32 v175, v136
	v_mov_b32_e32 v136, v135
	v_pk_mul_f32 v[134:135], v[38:39], v[174:175]
	v_pk_mul_f32 v[176:177], v[38:39], v[136:137]
	v_pk_fma_f32 v[134:135], v[46:47], v[136:137], v[134:135]
	v_mov_b32_e32 v136, v212
	v_mov_b32_e32 v137, v213
	v_mov_b32_e32 v138, v214
	v_mov_b32_e32 v139, v215
	v_pk_mul_f32 v[134:135], v[134:135], s[76:77] op_sel_hi:[1,0]
	v_pk_fma_f32 v[140:141], v[46:47], v[174:175], v[176:177] neg_lo:[0,0,1] neg_hi:[0,0,1]
	s_waitcnt vmcnt(0) lgkmcnt(0)
	v_mov_b32_e32 v178, v136
	v_mov_b32_e32 v179, v138
	v_mov_b32_e32 v138, v137
	v_pk_mul_f32 v[136:137], v[32:33], v[178:179]
	v_pk_mul_f32 v[180:181], v[32:33], v[138:139]
	v_pk_fma_f32 v[136:137], v[40:41], v[138:139], v[136:137]
	v_mov_b32_e32 v138, v34
	v_mov_b32_e32 v139, v42
	v_pk_mul_f32 v[138:139], v[138:139], v[168:169]
	v_pk_mul_f32 v[136:137], v[136:137], s[76:77] op_sel_hi:[1,0]
	v_add_f32_e32 v131, v139, v138
	v_mov_b32_e32 v138, v43
	v_mov_b32_e32 v139, v35
	v_pk_mul_f32 v[138:139], v[138:139], v[170:171]
	v_mul_f32_e32 v159, 0x3d800000, v131
	v_mov_b32_e32 v183, v138
	v_mov_b32_e32 v185, v139
	v_pk_fma_f32 v[138:139], v[44:45], v[142:143], v[172:173] neg_lo:[0,0,1] neg_hi:[0,0,1]
	v_mov_b32_e32 v172, v35
	v_mov_b32_e32 v173, v43
	v_pk_mul_f32 v[170:171], v[172:173], v[170:171]
	v_pk_fma_f32 v[142:143], v[40:41], v[178:179], v[180:181] neg_lo:[0,0,1] neg_hi:[0,0,1]
	v_pk_add_f32 v[168:169], v[182:183], v[184:185] neg_lo:[0,1] neg_hi:[0,1]
	v_add_f32_e32 v131, v171, v170

; __device__ __forceinline__ u32x4 pack8(const float* v) { u32x4 w; w.x = cvt_pk_bf16(v[0], v[1]); w.y = cvt_pk_bf16(v[2], v[3]); w.z = cvt_pk_bf16(v[4], v[5]); w.w = cvt_pk_bf16(v[6], v[7]); return w; }
;     template <int NQ> __device__ __forceinline__ void roped(const float* rope, const f32x4 (&acc)[2][2][4][2], int row0, bool is_ctx, int rowb  , int axis, int j0,
;                                                              bf16_t* dst, int ld, int c1, int dx2, float sc, int cz  ) const {
;     ...
;                 if (!is_ctx) { const int t = row - rowb, pos = axis ? (t & 63) : (t >> 6); const f32x4* tp = (const f32x4*)(rope + (size_t)(pos * NQ + j0) * 2);
; #pragma unroll
;                     for (int q = 0; q < 4; ++q) { const f32x4 cs = tp[q];
; #pragma unroll
;                         for (int hh = 0; hh < 2; ++hh) { const int e = 2 * q + hh; const float c = hh ? cs[2] : cs[0], s = hh ? cs[3] : cs[1];
;                             const float x1 = acc[ai][0][m][e >> 2][e & 3], x2 = acc[ai][1][m][e >> 2][e & 3];
;                             y1[e] = (x1 * c - x2 * s) * sc; y2[e] = (x2 * c + x1 * s) * sc; } }
;                 } else {
; #pragma unroll
;                     for (int e = 0; e < 8; ++e) { y1[e] = acc[ai][0][m][e >> 2][e & 3] * sc; y2[e] = acc[ai][1][m][e >> 2][e & 3] * sc; }
;                 }
;                 bf16_t* rp = dst + (size_t)row * ld;
;                 *(u32x4*)(rp + c1) = pack8(y1); *(u32x4*)(rp + c1 + dx2) = pack8(y2);
.LBB0_302:
	v_mul_f32_e32 v167, 0x3d800000, v131
	v_ashrrev_i32_e32 v131, 31, v130
	v_pk_mul_f32 v[168:169], v[168:169], s[76:77] op_sel_hi:[1,0]
	v_pk_mul_f32 v[142:143], v[142:143], s[76:77] op_sel_hi:[1,0]
	v_pk_mul_f32 v[140:141], v[140:141], s[76:77] op_sel_hi:[1,0]
	v_pk_mul_f32 v[138:139], v[138:139], s[76:77] op_sel_hi:[1,0]
	v_lshlrev_b64 v[130:131], 11, v[130:131]
	v_cvt_pk_bf16_f32 v138, v138, v139
	v_cvt_pk_bf16_f32 v139, v140, v141
	v_cvt_pk_bf16_f32 v140, v142, v143
	v_cvt_pk_bf16_f32 v141, v168, v169
	v_lshl_add_u64 v[142:143], v[128:129], 0, v[130:131]
	v_cvt_pk_bf16_f32 v130, v132, v133
	v_cvt_pk_bf16_f32 v131, v134, v135
	v_cvt_pk_bf16_f32 v132, v136, v137
	v_cvt_pk_bf16_f32 v133, v159, v167
	flat_store_dwordx4 v[142:143], v[138:141]
	flat_store_dwordx4 v[142:143], v[130:133] offset:128
	s_and_b64 vcc, exec, s[10:11]
	s_mov_b64 s[14:15], -1
	v_add_u32_e32 v130, 0xa0, v166
	s_cbranch_vccnz .LBB0_304
	v_subrev_u32_e32 v131, s61, v130
	v_and_b32_e32 v132, 63, v130
	v_lshrrev_b32_e32 v131, 6, v131
	v_cndmask_b32_e64 v131, v132, v131, s[6:7]
	v_lshl_add_u32 v132, v131, 6, v144
	v_ashrrev_i32_e32 v133, 31, v132
	v_lshl_add_u64 v[140:141], v[132:133], 3, s[30:31]
	flat_load_dwordx4 v[132:135], v[140:141]
	flat_load_dwordx4 v[168:171], v[140:141] offset:48
	flat_load_dwordx4 v[208:211], v[140:141] offset:16
	flat_load_dwordx4 v[212:215], v[140:141] offset:32
	s_mov_b64 s[14:15], 0
	s_waitcnt vmcnt(0) lgkmcnt(0)
	v_mov_b32_e32 v142, v132
	v_mov_b32_e32 v143, v134
	v_mov_b32_e32 v134, v133
	v_pk_mul_f32 v[132:133], v[20:21], v[142:143]
	v_pk_mul_f32 v[172:173], v[20:21], v[134:135]
	v_pk_fma_f32 v[132:133], v[28:29], v[134:135], v[132:133]
	v_mov_b32_e32 v134, v208
	v_mov_b32_e32 v135, v209
	v_mov_b32_e32 v136, v210
	v_mov_b32_e32 v137, v211
	v_mul_f32_e32 v182, v26, v168
	v_mul_f32_e32 v184, v18, v169
	v_pk_mul_f32 v[132:133], v[132:133], s[76:77] op_sel_hi:[1,0]
	s_waitcnt vmcnt(0) lgkmcnt(0)
	v_mov_b32_e32 v174, v134
	v_mov_b32_e32 v175, v136
	v_mov_b32_e32 v136, v135
	v_pk_mul_f32 v[134:135], v[22:23], v[174:175]
	v_pk_mul_f32 v[176:177], v[22:23], v[136:137]
	v_pk_fma_f32 v[134:135], v[30:31], v[136:137], v[134:135]
	v_mov_b32_e32 v136, v212
	v_mov_b32_e32 v137, v213
	v_mov_b32_e32 v138, v214
	v_mov_b32_e32 v139, v215
	v_pk_mul_f32 v[134:135], v[134:135], s[76:77] op_sel_hi:[1,0]
	v_pk_fma_f32 v[140:141], v[30:31], v[174:175], v[176:177] neg_lo:[0,0,1] neg_hi:[0,0,1]
	s_waitcnt vmcnt(0) lgkmcnt(0)
	v_mov_b32_e32 v178, v136
	v_mov_b32_e32 v179, v138
	v_mov_b32_e32 v138, v137
	v_pk_mul_f32 v[136:137], v[16:17], v[178:179]
	v_pk_mul_f32 v[180:181], v[16:17], v[138:139]
	v_pk_fma_f32 v[136:137], v[24:25], v[138:139], v[136:137]
	v_mov_b32_e32 v138, v18
	v_mov_b32_e32 v139, v26
	v_pk_mul_f32 v[138:139], v[138:139], v[168:169]
	v_pk_mul_f32 v[136:137], v[136:137], s[76:77] op_sel_hi:[1,0]
	v_add_f32_e32 v131, v139, v138
	v_mov_b32_e32 v138, v27
	v_mov_b32_e32 v139, v19
	v_pk_mul_f32 v[138:139], v[138:139], v[170:171]
	v_mul_f32_e32 v159, 0x3d800000, v131
	v_mov_b32_e32 v183, v138
	v_mov_b32_e32 v185, v139
	v_pk_fma_f32 v[138:139], v[28:29], v[142:143], v[172:173] neg_lo:[0,0,1] neg_hi:[0,0,1]
	v_mov_b32_e32 v172, v19
	v_mov_b32_e32 v173, v27
	v_pk_mul_f32 v[170:171], v[172:173], v[170:171]
	v_pk_fma_f32 v[142:143], v[24:25], v[178:179], v[180:181] neg_lo:[0,0,1] neg_hi:[0,0,1]
	v_pk_add_f32 v[168:169], v[182:183], v[184:185] neg_lo:[0,1] neg_hi:[0,1]
	v_add_f32_e32 v131, v171, v170

; __device__ __forceinline__ u32x4 pack8(const float* v) { u32x4 w; w.x = cvt_pk_bf16(v[0], v[1]); w.y = cvt_pk_bf16(v[2], v[3]); w.z = cvt_pk_bf16(v[4], v[5]); w.w = cvt_pk_bf16(v[6], v[7]); return w; }
;     template <int NQ> __device__ __forceinline__ void roped(const float* rope, const f32x4 (&acc)[2][2][4][2], int row0, bool is_ctx, int rowb  , int axis, int j0,
;                                                              bf16_t* dst, int ld, int c1, int dx2, float sc, int cz  ) const {
;     ...
;                 if (!is_ctx) { const int t = row - rowb, pos = axis ? (t & 63) : (t >> 6); const f32x4* tp = (const f32x4*)(rope + (size_t)(pos * NQ + j0) * 2);
; #pragma unroll
;                     for (int q = 0; q < 4; ++q) { const f32x4 cs = tp[q];
; #pragma unroll
;                         for (int hh = 0; hh < 2; ++hh) { const int e = 2 * q + hh; const float c = hh ? cs[2] : cs[0], s = hh ? cs[3] : cs[1];
;                             const float x1 = acc[ai][0][m][e >> 2][e & 3], x2 = acc[ai][1][m][e >> 2][e & 3];
;                             y1[e] = (x1 * c - x2 * s) * sc; y2[e] = (x2 * c + x1 * s) * sc; } }
;                 } else {
; #pragma unroll
;                     for (int e = 0; e < 8; ++e) { y1[e] = acc[ai][0][m][e >> 2][e & 3] * sc; y2[e] = acc[ai][1][m][e >> 2][e & 3] * sc; }
;                 }
;                 bf16_t* rp = dst + (size_t)row * ld;
;                 *(u32x4*)(rp + c1) = pack8(y1); *(u32x4*)(rp + c1 + dx2) = pack8(y2);
.LBB0_306:
	v_mul_f32_e32 v167, 0x3d800000, v131
	v_ashrrev_i32_e32 v131, 31, v130
	v_pk_mul_f32 v[168:169], v[168:169], s[76:77] op_sel_hi:[1,0]
	v_pk_mul_f32 v[142:143], v[142:143], s[76:77] op_sel_hi:[1,0]
	v_pk_mul_f32 v[140:141], v[140:141], s[76:77] op_sel_hi:[1,0]
	v_pk_mul_f32 v[138:139], v[138:139], s[76:77] op_sel_hi:[1,0]
	v_lshlrev_b64 v[130:131], 11, v[130:131]
	v_cvt_pk_bf16_f32 v138, v138, v139
	v_cvt_pk_bf16_f32 v139, v140, v141
	v_cvt_pk_bf16_f32 v140, v142, v143
	v_cvt_pk_bf16_f32 v141, v168, v169
	v_lshl_add_u64 v[142:143], v[128:129], 0, v[130:131]
	v_cvt_pk_bf16_f32 v130, v132, v133
	v_cvt_pk_bf16_f32 v131, v134, v135
	v_cvt_pk_bf16_f32 v132, v136, v137
	v_cvt_pk_bf16_f32 v133, v159, v167
	flat_store_dwordx4 v[142:143], v[138:141]
	flat_store_dwordx4 v[142:143], v[130:133] offset:128
	s_and_b64 vcc, exec, s[10:11]
	s_mov_b64 s[10:11], -1
	v_add_u32_e32 v130, 0xb0, v166
	s_cbranch_vccnz .LBB0_308
	v_subrev_u32_e32 v131, s61, v130
	v_and_b32_e32 v132, 63, v130
	v_lshrrev_b32_e32 v131, 6, v131
	v_cndmask_b32_e64 v131, v132, v131, s[6:7]
	v_lshl_add_u32 v132, v131, 6, v144
	v_ashrrev_i32_e32 v133, 31, v132
	v_lshl_add_u64 v[140:141], v[132:133], 3, s[30:31]
	flat_load_dwordx4 v[132:135], v[140:141]
	flat_load_dwordx4 v[168:171], v[140:141] offset:48
	flat_load_dwordx4 v[208:211], v[140:141] offset:16
	flat_load_dwordx4 v[212:215], v[140:141] offset:32
	s_mov_b64 s[10:11], 0
	s_waitcnt vmcnt(0) lgkmcnt(0)
	v_mov_b32_e32 v142, v132
	v_mov_b32_e32 v143, v134
	v_mov_b32_e32 v134, v133
	v_pk_mul_f32 v[132:133], v[4:5], v[142:143]
	v_pk_mul_f32 v[172:173], v[4:5], v[134:135]
	v_pk_fma_f32 v[132:133], v[12:13], v[134:135], v[132:133]
	v_mov_b32_e32 v134, v208
	v_mov_b32_e32 v135, v209
	v_mov_b32_e32 v136, v210
	v_mov_b32_e32 v137, v211
	v_mul_f32_e32 v182, v10, v168
	v_mul_f32_e32 v184, v2, v169
	v_pk_mul_f32 v[132:133], v[132:133], s[76:77] op_sel_hi:[1,0]
	s_waitcnt vmcnt(0) lgkmcnt(0)
	v_mov_b32_e32 v174, v134
	v_mov_b32_e32 v175, v136
	v_mov_b32_e32 v136, v135
	v_pk_mul_f32 v[134:135], v[6:7], v[174:175]
	v_pk_mul_f32 v[176:177], v[6:7], v[136:137]
	v_pk_fma_f32 v[134:135], v[14:15], v[136:137], v[134:135]
	v_mov_b32_e32 v136, v212
	v_mov_b32_e32 v137, v213
	v_mov_b32_e32 v138, v214
	v_mov_b32_e32 v139, v215
	v_pk_mul_f32 v[134:135], v[134:135], s[76:77] op_sel_hi:[1,0]
	v_pk_fma_f32 v[140:141], v[14:15], v[174:175], v[176:177] neg_lo:[0,0,1] neg_hi:[0,0,1]
	s_waitcnt vmcnt(0) lgkmcnt(0)
	v_mov_b32_e32 v178, v136
	v_mov_b32_e32 v179, v138
	v_mov_b32_e32 v138, v137
	v_pk_mul_f32 v[136:137], v[0:1], v[178:179]
	v_pk_mul_f32 v[180:181], v[0:1], v[138:139]
	v_pk_fma_f32 v[136:137], v[8:9], v[138:139], v[136:137]
	v_mov_b32_e32 v138, v2
	v_mov_b32_e32 v139, v10
	v_pk_mul_f32 v[138:139], v[138:139], v[168:169]
	v_pk_mul_f32 v[136:137], v[136:137], s[76:77] op_sel_hi:[1,0]
	v_add_f32_e32 v131, v139, v138
	v_mov_b32_e32 v138, v11
	v_mov_b32_e32 v139, v3
	v_pk_mul_f32 v[138:139], v[138:139], v[170:171]
	v_mul_f32_e32 v159, 0x3d800000, v131
	v_mov_b32_e32 v183, v138
	v_mov_b32_e32 v185, v139
	v_pk_fma_f32 v[138:139], v[12:13], v[142:143], v[172:173] neg_lo:[0,0,1] neg_hi:[0,0,1]
	v_mov_b32_e32 v172, v3
	v_mov_b32_e32 v173, v11
	v_pk_mul_f32 v[170:171], v[172:173], v[170:171]
	v_pk_fma_f32 v[142:143], v[8:9], v[178:179], v[180:181] neg_lo:[0,0,1] neg_hi:[0,0,1]
	v_pk_add_f32 v[168:169], v[182:183], v[184:185] neg_lo:[0,1] neg_hi:[0,1]
	v_add_f32_e32 v131, v171, v170

;     template <int NQ> __device__ __forceinline__ void roped(const float* rope, const f32x4 (&acc)[2][2][4][2], int row0, bool is_ctx, int rowb  , int axis, int j0,
;                                                              bf16_t* dst, int ld, int c1, int dx2, float sc, int cz  ) const {
;     ...
;                 if (!is_ctx) { const int t = row - rowb, pos = axis ? (t & 63) : (t >> 6); const f32x4* tp = (const f32x4*)(rope + (size_t)(pos * NQ + j0) * 2);
; #pragma unroll
;                     for (int q = 0; q < 4; ++q) { const f32x4 cs = tp[q];
; #pragma unroll
;                         for (int hh = 0; hh < 2; ++hh) { const int e = 2 * q + hh; const float c = hh ? cs[2] : cs[0], s = hh ? cs[3] : cs[1];
;                             const float x1 = acc[ai][0][m][e >> 2][e & 3], x2 = acc[ai][1][m][e >> 2][e & 3];
;                             y1[e] = (x1 * c - x2 * s) * sc; y2[e] = (x2 * c + x1 * s) * sc; } }
;     __device__ __forceinline__ void operator()(const f32x4 (&acc)[2][2][4][2], const Unit& u, int wr, int wc, int fr, int fq) const {
;     ...
;                 if (u.pn < 4) roped<64>(rope, acc, row0, is_ctx, rowb, axis, j0, (bf16_t*)BIG, 1024, u.pn * 256 + axis * 128 + j0, 64, 1.f, -1);
.LBB0_311:
	s_and_b64 vcc, exec, s[10:11]
	s_cbranch_vccz .LBB0_345
	s_mov_b64 s[10:11], -1
	s_and_b64 vcc, exec, s[56:57]
	s_cbranch_vccz .LBB0_314
	v_subrev_u32_e32 v128, s61, v166
	v_and_b32_e32 v129, 63, v205
	v_lshrrev_b32_e32 v128, 6, v128
	v_cndmask_b32_e64 v128, v129, v128, s[6:7]
	v_lshl_add_u32 v128, v128, 6, v144
	v_ashrrev_i32_e32 v129, 31, v128
	v_lshl_add_u64 v[138:139], v[128:129], 3, s[30:31]
	flat_load_dwordx4 v[128:131], v[138:139]
	flat_load_dwordx4 v[168:171], v[138:139] offset:48
	flat_load_dwordx4 v[208:211], v[138:139] offset:16
	flat_load_dwordx4 v[212:215], v[138:139] offset:32
	s_mov_b64 s[10:11], 0
	s_waitcnt vmcnt(0) lgkmcnt(0)
	v_mov_b32_e32 v140, v128
	v_mov_b32_e32 v141, v130
	v_mov_b32_e32 v130, v129
	v_pk_mul_f32 v[132:133], v[116:117], v[140:141]
	v_pk_mul_f32 v[128:129], v[116:117], v[130:131]
	v_pk_fma_f32 v[130:131], v[124:125], v[130:131], v[132:133]
	v_mov_b32_e32 v132, v208
	v_mov_b32_e32 v133, v209
	v_mov_b32_e32 v134, v210
	v_mov_b32_e32 v135, v211
	v_mul_f32_e32 v180, v122, v169
	v_mul_f32_e32 v178, v114, v169
	v_pk_fma_f32 v[140:141], v[124:125], v[140:141], v[128:129] neg_lo:[0,0,1] neg_hi:[0,0,1]
	v_mov_b32_e32 v128, v115
	v_mov_b32_e32 v129, v123
	v_pk_mul_f32 v[128:129], v[128:129], v[170:171]
	s_waitcnt vmcnt(0) lgkmcnt(0)
	v_mov_b32_e32 v142, v132
	v_mov_b32_e32 v143, v134
	v_mov_b32_e32 v134, v133
	v_pk_mul_f32 v[132:133], v[118:119], v[142:143]
	v_pk_mul_f32 v[172:173], v[118:119], v[134:135]
	v_pk_fma_f32 v[132:133], v[126:127], v[134:135], v[132:133]
	v_mov_b32_e32 v134, v212
	v_mov_b32_e32 v135, v213
	v_mov_b32_e32 v136, v214
	v_mov_b32_e32 v137, v215
	v_mul_f32_e32 v138, v122, v168
	v_pk_fma_f32 v[142:143], v[126:127], v[142:143], v[172:173] neg_lo:[0,0,1] neg_hi:[0,0,1]
	s_waitcnt vmcnt(0) lgkmcnt(0)
	v_mov_b32_e32 v174, v134
	v_mov_b32_e32 v175, v136
	v_mov_b32_e32 v136, v135
	v_pk_mul_f32 v[134:135], v[112:113], v[174:175]
	v_pk_mul_f32 v[176:177], v[112:113], v[136:137]
	v_pk_fma_f32 v[134:135], v[120:121], v[136:137], v[134:135]
	v_mov_b32_e32 v136, v114
	v_mov_b32_e32 v137, v122
	v_pk_fma_f32 v[136:137], v[136:137], v[168:169], v[180:181] op_sel_hi:[1,1,0]
	v_mov_b32_e32 v168, v123
	v_mov_b32_e32 v169, v115
	v_pk_mul_f32 v[168:169], v[168:169], v[170:171]
	v_add_f32_e32 v137, v129, v128
	v_mov_b32_e32 v139, v168
	v_mov_b32_e32 v179, v169
	v_pk_fma_f32 v[168:169], v[120:121], v[174:175], v[176:177] neg_lo:[0,0,1] neg_hi:[0,0,1]
	v_pk_add_f32 v[138:139], v[138:139], v[178:179] neg_lo:[0,1] neg_hi:[0,1]

; __device__ __forceinline__ u32x4 pack8(const float* v) { u32x4 w; w.x = cvt_pk_bf16(v[0], v[1]); w.y = cvt_pk_bf16(v[2], v[3]); w.z = cvt_pk_bf16(v[4], v[5]); w.w = cvt_pk_bf16(v[6], v[7]); return w; }
;     template <int NQ> __device__ __forceinline__ void roped(const float* rope, const f32x4 (&acc)[2][2][4][2], int row0, bool is_ctx, int rowb  , int axis, int j0,
;                                                              bf16_t* dst, int ld, int c1, int dx2, float sc, int cz  ) const {
;     ...
;                 if (!is_ctx) { const int t = row - rowb, pos = axis ? (t & 63) : (t >> 6); const f32x4* tp = (const f32x4*)(rope + (size_t)(pos * NQ + j0) * 2);
; #pragma unroll
;                     for (int q = 0; q < 4; ++q) { const f32x4 cs = tp[q];
; #pragma unroll
;                         for (int hh = 0; hh < 2; ++hh) { const int e = 2 * q + hh; const float c = hh ? cs[2] : cs[0], s = hh ? cs[3] : cs[1];
;                             const float x1 = acc[ai][0][m][e >> 2][e & 3], x2 = acc[ai][1][m][e >> 2][e & 3];
;                             y1[e] = (x1 * c - x2 * s) * sc; y2[e] = (x2 * c + x1 * s) * sc; } }
;                 } else {
; #pragma unroll
;                     for (int e = 0; e < 8; ++e) { y1[e] = acc[ai][0][m][e >> 2][e & 3] * sc; y2[e] = acc[ai][1][m][e >> 2][e & 3] * sc; }
;                 }
;                 bf16_t* rp = dst + (size_t)row * ld;
;                 *(u32x4*)(rp + c1) = pack8(y1); *(u32x4*)(rp + c1 + dx2) = pack8(y2);
.LBB0_316:
	s_or_b32 s10, s36, s62
	v_add_u32_e32 v128, s10, v144
	v_ashrrev_i32_e32 v129, 31, v128
	v_ashrrev_i32_e32 v167, 31, v166
	v_lshl_add_u64 v[128:129], v[128:129], 1, s[90:91]
	v_lshlrev_b64 v[170:171], 11, v[166:167]
	v_cvt_pk_bf16_f32 v140, v140, v141
	v_cvt_pk_bf16_f32 v141, v142, v143
	v_cvt_pk_bf16_f32 v142, v168, v169
	v_cvt_pk_bf16_f32 v143, v138, v139
	v_lshl_add_u64 v[138:139], v[128:129], 0, v[170:171]
	v_cvt_pk_bf16_f32 v130, v130, v131
	v_cvt_pk_bf16_f32 v131, v132, v133
	v_cvt_pk_bf16_f32 v132, v134, v135
	v_cvt_pk_bf16_f32 v133, v136, v137
	flat_store_dwordx4 v[138:139], v[140:143]
	flat_store_dwordx4 v[138:139], v[130:133] offset:128
	s_andn2_b64 vcc, exec, s[56:57]
	s_mov_b64 s[14:15], -1
	v_cndmask_b32_e64 v131, 0, 1, s[56:57]
	v_add_u32_e32 v130, 16, v166
	v_cmp_ne_u32_e64 s[10:11], 1, v131
	s_cbranch_vccnz .LBB0_318
	v_subrev_u32_e32 v131, s61, v130
	v_and_b32_e32 v132, 63, v130
	v_lshrrev_b32_e32 v131, 6, v131
	v_cndmask_b32_e64 v131, v132, v131, s[6:7]
	v_lshl_add_u32 v132, v131, 6, v144
	v_ashrrev_i32_e32 v133, 31, v132
	v_lshl_add_u64 v[140:141], v[132:133], 3, s[30:31]
	flat_load_dwordx4 v[132:135], v[140:141]
	flat_load_dwordx4 v[170:173], v[140:141] offset:48
	flat_load_dwordx4 v[208:211], v[140:141] offset:16
	flat_load_dwordx4 v[212:215], v[140:141] offset:32
	s_mov_b64 s[14:15], 0
	s_waitcnt vmcnt(0) lgkmcnt(0)
	v_mov_b32_e32 v142, v132
	v_mov_b32_e32 v143, v134
	v_mov_b32_e32 v134, v133
	v_pk_mul_f32 v[132:133], v[100:101], v[142:143]
	v_pk_mul_f32 v[168:169], v[100:101], v[134:135]
	v_pk_fma_f32 v[132:133], v[108:109], v[134:135], v[132:133]
	v_mov_b32_e32 v134, v208
	v_mov_b32_e32 v135, v209
	v_mov_b32_e32 v136, v210
	v_mov_b32_e32 v137, v211
	v_mul_f32_e32 v184, v106, v171
	v_mul_f32_e32 v182, v98, v171
	v_pk_fma_f32 v[142:143], v[108:109], v[142:143], v[168:169] neg_lo:[0,0,1] neg_hi:[0,0,1]
	s_waitcnt vmcnt(0) lgkmcnt(0)
	v_mov_b32_e32 v174, v134
	v_mov_b32_e32 v175, v136
	v_mov_b32_e32 v136, v135
	v_pk_mul_f32 v[134:135], v[102:103], v[174:175]
	v_pk_mul_f32 v[176:177], v[102:103], v[136:137]
	v_pk_fma_f32 v[134:135], v[110:111], v[136:137], v[134:135]
	v_mov_b32_e32 v136, v212
	v_mov_b32_e32 v137, v213
	v_mov_b32_e32 v138, v214
	v_mov_b32_e32 v139, v215
	v_mul_f32_e32 v140, v106, v170
	v_pk_fma_f32 v[168:169], v[110:111], v[174:175], v[176:177] neg_lo:[0,0,1] neg_hi:[0,0,1]
	v_mov_b32_e32 v174, v99
	v_mov_b32_e32 v175, v107
	s_waitcnt vmcnt(0) lgkmcnt(0)
	v_mov_b32_e32 v178, v136
	v_mov_b32_e32 v179, v138
	v_mov_b32_e32 v138, v137
	v_pk_mul_f32 v[136:137], v[96:97], v[178:179]
	v_pk_mul_f32 v[180:181], v[96:97], v[138:139]
	v_pk_fma_f32 v[136:137], v[104:105], v[138:139], v[136:137]
	v_mov_b32_e32 v138, v98
	v_mov_b32_e32 v139, v106
	v_pk_fma_f32 v[138:139], v[138:139], v[170:171], v[184:185] op_sel_hi:[1,1,0]
	v_mov_b32_e32 v170, v107
	v_mov_b32_e32 v171, v99
	v_pk_mul_f32 v[170:171], v[170:171], v[172:173]
	v_pk_mul_f32 v[172:173], v[174:175], v[172:173]
	v_mov_b32_e32 v141, v170
	v_mov_b32_e32 v183, v171
	v_pk_fma_f32 v[170:171], v[104:105], v[178:179], v[180:181] neg_lo:[0,0,1] neg_hi:[0,0,1]
	v_pk_add_f32 v[140:141], v[140:141], v[182:183] neg_lo:[0,1] neg_hi:[0,1]
	v_add_f32_e32 v139, v173, v172

; __device__ __forceinline__ u32x4 pack8(const float* v) { u32x4 w; w.x = cvt_pk_bf16(v[0], v[1]); w.y = cvt_pk_bf16(v[2], v[3]); w.z = cvt_pk_bf16(v[4], v[5]); w.w = cvt_pk_bf16(v[6], v[7]); return w; }
;     template <int NQ> __device__ __forceinline__ void roped(const float* rope, const f32x4 (&acc)[2][2][4][2], int row0, bool is_ctx, int rowb  , int axis, int j0,
;                                                              bf16_t* dst, int ld, int c1, int dx2, float sc, int cz  ) const {
;     ...
;                 if (!is_ctx) { const int t = row - rowb, pos = axis ? (t & 63) : (t >> 6); const f32x4* tp = (const f32x4*)(rope + (size_t)(pos * NQ + j0) * 2);
; #pragma unroll
;                     for (int q = 0; q < 4; ++q) { const f32x4 cs = tp[q];
; #pragma unroll
;                         for (int hh = 0; hh < 2; ++hh) { const int e = 2 * q + hh; const float c = hh ? cs[2] : cs[0], s = hh ? cs[3] : cs[1];
;                             const float x1 = acc[ai][0][m][e >> 2][e & 3], x2 = acc[ai][1][m][e >> 2][e & 3];
;                             y1[e] = (x1 * c - x2 * s) * sc; y2[e] = (x2 * c + x1 * s) * sc; } }
;                 } else {
; #pragma unroll
;                     for (int e = 0; e < 8; ++e) { y1[e] = acc[ai][0][m][e >> 2][e & 3] * sc; y2[e] = acc[ai][1][m][e >> 2][e & 3] * sc; }
;                 }
;                 bf16_t* rp = dst + (size_t)row * ld;
;                 *(u32x4*)(rp + c1) = pack8(y1); *(u32x4*)(rp + c1 + dx2) = pack8(y2);
.LBB0_320:
	v_ashrrev_i32_e32 v131, 31, v130
	v_lshlrev_b64 v[130:131], 11, v[130:131]
	v_cvt_pk_bf16_f32 v172, v142, v143
	v_cvt_pk_bf16_f32 v173, v168, v169
	v_cvt_pk_bf16_f32 v174, v170, v171
	v_cvt_pk_bf16_f32 v175, v140, v141
	v_lshl_add_u64 v[140:141], v[128:129], 0, v[130:131]
	v_cvt_pk_bf16_f32 v130, v132, v133
	v_cvt_pk_bf16_f32 v131, v134, v135
	v_cvt_pk_bf16_f32 v132, v136, v137
	v_cvt_pk_bf16_f32 v133, v138, v139
	flat_store_dwordx4 v[140:141], v[172:175]
	flat_store_dwordx4 v[140:141], v[130:133] offset:128
	s_and_b64 vcc, exec, s[10:11]
	s_mov_b64 s[14:15], -1
	v_add_u32_e32 v130, 32, v166
	s_cbranch_vccnz .LBB0_322
	v_subrev_u32_e32 v131, s61, v130
	v_and_b32_e32 v132, 63, v130
	v_lshrrev_b32_e32 v131, 6, v131
	v_cndmask_b32_e64 v131, v132, v131, s[6:7]
	v_lshl_add_u32 v132, v131, 6, v144
	v_ashrrev_i32_e32 v133, 31, v132
	v_lshl_add_u64 v[140:141], v[132:133], 3, s[30:31]
	flat_load_dwordx4 v[132:135], v[140:141]
	flat_load_dwordx4 v[170:173], v[140:141] offset:48
	flat_load_dwordx4 v[208:211], v[140:141] offset:16
	flat_load_dwordx4 v[212:215], v[140:141] offset:32
	s_mov_b64 s[14:15], 0
	s_waitcnt vmcnt(0) lgkmcnt(0)
	v_mov_b32_e32 v142, v132
	v_mov_b32_e32 v143, v134
	v_mov_b32_e32 v134, v133
	v_pk_mul_f32 v[132:133], v[84:85], v[142:143]
	v_pk_mul_f32 v[168:169], v[84:85], v[134:135]
	v_pk_fma_f32 v[132:133], v[92:93], v[134:135], v[132:133]
	v_mov_b32_e32 v134, v208
	v_mov_b32_e32 v135, v209
	v_mov_b32_e32 v136, v210
	v_mov_b32_e32 v137, v211
	v_mul_f32_e32 v184, v90, v171
	v_mul_f32_e32 v182, v82, v171
	v_pk_fma_f32 v[142:143], v[92:93], v[142:143], v[168:169] neg_lo:[0,0,1] neg_hi:[0,0,1]
	s_waitcnt vmcnt(0) lgkmcnt(0)
	v_mov_b32_e32 v174, v134
	v_mov_b32_e32 v175, v136
	v_mov_b32_e32 v136, v135
	v_pk_mul_f32 v[134:135], v[86:87], v[174:175]
	v_pk_mul_f32 v[176:177], v[86:87], v[136:137]
	v_pk_fma_f32 v[134:135], v[94:95], v[136:137], v[134:135]
	v_mov_b32_e32 v136, v212
	v_mov_b32_e32 v137, v213
	v_mov_b32_e32 v138, v214
	v_mov_b32_e32 v139, v215
	v_mul_f32_e32 v140, v90, v170
	v_pk_fma_f32 v[168:169], v[94:95], v[174:175], v[176:177] neg_lo:[0,0,1] neg_hi:[0,0,1]
	v_mov_b32_e32 v174, v83
	v_mov_b32_e32 v175, v91
	s_waitcnt vmcnt(0) lgkmcnt(0)
	v_mov_b32_e32 v178, v136
	v_mov_b32_e32 v179, v138
	v_mov_b32_e32 v138, v137
	v_pk_mul_f32 v[136:137], v[80:81], v[178:179]
	v_pk_mul_f32 v[180:181], v[80:81], v[138:139]
	v_pk_fma_f32 v[136:137], v[88:89], v[138:139], v[136:137]
	v_mov_b32_e32 v138, v82
	v_mov_b32_e32 v139, v90
	v_pk_fma_f32 v[138:139], v[138:139], v[170:171], v[184:185] op_sel_hi:[1,1,0]
	v_mov_b32_e32 v170, v91
	v_mov_b32_e32 v171, v83
	v_pk_mul_f32 v[170:171], v[170:171], v[172:173]
	v_pk_mul_f32 v[172:173], v[174:175], v[172:173]
	v_mov_b32_e32 v141, v170
	v_mov_b32_e32 v183, v171
	v_pk_fma_f32 v[170:171], v[88:89], v[178:179], v[180:181] neg_lo:[0,0,1] neg_hi:[0,0,1]
	v_pk_add_f32 v[140:141], v[140:141], v[182:183] neg_lo:[0,1] neg_hi:[0,1]
	v_add_f32_e32 v139, v173, v172

; __device__ __forceinline__ u32x4 pack8(const float* v) { u32x4 w; w.x = cvt_pk_bf16(v[0], v[1]); w.y = cvt_pk_bf16(v[2], v[3]); w.z = cvt_pk_bf16(v[4], v[5]); w.w = cvt_pk_bf16(v[6], v[7]); return w; }
;     template <int NQ> __device__ __forceinline__ void roped(const float* rope, const f32x4 (&acc)[2][2][4][2], int row0, bool is_ctx, int rowb  , int axis, int j0,
;                                                              bf16_t* dst, int ld, int c1, int dx2, float sc, int cz  ) const {
;     ...
;                 if (!is_ctx) { const int t = row - rowb, pos = axis ? (t & 63) : (t >> 6); const f32x4* tp = (const f32x4*)(rope + (size_t)(pos * NQ + j0) * 2);
; #pragma unroll
;                     for (int q = 0; q < 4; ++q) { const f32x4 cs = tp[q];
; #pragma unroll
;                         for (int hh = 0; hh < 2; ++hh) { const int e = 2 * q + hh; const float c = hh ? cs[2] : cs[0], s = hh ? cs[3] : cs[1];
;                             const float x1 = acc[ai][0][m][e >> 2][e & 3], x2 = acc[ai][1][m][e >> 2][e & 3];
;                             y1[e] = (x1 * c - x2 * s) * sc; y2[e] = (x2 * c + x1 * s) * sc; } }
;                 } else {
; #pragma unroll
;                     for (int e = 0; e < 8; ++e) { y1[e] = acc[ai][0][m][e >> 2][e & 3] * sc; y2[e] = acc[ai][1][m][e >> 2][e & 3] * sc; }
;                 }
;                 bf16_t* rp = dst + (size_t)row * ld;
;                 *(u32x4*)(rp + c1) = pack8(y1); *(u32x4*)(rp + c1 + dx2) = pack8(y2);
.LBB0_324:
	v_ashrrev_i32_e32 v131, 31, v130
	v_lshlrev_b64 v[130:131], 11, v[130:131]
	v_cvt_pk_bf16_f32 v172, v142, v143
	v_cvt_pk_bf16_f32 v173, v168, v169
	v_cvt_pk_bf16_f32 v174, v170, v171
	v_cvt_pk_bf16_f32 v175, v140, v141
	v_lshl_add_u64 v[140:141], v[128:129], 0, v[130:131]
	v_cvt_pk_bf16_f32 v130, v132, v133
	v_cvt_pk_bf16_f32 v131, v134, v135
	v_cvt_pk_bf16_f32 v132, v136, v137
	v_cvt_pk_bf16_f32 v133, v138, v139
	flat_store_dwordx4 v[140:141], v[172:175]
	flat_store_dwordx4 v[140:141], v[130:133] offset:128
	s_and_b64 vcc, exec, s[10:11]
	s_mov_b64 s[14:15], -1
	v_add_u32_e32 v130, 48, v166
	s_cbranch_vccnz .LBB0_326
	v_subrev_u32_e32 v131, s61, v130
	v_and_b32_e32 v132, 63, v130
	v_lshrrev_b32_e32 v131, 6, v131
	v_cndmask_b32_e64 v131, v132, v131, s[6:7]
	v_lshl_add_u32 v132, v131, 6, v144
	v_ashrrev_i32_e32 v133, 31, v132
	v_lshl_add_u64 v[140:141], v[132:133], 3, s[30:31]
	flat_load_dwordx4 v[132:135], v[140:141]
	flat_load_dwordx4 v[170:173], v[140:141] offset:48
	flat_load_dwordx4 v[208:211], v[140:141] offset:16
	flat_load_dwordx4 v[212:215], v[140:141] offset:32
	s_mov_b64 s[14:15], 0
	s_waitcnt vmcnt(0) lgkmcnt(0)
	v_mov_b32_e32 v142, v132
	v_mov_b32_e32 v143, v134
	v_mov_b32_e32 v134, v133
	v_pk_mul_f32 v[132:133], v[68:69], v[142:143]
	v_pk_mul_f32 v[168:169], v[68:69], v[134:135]
	v_pk_fma_f32 v[132:133], v[76:77], v[134:135], v[132:133]
	v_mov_b32_e32 v134, v208
	v_mov_b32_e32 v135, v209
	v_mov_b32_e32 v136, v210
	v_mov_b32_e32 v137, v211
	v_mul_f32_e32 v184, v74, v171
	v_mul_f32_e32 v182, v66, v171
	v_pk_fma_f32 v[142:143], v[76:77], v[142:143], v[168:169] neg_lo:[0,0,1] neg_hi:[0,0,1]
	s_waitcnt vmcnt(0) lgkmcnt(0)
	v_mov_b32_e32 v174, v134
	v_mov_b32_e32 v175, v136
	v_mov_b32_e32 v136, v135
	v_pk_mul_f32 v[134:135], v[70:71], v[174:175]
	v_pk_mul_f32 v[176:177], v[70:71], v[136:137]
	v_pk_fma_f32 v[134:135], v[78:79], v[136:137], v[134:135]
	v_mov_b32_e32 v136, v212
	v_mov_b32_e32 v137, v213
	v_mov_b32_e32 v138, v214
	v_mov_b32_e32 v139, v215
	v_mul_f32_e32 v140, v74, v170
	v_pk_fma_f32 v[168:169], v[78:79], v[174:175], v[176:177] neg_lo:[0,0,1] neg_hi:[0,0,1]
	v_mov_b32_e32 v174, v67
	v_mov_b32_e32 v175, v75
	s_waitcnt vmcnt(0) lgkmcnt(0)
	v_mov_b32_e32 v178, v136
	v_mov_b32_e32 v179, v138
	v_mov_b32_e32 v138, v137
	v_pk_mul_f32 v[136:137], v[64:65], v[178:179]
	v_pk_mul_f32 v[180:181], v[64:65], v[138:139]
	v_pk_fma_f32 v[136:137], v[72:73], v[138:139], v[136:137]
	v_mov_b32_e32 v138, v66
	v_mov_b32_e32 v139, v74
	v_pk_fma_f32 v[138:139], v[138:139], v[170:171], v[184:185] op_sel_hi:[1,1,0]
	v_mov_b32_e32 v170, v75
	v_mov_b32_e32 v171, v67
	v_pk_mul_f32 v[170:171], v[170:171], v[172:173]
	v_pk_mul_f32 v[172:173], v[174:175], v[172:173]
	v_mov_b32_e32 v141, v170
	v_mov_b32_e32 v183, v171
	v_pk_fma_f32 v[170:171], v[72:73], v[178:179], v[180:181] neg_lo:[0,0,1] neg_hi:[0,0,1]
	v_pk_add_f32 v[140:141], v[140:141], v[182:183] neg_lo:[0,1] neg_hi:[0,1]
	v_add_f32_e32 v139, v173, v172

; __device__ __forceinline__ u32x4 pack8(const float* v) { u32x4 w; w.x = cvt_pk_bf16(v[0], v[1]); w.y = cvt_pk_bf16(v[2], v[3]); w.z = cvt_pk_bf16(v[4], v[5]); w.w = cvt_pk_bf16(v[6], v[7]); return w; }
;     template <int NQ> __device__ __forceinline__ void roped(const float* rope, const f32x4 (&acc)[2][2][4][2], int row0, bool is_ctx, int rowb  , int axis, int j0,
;                                                              bf16_t* dst, int ld, int c1, int dx2, float sc, int cz  ) const {
;     ...
;                 if (!is_ctx) { const int t = row - rowb, pos = axis ? (t & 63) : (t >> 6); const f32x4* tp = (const f32x4*)(rope + (size_t)(pos * NQ + j0) * 2);
; #pragma unroll
;                     for (int q = 0; q < 4; ++q) { const f32x4 cs = tp[q];
; #pragma unroll
;                         for (int hh = 0; hh < 2; ++hh) { const int e = 2 * q + hh; const float c = hh ? cs[2] : cs[0], s = hh ? cs[3] : cs[1];
;                             const float x1 = acc[ai][0][m][e >> 2][e & 3], x2 = acc[ai][1][m][e >> 2][e & 3];
;                             y1[e] = (x1 * c - x2 * s) * sc; y2[e] = (x2 * c + x1 * s) * sc; } }
;                 } else {
; #pragma unroll
;                     for (int e = 0; e < 8; ++e) { y1[e] = acc[ai][0][m][e >> 2][e & 3] * sc; y2[e] = acc[ai][1][m][e >> 2][e & 3] * sc; }
;                 }
;                 bf16_t* rp = dst + (size_t)row * ld;
;                 *(u32x4*)(rp + c1) = pack8(y1); *(u32x4*)(rp + c1 + dx2) = pack8(y2);
.LBB0_328:
	v_ashrrev_i32_e32 v131, 31, v130
	v_lshlrev_b64 v[130:131], 11, v[130:131]
	v_cvt_pk_bf16_f32 v172, v142, v143
	v_cvt_pk_bf16_f32 v173, v168, v169
	v_cvt_pk_bf16_f32 v174, v170, v171
	v_cvt_pk_bf16_f32 v175, v140, v141
	v_lshl_add_u64 v[140:141], v[128:129], 0, v[130:131]
	v_cvt_pk_bf16_f32 v130, v132, v133
	v_cvt_pk_bf16_f32 v131, v134, v135
	v_cvt_pk_bf16_f32 v132, v136, v137
	v_cvt_pk_bf16_f32 v133, v138, v139
	flat_store_dwordx4 v[140:141], v[172:175]
	flat_store_dwordx4 v[140:141], v[130:133] offset:128
	s_and_b64 vcc, exec, s[10:11]
	s_mov_b64 s[14:15], -1
	v_add_u32_e32 v130, 0x80, v166
	s_cbranch_vccnz .LBB0_330
	v_subrev_u32_e32 v131, s61, v130
	v_and_b32_e32 v132, 63, v205
	v_lshrrev_b32_e32 v131, 6, v131
	v_cndmask_b32_e64 v131, v132, v131, s[6:7]
	v_lshl_add_u32 v132, v131, 6, v144
	v_ashrrev_i32_e32 v133, 31, v132
	v_lshl_add_u64 v[140:141], v[132:133], 3, s[30:31]
	flat_load_dwordx4 v[132:135], v[140:141]
	flat_load_dwordx4 v[170:173], v[140:141] offset:48
	flat_load_dwordx4 v[208:211], v[140:141] offset:16
	flat_load_dwordx4 v[212:215], v[140:141] offset:32
	s_mov_b64 s[14:15], 0
	s_waitcnt vmcnt(0) lgkmcnt(0)
	v_mov_b32_e32 v142, v132
	v_mov_b32_e32 v143, v134
	v_mov_b32_e32 v134, v133
	v_pk_mul_f32 v[132:133], v[52:53], v[142:143]
	v_pk_mul_f32 v[168:169], v[52:53], v[134:135]
	v_pk_fma_f32 v[132:133], v[60:61], v[134:135], v[132:133]
	v_mov_b32_e32 v134, v208
	v_mov_b32_e32 v135, v209
	v_mov_b32_e32 v136, v210
	v_mov_b32_e32 v137, v211
	v_mul_f32_e32 v184, v58, v171
	v_mul_f32_e32 v182, v50, v171
	v_pk_fma_f32 v[142:143], v[60:61], v[142:143], v[168:169] neg_lo:[0,0,1] neg_hi:[0,0,1]
	s_waitcnt vmcnt(0) lgkmcnt(0)
	v_mov_b32_e32 v174, v134
	v_mov_b32_e32 v175, v136
	v_mov_b32_e32 v136, v135
	v_pk_mul_f32 v[134:135], v[54:55], v[174:175]
	v_pk_mul_f32 v[176:177], v[54:55], v[136:137]
	v_pk_fma_f32 v[134:135], v[62:63], v[136:137], v[134:135]
	v_mov_b32_e32 v136, v212
	v_mov_b32_e32 v137, v213
	v_mov_b32_e32 v138, v214
	v_mov_b32_e32 v139, v215
	v_mul_f32_e32 v140, v58, v170
	v_pk_fma_f32 v[168:169], v[62:63], v[174:175], v[176:177] neg_lo:[0,0,1] neg_hi:[0,0,1]
	v_mov_b32_e32 v174, v51
	v_mov_b32_e32 v175, v59
	s_waitcnt vmcnt(0) lgkmcnt(0)
	v_mov_b32_e32 v178, v136
	v_mov_b32_e32 v179, v138
	v_mov_b32_e32 v138, v137
	v_pk_mul_f32 v[136:137], v[48:49], v[178:179]
	v_pk_mul_f32 v[180:181], v[48:49], v[138:139]
	v_pk_fma_f32 v[136:137], v[56:57], v[138:139], v[136:137]
	v_mov_b32_e32 v138, v50
	v_mov_b32_e32 v139, v58
	v_pk_fma_f32 v[138:139], v[138:139], v[170:171], v[184:185] op_sel_hi:[1,1,0]
	v_mov_b32_e32 v170, v59
	v_mov_b32_e32 v171, v51
	v_pk_mul_f32 v[170:171], v[170:171], v[172:173]
	v_pk_mul_f32 v[172:173], v[174:175], v[172:173]
	v_mov_b32_e32 v141, v170
	v_mov_b32_e32 v183, v171
	v_pk_fma_f32 v[170:171], v[56:57], v[178:179], v[180:181] neg_lo:[0,0,1] neg_hi:[0,0,1]
	v_pk_add_f32 v[140:141], v[140:141], v[182:183] neg_lo:[0,1] neg_hi:[0,1]
	v_add_f32_e32 v139, v173, v172

; __device__ __forceinline__ u32x4 pack8(const float* v) { u32x4 w; w.x = cvt_pk_bf16(v[0], v[1]); w.y = cvt_pk_bf16(v[2], v[3]); w.z = cvt_pk_bf16(v[4], v[5]); w.w = cvt_pk_bf16(v[6], v[7]); return w; }
;     template <int NQ> __device__ __forceinline__ void roped(const float* rope, const f32x4 (&acc)[2][2][4][2], int row0, bool is_ctx, int rowb  , int axis, int j0,
;                                                              bf16_t* dst, int ld, int c1, int dx2, float sc, int cz  ) const {
;     ...
;                 if (!is_ctx) { const int t = row - rowb, pos = axis ? (t & 63) : (t >> 6); const f32x4* tp = (const f32x4*)(rope + (size_t)(pos * NQ + j0) * 2);
; #pragma unroll
;                     for (int q = 0; q < 4; ++q) { const f32x4 cs = tp[q];
; #pragma unroll
;                         for (int hh = 0; hh < 2; ++hh) { const int e = 2 * q + hh; const float c = hh ? cs[2] : cs[0], s = hh ? cs[3] : cs[1];
;                             const float x1 = acc[ai][0][m][e >> 2][e & 3], x2 = acc[ai][1][m][e >> 2][e & 3];
;                             y1[e] = (x1 * c - x2 * s) * sc; y2[e] = (x2 * c + x1 * s) * sc; } }
;                 } else {
; #pragma unroll
;                     for (int e = 0; e < 8; ++e) { y1[e] = acc[ai][0][m][e >> 2][e & 3] * sc; y2[e] = acc[ai][1][m][e >> 2][e & 3] * sc; }
;                 }
;                 bf16_t* rp = dst + (size_t)row * ld;
;                 *(u32x4*)(rp + c1) = pack8(y1); *(u32x4*)(rp + c1 + dx2) = pack8(y2);
.LBB0_332:
	v_ashrrev_i32_e32 v131, 31, v130
	v_lshlrev_b64 v[130:131], 11, v[130:131]
	v_cvt_pk_bf16_f32 v172, v142, v143
	v_cvt_pk_bf16_f32 v173, v168, v169
	v_cvt_pk_bf16_f32 v174, v170, v171
	v_cvt_pk_bf16_f32 v175, v140, v141
	v_lshl_add_u64 v[140:141], v[128:129], 0, v[130:131]
	v_cvt_pk_bf16_f32 v130, v132, v133
	v_cvt_pk_bf16_f32 v131, v134, v135
	v_cvt_pk_bf16_f32 v132, v136, v137
	v_cvt_pk_bf16_f32 v133, v138, v139
	flat_store_dwordx4 v[140:141], v[172:175]
	flat_store_dwordx4 v[140:141], v[130:133] offset:128
	s_and_b64 vcc, exec, s[10:11]
	s_mov_b64 s[14:15], -1
	v_add_u32_e32 v130, 0x90, v166
	s_cbranch_vccnz .LBB0_334
	v_subrev_u32_e32 v131, s61, v130
	v_and_b32_e32 v132, 63, v130
	v_lshrrev_b32_e32 v131, 6, v131
	v_cndmask_b32_e64 v131, v132, v131, s[6:7]
	v_lshl_add_u32 v132, v131, 6, v144
	v_ashrrev_i32_e32 v133, 31, v132
	v_lshl_add_u64 v[140:141], v[132:133], 3, s[30:31]
	flat_load_dwordx4 v[132:135], v[140:141]
	flat_load_dwordx4 v[170:173], v[140:141] offset:48
	flat_load_dwordx4 v[208:211], v[140:141] offset:16
	flat_load_dwordx4 v[212:215], v[140:141] offset:32
	s_mov_b64 s[14:15], 0
	s_waitcnt vmcnt(0) lgkmcnt(0)
	v_mov_b32_e32 v142, v132
	v_mov_b32_e32 v143, v134
	v_mov_b32_e32 v134, v133
	v_pk_mul_f32 v[132:133], v[36:37], v[142:143]
	v_pk_mul_f32 v[168:169], v[36:37], v[134:135]
	v_pk_fma_f32 v[132:133], v[44:45], v[134:135], v[132:133]
	v_mov_b32_e32 v134, v208
	v_mov_b32_e32 v135, v209
	v_mov_b32_e32 v136, v210
	v_mov_b32_e32 v137, v211
	v_mul_f32_e32 v184, v42, v171
	v_mul_f32_e32 v182, v34, v171
	v_pk_fma_f32 v[142:143], v[44:45], v[142:143], v[168:169] neg_lo:[0,0,1] neg_hi:[0,0,1]
	s_waitcnt vmcnt(0) lgkmcnt(0)
	v_mov_b32_e32 v174, v134
	v_mov_b32_e32 v175, v136
	v_mov_b32_e32 v136, v135
	v_pk_mul_f32 v[134:135], v[38:39], v[174:175]
	v_pk_mul_f32 v[176:177], v[38:39], v[136:137]
	v_pk_fma_f32 v[134:135], v[46:47], v[136:137], v[134:135]
	v_mov_b32_e32 v136, v212
	v_mov_b32_e32 v137, v213
	v_mov_b32_e32 v138, v214
	v_mov_b32_e32 v139, v215
	v_mul_f32_e32 v140, v42, v170
	v_pk_fma_f32 v[168:169], v[46:47], v[174:175], v[176:177] neg_lo:[0,0,1] neg_hi:[0,0,1]
	v_mov_b32_e32 v174, v35
	v_mov_b32_e32 v175, v43
	s_waitcnt vmcnt(0) lgkmcnt(0)
	v_mov_b32_e32 v178, v136
	v_mov_b32_e32 v179, v138
	v_mov_b32_e32 v138, v137
	v_pk_mul_f32 v[136:137], v[32:33], v[178:179]
	v_pk_mul_f32 v[180:181], v[32:33], v[138:139]
	v_pk_fma_f32 v[136:137], v[40:41], v[138:139], v[136:137]
	v_mov_b32_e32 v138, v34
	v_mov_b32_e32 v139, v42
	v_pk_fma_f32 v[138:139], v[138:139], v[170:171], v[184:185] op_sel_hi:[1,1,0]
	v_mov_b32_e32 v170, v43
	v_mov_b32_e32 v171, v35
	v_pk_mul_f32 v[170:171], v[170:171], v[172:173]
	v_pk_mul_f32 v[172:173], v[174:175], v[172:173]
	v_mov_b32_e32 v141, v170
	v_mov_b32_e32 v183, v171
	v_pk_fma_f32 v[170:171], v[40:41], v[178:179], v[180:181] neg_lo:[0,0,1] neg_hi:[0,0,1]
	v_pk_add_f32 v[140:141], v[140:141], v[182:183] neg_lo:[0,1] neg_hi:[0,1]
	v_add_f32_e32 v139, v173, v172

; __device__ __forceinline__ u32x4 pack8(const float* v) { u32x4 w; w.x = cvt_pk_bf16(v[0], v[1]); w.y = cvt_pk_bf16(v[2], v[3]); w.z = cvt_pk_bf16(v[4], v[5]); w.w = cvt_pk_bf16(v[6], v[7]); return w; }
;     template <int NQ> __device__ __forceinline__ void roped(const float* rope, const f32x4 (&acc)[2][2][4][2], int row0, bool is_ctx, int rowb  , int axis, int j0,
;                                                              bf16_t* dst, int ld, int c1, int dx2, float sc, int cz  ) const {
;     ...
;                 if (!is_ctx) { const int t = row - rowb, pos = axis ? (t & 63) : (t >> 6); const f32x4* tp = (const f32x4*)(rope + (size_t)(pos * NQ + j0) * 2);
; #pragma unroll
;                     for (int q = 0; q < 4; ++q) { const f32x4 cs = tp[q];
; #pragma unroll
;                         for (int hh = 0; hh < 2; ++hh) { const int e = 2 * q + hh; const float c = hh ? cs[2] : cs[0], s = hh ? cs[3] : cs[1];
;                             const float x1 = acc[ai][0][m][e >> 2][e & 3], x2 = acc[ai][1][m][e >> 2][e & 3];
;                             y1[e] = (x1 * c - x2 * s) * sc; y2[e] = (x2 * c + x1 * s) * sc; } }
;                 } else {
; #pragma unroll
;                     for (int e = 0; e < 8; ++e) { y1[e] = acc[ai][0][m][e >> 2][e & 3] * sc; y2[e] = acc[ai][1][m][e >> 2][e & 3] * sc; }
;                 }
;                 bf16_t* rp = dst + (size_t)row * ld;
;                 *(u32x4*)(rp + c1) = pack8(y1); *(u32x4*)(rp + c1 + dx2) = pack8(y2);
.LBB0_336:
	v_ashrrev_i32_e32 v131, 31, v130
	v_lshlrev_b64 v[130:131], 11, v[130:131]
	v_cvt_pk_bf16_f32 v172, v142, v143
	v_cvt_pk_bf16_f32 v173, v168, v169
	v_cvt_pk_bf16_f32 v174, v170, v171
	v_cvt_pk_bf16_f32 v175, v140, v141
	v_lshl_add_u64 v[140:141], v[128:129], 0, v[130:131]
	v_cvt_pk_bf16_f32 v130, v132, v133
	v_cvt_pk_bf16_f32 v131, v134, v135
	v_cvt_pk_bf16_f32 v132, v136, v137
	v_cvt_pk_bf16_f32 v133, v138, v139
	flat_store_dwordx4 v[140:141], v[172:175]
	flat_store_dwordx4 v[140:141], v[130:133] offset:128
	s_and_b64 vcc, exec, s[10:11]
	s_mov_b64 s[14:15], -1
	v_add_u32_e32 v130, 0xa0, v166
	s_cbranch_vccnz .LBB0_338
	v_subrev_u32_e32 v131, s61, v130
	v_and_b32_e32 v132, 63, v130
	v_lshrrev_b32_e32 v131, 6, v131
	v_cndmask_b32_e64 v131, v132, v131, s[6:7]
	v_lshl_add_u32 v132, v131, 6, v144
	v_ashrrev_i32_e32 v133, 31, v132
	v_lshl_add_u64 v[140:141], v[132:133], 3, s[30:31]
	flat_load_dwordx4 v[132:135], v[140:141]
	flat_load_dwordx4 v[170:173], v[140:141] offset:48
	flat_load_dwordx4 v[208:211], v[140:141] offset:16
	flat_load_dwordx4 v[212:215], v[140:141] offset:32
	s_mov_b64 s[14:15], 0
	s_waitcnt vmcnt(0) lgkmcnt(0)
	v_mov_b32_e32 v142, v132
	v_mov_b32_e32 v143, v134
	v_mov_b32_e32 v134, v133
	v_pk_mul_f32 v[132:133], v[20:21], v[142:143]
	v_pk_mul_f32 v[168:169], v[20:21], v[134:135]
	v_pk_fma_f32 v[132:133], v[28:29], v[134:135], v[132:133]
	v_mov_b32_e32 v134, v208
	v_mov_b32_e32 v135, v209
	v_mov_b32_e32 v136, v210
	v_mov_b32_e32 v137, v211
	v_mul_f32_e32 v184, v26, v171
	v_mul_f32_e32 v182, v18, v171
	v_pk_fma_f32 v[142:143], v[28:29], v[142:143], v[168:169] neg_lo:[0,0,1] neg_hi:[0,0,1]
	s_waitcnt vmcnt(0) lgkmcnt(0)
	v_mov_b32_e32 v174, v134
	v_mov_b32_e32 v175, v136
	v_mov_b32_e32 v136, v135
	v_pk_mul_f32 v[134:135], v[22:23], v[174:175]
	v_pk_mul_f32 v[176:177], v[22:23], v[136:137]
	v_pk_fma_f32 v[134:135], v[30:31], v[136:137], v[134:135]
	v_mov_b32_e32 v136, v212
	v_mov_b32_e32 v137, v213
	v_mov_b32_e32 v138, v214
	v_mov_b32_e32 v139, v215
	v_mul_f32_e32 v140, v26, v170
	v_pk_fma_f32 v[168:169], v[30:31], v[174:175], v[176:177] neg_lo:[0,0,1] neg_hi:[0,0,1]
	v_mov_b32_e32 v174, v19
	v_mov_b32_e32 v175, v27
	s_waitcnt vmcnt(0) lgkmcnt(0)
	v_mov_b32_e32 v178, v136
	v_mov_b32_e32 v179, v138
	v_mov_b32_e32 v138, v137
	v_pk_mul_f32 v[136:137], v[16:17], v[178:179]
	v_pk_mul_f32 v[180:181], v[16:17], v[138:139]
	v_pk_fma_f32 v[136:137], v[24:25], v[138:139], v[136:137]
	v_mov_b32_e32 v138, v18
	v_mov_b32_e32 v139, v26
	v_pk_fma_f32 v[138:139], v[138:139], v[170:171], v[184:185] op_sel_hi:[1,1,0]
	v_mov_b32_e32 v170, v27
	v_mov_b32_e32 v171, v19
	v_pk_mul_f32 v[170:171], v[170:171], v[172:173]
	v_pk_mul_f32 v[172:173], v[174:175], v[172:173]
	v_mov_b32_e32 v141, v170
	v_mov_b32_e32 v183, v171
	v_pk_fma_f32 v[170:171], v[24:25], v[178:179], v[180:181] neg_lo:[0,0,1] neg_hi:[0,0,1]
	v_pk_add_f32 v[140:141], v[140:141], v[182:183] neg_lo:[0,1] neg_hi:[0,1]
	v_add_f32_e32 v139, v173, v172

; __device__ __forceinline__ u32x4 pack8(const float* v) { u32x4 w; w.x = cvt_pk_bf16(v[0], v[1]); w.y = cvt_pk_bf16(v[2], v[3]); w.z = cvt_pk_bf16(v[4], v[5]); w.w = cvt_pk_bf16(v[6], v[7]); return w; }
;     template <int NQ> __device__ __forceinline__ void roped(const float* rope, const f32x4 (&acc)[2][2][4][2], int row0, bool is_ctx, int rowb  , int axis, int j0,
;                                                              bf16_t* dst, int ld, int c1, int dx2, float sc, int cz  ) const {
;     ...
;                 if (!is_ctx) { const int t = row - rowb, pos = axis ? (t & 63) : (t >> 6); const f32x4* tp = (const f32x4*)(rope + (size_t)(pos * NQ + j0) * 2);
; #pragma unroll
;                     for (int q = 0; q < 4; ++q) { const f32x4 cs = tp[q];
; #pragma unroll
;                         for (int hh = 0; hh < 2; ++hh) { const int e = 2 * q + hh; const float c = hh ? cs[2] : cs[0], s = hh ? cs[3] : cs[1];
;                             const float x1 = acc[ai][0][m][e >> 2][e & 3], x2 = acc[ai][1][m][e >> 2][e & 3];
;                             y1[e] = (x1 * c - x2 * s) * sc; y2[e] = (x2 * c + x1 * s) * sc; } }
;                 } else {
; #pragma unroll
;                     for (int e = 0; e < 8; ++e) { y1[e] = acc[ai][0][m][e >> 2][e & 3] * sc; y2[e] = acc[ai][1][m][e >> 2][e & 3] * sc; }
;                 }
;                 bf16_t* rp = dst + (size_t)row * ld;
;                 *(u32x4*)(rp + c1) = pack8(y1); *(u32x4*)(rp + c1 + dx2) = pack8(y2);
.LBB0_340:
	v_ashrrev_i32_e32 v131, 31, v130
	v_lshlrev_b64 v[130:131], 11, v[130:131]
	v_cvt_pk_bf16_f32 v172, v142, v143
	v_cvt_pk_bf16_f32 v173, v168, v169
	v_cvt_pk_bf16_f32 v174, v170, v171
	v_cvt_pk_bf16_f32 v175, v140, v141
	v_lshl_add_u64 v[140:141], v[128:129], 0, v[130:131]
	v_cvt_pk_bf16_f32 v130, v132, v133
	v_cvt_pk_bf16_f32 v131, v134, v135
	v_cvt_pk_bf16_f32 v132, v136, v137
	v_cvt_pk_bf16_f32 v133, v138, v139
	flat_store_dwordx4 v[140:141], v[172:175]
	flat_store_dwordx4 v[140:141], v[130:133] offset:128
	s_and_b64 vcc, exec, s[10:11]
	s_mov_b64 s[10:11], -1
	v_add_u32_e32 v130, 0xb0, v166
	s_cbranch_vccnz .LBB0_342
	v_subrev_u32_e32 v131, s61, v130
	v_and_b32_e32 v132, 63, v130
	v_lshrrev_b32_e32 v131, 6, v131
	v_cndmask_b32_e64 v131, v132, v131, s[6:7]
	v_lshl_add_u32 v132, v131, 6, v144
	v_ashrrev_i32_e32 v133, 31, v132
	v_lshl_add_u64 v[140:141], v[132:133], 3, s[30:31]
	flat_load_dwordx4 v[132:135], v[140:141]
	flat_load_dwordx4 v[170:173], v[140:141] offset:48
	flat_load_dwordx4 v[208:211], v[140:141] offset:16
	flat_load_dwordx4 v[212:215], v[140:141] offset:32
	s_mov_b64 s[10:11], 0
	s_waitcnt vmcnt(0) lgkmcnt(0)
	v_mov_b32_e32 v142, v132
	v_mov_b32_e32 v143, v134
	v_mov_b32_e32 v134, v133
	v_pk_mul_f32 v[132:133], v[4:5], v[142:143]
	v_pk_mul_f32 v[168:169], v[4:5], v[134:135]
	v_pk_fma_f32 v[132:133], v[12:13], v[134:135], v[132:133]
	v_mov_b32_e32 v134, v208
	v_mov_b32_e32 v135, v209
	v_mov_b32_e32 v136, v210
	v_mov_b32_e32 v137, v211
	v_mul_f32_e32 v144, v10, v171
	v_mul_f32_e32 v182, v2, v171
	v_pk_fma_f32 v[142:143], v[12:13], v[142:143], v[168:169] neg_lo:[0,0,1] neg_hi:[0,0,1]
	s_waitcnt vmcnt(0) lgkmcnt(0)
	v_mov_b32_e32 v174, v134
	v_mov_b32_e32 v175, v136
	v_mov_b32_e32 v136, v135
	v_pk_mul_f32 v[134:135], v[6:7], v[174:175]
	v_pk_mul_f32 v[176:177], v[6:7], v[136:137]
	v_pk_fma_f32 v[134:135], v[14:15], v[136:137], v[134:135]
	v_mov_b32_e32 v136, v212
	v_mov_b32_e32 v137, v213
	v_mov_b32_e32 v138, v214
	v_mov_b32_e32 v139, v215
	v_mul_f32_e32 v140, v10, v170
	v_pk_fma_f32 v[168:169], v[14:15], v[174:175], v[176:177] neg_lo:[0,0,1] neg_hi:[0,0,1]
	v_mov_b32_e32 v174, v3
	v_mov_b32_e32 v175, v11
	s_waitcnt vmcnt(0) lgkmcnt(0)
	v_mov_b32_e32 v178, v136
	v_mov_b32_e32 v179, v138
	v_mov_b32_e32 v138, v137
	v_pk_mul_f32 v[136:137], v[0:1], v[178:179]
	v_pk_mul_f32 v[180:181], v[0:1], v[138:139]
	v_pk_fma_f32 v[136:137], v[8:9], v[138:139], v[136:137]
	v_mov_b32_e32 v138, v2
	v_mov_b32_e32 v139, v10
	v_pk_fma_f32 v[138:139], v[138:139], v[170:171], v[144:145] op_sel_hi:[1,1,0]
	v_mov_b32_e32 v170, v11
	v_mov_b32_e32 v171, v3
	v_pk_mul_f32 v[170:171], v[170:171], v[172:173]
	v_pk_mul_f32 v[172:173], v[174:175], v[172:173]
	v_mov_b32_e32 v141, v170
	v_mov_b32_e32 v183, v171
	v_pk_fma_f32 v[170:171], v[8:9], v[178:179], v[180:181] neg_lo:[0,0,1] neg_hi:[0,0,1]
	v_pk_add_f32 v[140:141], v[140:141], v[182:183] neg_lo:[0,1] neg_hi:[0,1]
	v_add_f32_e32 v139, v173, v172

;     template <int NQ> __device__ __forceinline__ void roped(const float* rope, const f32x4 (&acc)[2][2][4][2], int row0, bool is_ctx, int rowb  , int axis, int j0,
;                                                              bf16_t* dst, int ld, int c1, int dx2, float sc, int cz  ) const {
;     ...
;                 if (!is_ctx) { const int t = row - rowb, pos = axis ? (t & 63) : (t >> 6); const f32x4* tp = (const f32x4*)(rope + (size_t)(pos * NQ + j0) * 2);
; #pragma unroll
;                     for (int q = 0; q < 4; ++q) { const f32x4 cs = tp[q];
; #pragma unroll
;                         for (int hh = 0; hh < 2; ++hh) { const int e = 2 * q + hh; const float c = hh ? cs[2] : cs[0], s = hh ? cs[3] : cs[1];
;                             const float x1 = acc[ai][0][m][e >> 2][e & 3], x2 = acc[ai][1][m][e >> 2][e & 3];
;                             y1[e] = (x1 * c - x2 * s) * sc; y2[e] = (x2 * c + x1 * s) * sc; } }
;     __device__ __forceinline__ void operator()(const f32x4 (&acc)[2][2][4][2], const Unit& u, int wr, int wc, int fr, int fq) const {
;     ...
;             if (u.pn < 8) { const int axis = fq >> 1, j0 = (fq & 1) * 8;
;                 if (u.pn < 4) { const int ug = u.pn * 4 + wc; roped<16>(rope, acc, row0, is_ctx, rowb, axis, j0, (bf16_t*)BIG, 2048, ug * 128 + (ug & 1) * 64 + axis * 32 + j0, 16, 0.125f, ug * 128 + ((ug & 1) ^ 1) * 64 + axis * 32 + j0); }
;                 else roped<16>(rope, acc, row0, is_ctx, rowb, axis, j0, (bf16_t*)(BIG + 2 * U1), 1024, (u.pn - 4) * 256 + wc * 64 + axis * 32 + j0, 16, 1.f, -1);
.LBB0_351:
	s_andn2_b64 vcc, exec, s[10:11]
	s_cbranch_vccnz .LBB0_436
	v_lshlrev_b32_e32 v128, 3, v204
	v_and_b32_e32 v159, 8, v128
	v_lshlrev_b32_e32 v128, 4, v204
	s_cmp_gt_i32 s95, 3
	v_and_b32_e32 v144, 0xffffffe0, v128
	s_mov_b64 s[12:13], -1
	v_cmp_gt_u32_e64 s[10:11], 2, v204
	s_cbranch_scc0 .LBB0_386
	s_and_b64 vcc, exec, s[56:57]
	s_cbranch_vccz .LBB0_355
	v_subrev_u32_e32 v128, s61, v166
	v_and_b32_e32 v129, 63, v205
	v_ashrrev_i32_e32 v128, 6, v128
	v_cndmask_b32_e64 v128, v129, v128, s[10:11]
	v_lshl_or_b32 v128, v128, 4, v159
	v_ashrrev_i32_e32 v129, 31, v128
	v_lshl_add_u64 v[138:139], v[128:129], 3, s[68:69]
	flat_load_dwordx4 v[128:131], v[138:139]
	flat_load_dwordx4 v[168:171], v[138:139] offset:48
	flat_load_dwordx4 v[208:211], v[138:139] offset:16
	flat_load_dwordx4 v[212:215], v[138:139] offset:32
	s_mov_b64 s[12:13], 0
	s_waitcnt vmcnt(0) lgkmcnt(0)
	v_mov_b32_e32 v140, v128
	v_mov_b32_e32 v141, v130
	v_mov_b32_e32 v130, v129
	v_pk_mul_f32 v[132:133], v[116:117], v[140:141]
	v_pk_mul_f32 v[128:129], v[116:117], v[130:131]
	v_pk_fma_f32 v[130:131], v[124:125], v[130:131], v[132:133]
	v_mov_b32_e32 v132, v208
	v_mov_b32_e32 v133, v209
	v_mov_b32_e32 v134, v210
	v_mov_b32_e32 v135, v211
	v_mul_f32_e32 v180, v122, v169
	v_mul_f32_e32 v178, v114, v169
	v_pk_fma_f32 v[140:141], v[124:125], v[140:141], v[128:129] neg_lo:[0,0,1] neg_hi:[0,0,1]
	v_mov_b32_e32 v128, v115
	v_mov_b32_e32 v129, v123
	v_pk_mul_f32 v[128:129], v[128:129], v[170:171]
	s_waitcnt vmcnt(0) lgkmcnt(0)
	v_mov_b32_e32 v142, v132
	v_mov_b32_e32 v143, v134
	v_mov_b32_e32 v134, v133
	v_pk_mul_f32 v[132:133], v[118:119], v[142:143]
	v_pk_mul_f32 v[172:173], v[118:119], v[134:135]
	v_pk_fma_f32 v[132:133], v[126:127], v[134:135], v[132:133]
	v_mov_b32_e32 v134, v212
	v_mov_b32_e32 v135, v213
	v_mov_b32_e32 v136, v214
	v_mov_b32_e32 v137, v215
	v_mul_f32_e32 v138, v122, v168
	v_pk_fma_f32 v[142:143], v[126:127], v[142:143], v[172:173] neg_lo:[0,0,1] neg_hi:[0,0,1]
	s_waitcnt vmcnt(0) lgkmcnt(0)
	v_mov_b32_e32 v174, v134
	v_mov_b32_e32 v175, v136
	v_mov_b32_e32 v136, v135
	v_pk_mul_f32 v[134:135], v[112:113], v[174:175]
	v_pk_mul_f32 v[176:177], v[112:113], v[136:137]
	v_pk_fma_f32 v[134:135], v[120:121], v[136:137], v[134:135]
	v_mov_b32_e32 v136, v114
	v_mov_b32_e32 v137, v122
	v_pk_fma_f32 v[136:137], v[136:137], v[168:169], v[180:181] op_sel_hi:[1,1,0]
	v_mov_b32_e32 v168, v123
	v_mov_b32_e32 v169, v115
	v_pk_mul_f32 v[168:169], v[168:169], v[170:171]
	v_add_f32_e32 v137, v129, v128
	v_mov_b32_e32 v139, v168
	v_mov_b32_e32 v179, v169
	v_pk_fma_f32 v[168:169], v[120:121], v[174:175], v[176:177] neg_lo:[0,0,1] neg_hi:[0,0,1]
	v_pk_add_f32 v[138:139], v[138:139], v[178:179] neg_lo:[0,1] neg_hi:[0,1]

; __device__ __forceinline__ u32x4 pack8(const float* v) { u32x4 w; w.x = cvt_pk_bf16(v[0], v[1]); w.y = cvt_pk_bf16(v[2], v[3]); w.z = cvt_pk_bf16(v[4], v[5]); w.w = cvt_pk_bf16(v[6], v[7]); return w; }
;     template <int NQ> __device__ __forceinline__ void roped(const float* rope, const f32x4 (&acc)[2][2][4][2], int row0, bool is_ctx, int rowb  , int axis, int j0,
;                                                              bf16_t* dst, int ld, int c1, int dx2, float sc, int cz  ) const {
;     ...
;                 if (!is_ctx) { const int t = row - rowb, pos = axis ? (t & 63) : (t >> 6); const f32x4* tp = (const f32x4*)(rope + (size_t)(pos * NQ + j0) * 2);
; #pragma unroll
;                     for (int q = 0; q < 4; ++q) { const f32x4 cs = tp[q];
; #pragma unroll
;                         for (int hh = 0; hh < 2; ++hh) { const int e = 2 * q + hh; const float c = hh ? cs[2] : cs[0], s = hh ? cs[3] : cs[1];
;                             const float x1 = acc[ai][0][m][e >> 2][e & 3], x2 = acc[ai][1][m][e >> 2][e & 3];
;                             y1[e] = (x1 * c - x2 * s) * sc; y2[e] = (x2 * c + x1 * s) * sc; } }
;                 } else {
; #pragma unroll
;                     for (int e = 0; e < 8; ++e) { y1[e] = acc[ai][0][m][e >> 2][e & 3] * sc; y2[e] = acc[ai][1][m][e >> 2][e & 3] * sc; }
;                 }
;                 bf16_t* rp = dst + (size_t)row * ld;
;                 *(u32x4*)(rp + c1) = pack8(y1); *(u32x4*)(rp + c1 + dx2) = pack8(y2);
.LBB0_357:
	s_lshl_b32 s12, s95, 8
	v_readlane_b32 s13, v255, 28
	s_add_i32 s12, s13, s12
	v_add_u32_e32 v128, s12, v144
	v_ashrrev_i32_e32 v167, 31, v166
	v_readlane_b32 s12, v255, 3
	v_or_b32_e32 v128, v128, v159
	v_lshlrev_b64 v[170:171], 11, v[166:167]
	v_readlane_b32 s13, v255, 4
	v_ashrrev_i32_e32 v129, 31, v128
	v_cvt_pk_bf16_f32 v140, v140, v141
	v_lshl_add_u64 v[170:171], s[12:13], 0, v[170:171]
	v_cvt_pk_bf16_f32 v141, v142, v143
	v_cvt_pk_bf16_f32 v142, v168, v169
	v_cvt_pk_bf16_f32 v143, v138, v139
	v_lshl_add_u64 v[138:139], v[128:129], 1, v[170:171]
	v_cvt_pk_bf16_f32 v130, v130, v131
	v_cvt_pk_bf16_f32 v131, v132, v133
	v_cvt_pk_bf16_f32 v132, v134, v135
	v_cvt_pk_bf16_f32 v133, v136, v137
	flat_store_dwordx4 v[138:139], v[140:143]
	flat_store_dwordx4 v[138:139], v[130:133] offset:32
	s_andn2_b64 vcc, exec, s[56:57]
	s_mov_b64 s[14:15], -1
	v_cndmask_b32_e64 v131, 0, 1, s[56:57]
	v_add_u32_e32 v130, 16, v166
	v_cmp_ne_u32_e64 s[12:13], 1, v131
	s_cbranch_vccnz .LBB0_359
	v_subrev_u32_e32 v131, s61, v130
	v_and_b32_e32 v132, 63, v130
	v_ashrrev_i32_e32 v131, 6, v131
	v_cndmask_b32_e64 v131, v132, v131, s[10:11]
	v_lshl_or_b32 v132, v131, 4, v159
	v_ashrrev_i32_e32 v133, 31, v132
	v_lshl_add_u64 v[140:141], v[132:133], 3, s[68:69]
	flat_load_dwordx4 v[132:135], v[140:141]
	flat_load_dwordx4 v[170:173], v[140:141] offset:48
	flat_load_dwordx4 v[208:211], v[140:141] offset:16
	flat_load_dwordx4 v[212:215], v[140:141] offset:32
	s_mov_b64 s[14:15], 0
	s_waitcnt vmcnt(0) lgkmcnt(0)
	v_mov_b32_e32 v142, v132
	v_mov_b32_e32 v143, v134
	v_mov_b32_e32 v134, v133
	v_pk_mul_f32 v[132:133], v[100:101], v[142:143]
	v_pk_mul_f32 v[168:169], v[100:101], v[134:135]
	v_pk_fma_f32 v[132:133], v[108:109], v[134:135], v[132:133]
	v_mov_b32_e32 v134, v208
	v_mov_b32_e32 v135, v209
	v_mov_b32_e32 v136, v210
	v_mov_b32_e32 v137, v211
	v_mul_f32_e32 v184, v106, v171
	v_mul_f32_e32 v182, v98, v171
	v_pk_fma_f32 v[142:143], v[108:109], v[142:143], v[168:169] neg_lo:[0,0,1] neg_hi:[0,0,1]
	s_waitcnt vmcnt(0) lgkmcnt(0)
	v_mov_b32_e32 v174, v134
	v_mov_b32_e32 v175, v136
	v_mov_b32_e32 v136, v135
	v_pk_mul_f32 v[134:135], v[102:103], v[174:175]
	v_pk_mul_f32 v[176:177], v[102:103], v[136:137]
	v_pk_fma_f32 v[134:135], v[110:111], v[136:137], v[134:135]
	v_mov_b32_e32 v136, v212
	v_mov_b32_e32 v137, v213
	v_mov_b32_e32 v138, v214
	v_mov_b32_e32 v139, v215
	v_mul_f32_e32 v140, v106, v170
	v_pk_fma_f32 v[168:169], v[110:111], v[174:175], v[176:177] neg_lo:[0,0,1] neg_hi:[0,0,1]
	v_mov_b32_e32 v174, v99
	v_mov_b32_e32 v175, v107
	s_waitcnt vmcnt(0) lgkmcnt(0)
	v_mov_b32_e32 v178, v136
	v_mov_b32_e32 v179, v138
	v_mov_b32_e32 v138, v137
	v_pk_mul_f32 v[136:137], v[96:97], v[178:179]
	v_pk_mul_f32 v[180:181], v[96:97], v[138:139]
	v_pk_fma_f32 v[136:137], v[104:105], v[138:139], v[136:137]
	v_mov_b32_e32 v138, v98
	v_mov_b32_e32 v139, v106
	v_pk_fma_f32 v[138:139], v[138:139], v[170:171], v[184:185] op_sel_hi:[1,1,0]
	v_mov_b32_e32 v170, v107
	v_mov_b32_e32 v171, v99
	v_pk_mul_f32 v[170:171], v[170:171], v[172:173]
	v_pk_mul_f32 v[172:173], v[174:175], v[172:173]
	v_mov_b32_e32 v141, v170
	v_mov_b32_e32 v183, v171
	v_pk_fma_f32 v[170:171], v[104:105], v[178:179], v[180:181] neg_lo:[0,0,1] neg_hi:[0,0,1]
	v_pk_add_f32 v[140:141], v[140:141], v[182:183] neg_lo:[0,1] neg_hi:[0,1]
	v_add_f32_e32 v139, v173, v172

; __device__ __forceinline__ u32x4 pack8(const float* v) { u32x4 w; w.x = cvt_pk_bf16(v[0], v[1]); w.y = cvt_pk_bf16(v[2], v[3]); w.z = cvt_pk_bf16(v[4], v[5]); w.w = cvt_pk_bf16(v[6], v[7]); return w; }
;     template <int NQ> __device__ __forceinline__ void roped(const float* rope, const f32x4 (&acc)[2][2][4][2], int row0, bool is_ctx, int rowb  , int axis, int j0,
;                                                              bf16_t* dst, int ld, int c1, int dx2, float sc, int cz  ) const {
;     ...
;                 if (!is_ctx) { const int t = row - rowb, pos = axis ? (t & 63) : (t >> 6); const f32x4* tp = (const f32x4*)(rope + (size_t)(pos * NQ + j0) * 2);
; #pragma unroll
;                     for (int q = 0; q < 4; ++q) { const f32x4 cs = tp[q];
; #pragma unroll
;                         for (int hh = 0; hh < 2; ++hh) { const int e = 2 * q + hh; const float c = hh ? cs[2] : cs[0], s = hh ? cs[3] : cs[1];
;                             const float x1 = acc[ai][0][m][e >> 2][e & 3], x2 = acc[ai][1][m][e >> 2][e & 3];
;                             y1[e] = (x1 * c - x2 * s) * sc; y2[e] = (x2 * c + x1 * s) * sc; } }
;                 } else {
; #pragma unroll
;                     for (int e = 0; e < 8; ++e) { y1[e] = acc[ai][0][m][e >> 2][e & 3] * sc; y2[e] = acc[ai][1][m][e >> 2][e & 3] * sc; }
;                 }
;                 bf16_t* rp = dst + (size_t)row * ld;
;                 *(u32x4*)(rp + c1) = pack8(y1); *(u32x4*)(rp + c1 + dx2) = pack8(y2);
.LBB0_361:
	v_ashrrev_i32_e32 v131, 31, v130
	v_readlane_b32 s14, v255, 3
	v_lshlrev_b64 v[130:131], 11, v[130:131]
	v_readlane_b32 s15, v255, 4
	v_cvt_pk_bf16_f32 v172, v142, v143
	v_cvt_pk_bf16_f32 v173, v168, v169
	v_lshl_add_u64 v[130:131], s[14:15], 0, v[130:131]
	v_cvt_pk_bf16_f32 v174, v170, v171
	v_cvt_pk_bf16_f32 v175, v140, v141
	v_lshl_add_u64 v[140:141], v[128:129], 1, v[130:131]
	v_cvt_pk_bf16_f32 v130, v132, v133
	v_cvt_pk_bf16_f32 v131, v134, v135
	v_cvt_pk_bf16_f32 v132, v136, v137
	v_cvt_pk_bf16_f32 v133, v138, v139
	flat_store_dwordx4 v[140:141], v[172:175]
	flat_store_dwordx4 v[140:141], v[130:133] offset:32
	s_and_b64 vcc, exec, s[12:13]
	s_mov_b64 s[14:15], -1
	v_add_u32_e32 v130, 32, v166
	s_cbranch_vccnz .LBB0_363
	v_subrev_u32_e32 v131, s61, v130
	v_and_b32_e32 v132, 63, v130
	v_ashrrev_i32_e32 v131, 6, v131
	v_cndmask_b32_e64 v131, v132, v131, s[10:11]
	v_lshl_or_b32 v132, v131, 4, v159
	v_ashrrev_i32_e32 v133, 31, v132
	v_lshl_add_u64 v[140:141], v[132:133], 3, s[68:69]
	flat_load_dwordx4 v[132:135], v[140:141]
	flat_load_dwordx4 v[170:173], v[140:141] offset:48
	flat_load_dwordx4 v[208:211], v[140:141] offset:16
	flat_load_dwordx4 v[212:215], v[140:141] offset:32
	s_mov_b64 s[14:15], 0
	s_waitcnt vmcnt(0) lgkmcnt(0)
	v_mov_b32_e32 v142, v132
	v_mov_b32_e32 v143, v134
	v_mov_b32_e32 v134, v133
	v_pk_mul_f32 v[132:133], v[84:85], v[142:143]
	v_pk_mul_f32 v[168:169], v[84:85], v[134:135]
	v_pk_fma_f32 v[132:133], v[92:93], v[134:135], v[132:133]
	v_mov_b32_e32 v134, v208
	v_mov_b32_e32 v135, v209
	v_mov_b32_e32 v136, v210
	v_mov_b32_e32 v137, v211
	v_mul_f32_e32 v184, v90, v171
	v_mul_f32_e32 v182, v82, v171
	v_pk_fma_f32 v[142:143], v[92:93], v[142:143], v[168:169] neg_lo:[0,0,1] neg_hi:[0,0,1]
	s_waitcnt vmcnt(0) lgkmcnt(0)
	v_mov_b32_e32 v174, v134
	v_mov_b32_e32 v175, v136
	v_mov_b32_e32 v136, v135
	v_pk_mul_f32 v[134:135], v[86:87], v[174:175]
	v_pk_mul_f32 v[176:177], v[86:87], v[136:137]
	v_pk_fma_f32 v[134:135], v[94:95], v[136:137], v[134:135]
	v_mov_b32_e32 v136, v212
	v_mov_b32_e32 v137, v213
	v_mov_b32_e32 v138, v214
	v_mov_b32_e32 v139, v215
	v_mul_f32_e32 v140, v90, v170
	v_pk_fma_f32 v[168:169], v[94:95], v[174:175], v[176:177] neg_lo:[0,0,1] neg_hi:[0,0,1]
	v_mov_b32_e32 v174, v83
	v_mov_b32_e32 v175, v91
	s_waitcnt vmcnt(0) lgkmcnt(0)
	v_mov_b32_e32 v178, v136
	v_mov_b32_e32 v179, v138
	v_mov_b32_e32 v138, v137
	v_pk_mul_f32 v[136:137], v[80:81], v[178:179]
	v_pk_mul_f32 v[180:181], v[80:81], v[138:139]
	v_pk_fma_f32 v[136:137], v[88:89], v[138:139], v[136:137]
	v_mov_b32_e32 v138, v82
	v_mov_b32_e32 v139, v90
	v_pk_fma_f32 v[138:139], v[138:139], v[170:171], v[184:185] op_sel_hi:[1,1,0]
	v_mov_b32_e32 v170, v91
	v_mov_b32_e32 v171, v83
	v_pk_mul_f32 v[170:171], v[170:171], v[172:173]
	v_pk_mul_f32 v[172:173], v[174:175], v[172:173]
	v_mov_b32_e32 v141, v170
	v_mov_b32_e32 v183, v171
	v_pk_fma_f32 v[170:171], v[88:89], v[178:179], v[180:181] neg_lo:[0,0,1] neg_hi:[0,0,1]
	v_pk_add_f32 v[140:141], v[140:141], v[182:183] neg_lo:[0,1] neg_hi:[0,1]
	v_add_f32_e32 v139, v173, v172

; __device__ __forceinline__ u32x4 pack8(const float* v) { u32x4 w; w.x = cvt_pk_bf16(v[0], v[1]); w.y = cvt_pk_bf16(v[2], v[3]); w.z = cvt_pk_bf16(v[4], v[5]); w.w = cvt_pk_bf16(v[6], v[7]); return w; }
;     template <int NQ> __device__ __forceinline__ void roped(const float* rope, const f32x4 (&acc)[2][2][4][2], int row0, bool is_ctx, int rowb  , int axis, int j0,
;                                                              bf16_t* dst, int ld, int c1, int dx2, float sc, int cz  ) const {
;     ...
;                 if (!is_ctx) { const int t = row - rowb, pos = axis ? (t & 63) : (t >> 6); const f32x4* tp = (const f32x4*)(rope + (size_t)(pos * NQ + j0) * 2);
; #pragma unroll
;                     for (int q = 0; q < 4; ++q) { const f32x4 cs = tp[q];
; #pragma unroll
;                         for (int hh = 0; hh < 2; ++hh) { const int e = 2 * q + hh; const float c = hh ? cs[2] : cs[0], s = hh ? cs[3] : cs[1];
;                             const float x1 = acc[ai][0][m][e >> 2][e & 3], x2 = acc[ai][1][m][e >> 2][e & 3];
;                             y1[e] = (x1 * c - x2 * s) * sc; y2[e] = (x2 * c + x1 * s) * sc; } }
;                 } else {
; #pragma unroll
;                     for (int e = 0; e < 8; ++e) { y1[e] = acc[ai][0][m][e >> 2][e & 3] * sc; y2[e] = acc[ai][1][m][e >> 2][e & 3] * sc; }
;                 }
;                 bf16_t* rp = dst + (size_t)row * ld;
;                 *(u32x4*)(rp + c1) = pack8(y1); *(u32x4*)(rp + c1 + dx2) = pack8(y2);
.LBB0_365:
	v_ashrrev_i32_e32 v131, 31, v130
	v_readlane_b32 s14, v255, 3
	v_lshlrev_b64 v[130:131], 11, v[130:131]
	v_readlane_b32 s15, v255, 4
	v_cvt_pk_bf16_f32 v172, v142, v143
	v_cvt_pk_bf16_f32 v173, v168, v169
	v_lshl_add_u64 v[130:131], s[14:15], 0, v[130:131]
	v_cvt_pk_bf16_f32 v174, v170, v171
	v_cvt_pk_bf16_f32 v175, v140, v141
	v_lshl_add_u64 v[140:141], v[128:129], 1, v[130:131]
	v_cvt_pk_bf16_f32 v130, v132, v133
	v_cvt_pk_bf16_f32 v131, v134, v135
	v_cvt_pk_bf16_f32 v132, v136, v137
	v_cvt_pk_bf16_f32 v133, v138, v139
	flat_store_dwordx4 v[140:141], v[172:175]
	flat_store_dwordx4 v[140:141], v[130:133] offset:32
	s_and_b64 vcc, exec, s[12:13]
	s_mov_b64 s[14:15], -1
	v_add_u32_e32 v130, 48, v166
	s_cbranch_vccnz .LBB0_367
	v_subrev_u32_e32 v131, s61, v130
	v_and_b32_e32 v132, 63, v130
	v_ashrrev_i32_e32 v131, 6, v131
	v_cndmask_b32_e64 v131, v132, v131, s[10:11]
	v_lshl_or_b32 v132, v131, 4, v159
	v_ashrrev_i32_e32 v133, 31, v132
	v_lshl_add_u64 v[140:141], v[132:133], 3, s[68:69]
	flat_load_dwordx4 v[132:135], v[140:141]
	flat_load_dwordx4 v[170:173], v[140:141] offset:48
	flat_load_dwordx4 v[208:211], v[140:141] offset:16
	flat_load_dwordx4 v[212:215], v[140:141] offset:32
	s_mov_b64 s[14:15], 0
	s_waitcnt vmcnt(0) lgkmcnt(0)
	v_mov_b32_e32 v142, v132
	v_mov_b32_e32 v143, v134
	v_mov_b32_e32 v134, v133
	v_pk_mul_f32 v[132:133], v[68:69], v[142:143]
	v_pk_mul_f32 v[168:169], v[68:69], v[134:135]
	v_pk_fma_f32 v[132:133], v[76:77], v[134:135], v[132:133]
	v_mov_b32_e32 v134, v208
	v_mov_b32_e32 v135, v209
	v_mov_b32_e32 v136, v210
	v_mov_b32_e32 v137, v211
	v_mul_f32_e32 v184, v74, v171
	v_mul_f32_e32 v182, v66, v171
	v_pk_fma_f32 v[142:143], v[76:77], v[142:143], v[168:169] neg_lo:[0,0,1] neg_hi:[0,0,1]
	s_waitcnt vmcnt(0) lgkmcnt(0)
	v_mov_b32_e32 v174, v134
	v_mov_b32_e32 v175, v136
	v_mov_b32_e32 v136, v135
	v_pk_mul_f32 v[134:135], v[70:71], v[174:175]
	v_pk_mul_f32 v[176:177], v[70:71], v[136:137]
	v_pk_fma_f32 v[134:135], v[78:79], v[136:137], v[134:135]
	v_mov_b32_e32 v136, v212
	v_mov_b32_e32 v137, v213
	v_mov_b32_e32 v138, v214
	v_mov_b32_e32 v139, v215
	v_mul_f32_e32 v140, v74, v170
	v_pk_fma_f32 v[168:169], v[78:79], v[174:175], v[176:177] neg_lo:[0,0,1] neg_hi:[0,0,1]
	v_mov_b32_e32 v174, v67
	v_mov_b32_e32 v175, v75
	s_waitcnt vmcnt(0) lgkmcnt(0)
	v_mov_b32_e32 v178, v136
	v_mov_b32_e32 v179, v138
	v_mov_b32_e32 v138, v137
	v_pk_mul_f32 v[136:137], v[64:65], v[178:179]
	v_pk_mul_f32 v[180:181], v[64:65], v[138:139]
	v_pk_fma_f32 v[136:137], v[72:73], v[138:139], v[136:137]
	v_mov_b32_e32 v138, v66
	v_mov_b32_e32 v139, v74
	v_pk_fma_f32 v[138:139], v[138:139], v[170:171], v[184:185] op_sel_hi:[1,1,0]
	v_mov_b32_e32 v170, v75
	v_mov_b32_e32 v171, v67
	v_pk_mul_f32 v[170:171], v[170:171], v[172:173]
	v_pk_mul_f32 v[172:173], v[174:175], v[172:173]
	v_mov_b32_e32 v141, v170
	v_mov_b32_e32 v183, v171
	v_pk_fma_f32 v[170:171], v[72:73], v[178:179], v[180:181] neg_lo:[0,0,1] neg_hi:[0,0,1]
	v_pk_add_f32 v[140:141], v[140:141], v[182:183] neg_lo:[0,1] neg_hi:[0,1]
	v_add_f32_e32 v139, v173, v172

; __device__ __forceinline__ u32x4 pack8(const float* v) { u32x4 w; w.x = cvt_pk_bf16(v[0], v[1]); w.y = cvt_pk_bf16(v[2], v[3]); w.z = cvt_pk_bf16(v[4], v[5]); w.w = cvt_pk_bf16(v[6], v[7]); return w; }
;     template <int NQ> __device__ __forceinline__ void roped(const float* rope, const f32x4 (&acc)[2][2][4][2], int row0, bool is_ctx, int rowb  , int axis, int j0,
;                                                              bf16_t* dst, int ld, int c1, int dx2, float sc, int cz  ) const {
;     ...
;                 if (!is_ctx) { const int t = row - rowb, pos = axis ? (t & 63) : (t >> 6); const f32x4* tp = (const f32x4*)(rope + (size_t)(pos * NQ + j0) * 2);
; #pragma unroll
;                     for (int q = 0; q < 4; ++q) { const f32x4 cs = tp[q];
; #pragma unroll
;                         for (int hh = 0; hh < 2; ++hh) { const int e = 2 * q + hh; const float c = hh ? cs[2] : cs[0], s = hh ? cs[3] : cs[1];
;                             const float x1 = acc[ai][0][m][e >> 2][e & 3], x2 = acc[ai][1][m][e >> 2][e & 3];
;                             y1[e] = (x1 * c - x2 * s) * sc; y2[e] = (x2 * c + x1 * s) * sc; } }
;                 } else {
; #pragma unroll
;                     for (int e = 0; e < 8; ++e) { y1[e] = acc[ai][0][m][e >> 2][e & 3] * sc; y2[e] = acc[ai][1][m][e >> 2][e & 3] * sc; }
;                 }
;                 bf16_t* rp = dst + (size_t)row * ld;
;                 *(u32x4*)(rp + c1) = pack8(y1); *(u32x4*)(rp + c1 + dx2) = pack8(y2);
.LBB0_369:
	v_ashrrev_i32_e32 v131, 31, v130
	v_readlane_b32 s14, v255, 3
	v_lshlrev_b64 v[130:131], 11, v[130:131]
	v_readlane_b32 s15, v255, 4
	v_cvt_pk_bf16_f32 v172, v142, v143
	v_cvt_pk_bf16_f32 v173, v168, v169
	v_lshl_add_u64 v[130:131], s[14:15], 0, v[130:131]
	v_cvt_pk_bf16_f32 v174, v170, v171
	v_cvt_pk_bf16_f32 v175, v140, v141
	v_lshl_add_u64 v[140:141], v[128:129], 1, v[130:131]
	v_cvt_pk_bf16_f32 v130, v132, v133
	v_cvt_pk_bf16_f32 v131, v134, v135
	v_cvt_pk_bf16_f32 v132, v136, v137
	v_cvt_pk_bf16_f32 v133, v138, v139
	flat_store_dwordx4 v[140:141], v[172:175]
	flat_store_dwordx4 v[140:141], v[130:133] offset:32
	s_and_b64 vcc, exec, s[12:13]
	s_mov_b64 s[14:15], -1
	v_add_u32_e32 v130, 0x80, v166
	s_cbranch_vccnz .LBB0_371
	v_subrev_u32_e32 v131, s61, v130
	v_and_b32_e32 v132, 63, v205
	v_ashrrev_i32_e32 v131, 6, v131
	v_cndmask_b32_e64 v131, v132, v131, s[10:11]
	v_lshl_or_b32 v132, v131, 4, v159
	v_ashrrev_i32_e32 v133, 31, v132
	v_lshl_add_u64 v[140:141], v[132:133], 3, s[68:69]
	flat_load_dwordx4 v[132:135], v[140:141]
	flat_load_dwordx4 v[170:173], v[140:141] offset:48
	flat_load_dwordx4 v[208:211], v[140:141] offset:16
	flat_load_dwordx4 v[212:215], v[140:141] offset:32
	s_mov_b64 s[14:15], 0
	s_waitcnt vmcnt(0) lgkmcnt(0)
	v_mov_b32_e32 v142, v132
	v_mov_b32_e32 v143, v134
	v_mov_b32_e32 v134, v133
	v_pk_mul_f32 v[132:133], v[52:53], v[142:143]
	v_pk_mul_f32 v[168:169], v[52:53], v[134:135]
	v_pk_fma_f32 v[132:133], v[60:61], v[134:135], v[132:133]
	v_mov_b32_e32 v134, v208
	v_mov_b32_e32 v135, v209
	v_mov_b32_e32 v136, v210
	v_mov_b32_e32 v137, v211
	v_mul_f32_e32 v184, v58, v171
	v_mul_f32_e32 v182, v50, v171
	v_pk_fma_f32 v[142:143], v[60:61], v[142:143], v[168:169] neg_lo:[0,0,1] neg_hi:[0,0,1]
	s_waitcnt vmcnt(0) lgkmcnt(0)
	v_mov_b32_e32 v174, v134
	v_mov_b32_e32 v175, v136
	v_mov_b32_e32 v136, v135
	v_pk_mul_f32 v[134:135], v[54:55], v[174:175]
	v_pk_mul_f32 v[176:177], v[54:55], v[136:137]
	v_pk_fma_f32 v[134:135], v[62:63], v[136:137], v[134:135]
	v_mov_b32_e32 v136, v212
	v_mov_b32_e32 v137, v213
	v_mov_b32_e32 v138, v214
	v_mov_b32_e32 v139, v215
	v_mul_f32_e32 v140, v58, v170
	v_pk_fma_f32 v[168:169], v[62:63], v[174:175], v[176:177] neg_lo:[0,0,1] neg_hi:[0,0,1]
	v_mov_b32_e32 v174, v51
	v_mov_b32_e32 v175, v59
	s_waitcnt vmcnt(0) lgkmcnt(0)
	v_mov_b32_e32 v178, v136
	v_mov_b32_e32 v179, v138
	v_mov_b32_e32 v138, v137
	v_pk_mul_f32 v[136:137], v[48:49], v[178:179]
	v_pk_mul_f32 v[180:181], v[48:49], v[138:139]
	v_pk_fma_f32 v[136:137], v[56:57], v[138:139], v[136:137]
	v_mov_b32_e32 v138, v50
	v_mov_b32_e32 v139, v58
	v_pk_fma_f32 v[138:139], v[138:139], v[170:171], v[184:185] op_sel_hi:[1,1,0]
	v_mov_b32_e32 v170, v59
	v_mov_b32_e32 v171, v51
	v_pk_mul_f32 v[170:171], v[170:171], v[172:173]
	v_pk_mul_f32 v[172:173], v[174:175], v[172:173]
	v_mov_b32_e32 v141, v170
	v_mov_b32_e32 v183, v171
	v_pk_fma_f32 v[170:171], v[56:57], v[178:179], v[180:181] neg_lo:[0,0,1] neg_hi:[0,0,1]
	v_pk_add_f32 v[140:141], v[140:141], v[182:183] neg_lo:[0,1] neg_hi:[0,1]
	v_add_f32_e32 v139, v173, v172

; __device__ __forceinline__ u32x4 pack8(const float* v) { u32x4 w; w.x = cvt_pk_bf16(v[0], v[1]); w.y = cvt_pk_bf16(v[2], v[3]); w.z = cvt_pk_bf16(v[4], v[5]); w.w = cvt_pk_bf16(v[6], v[7]); return w; }
;     template <int NQ> __device__ __forceinline__ void roped(const float* rope, const f32x4 (&acc)[2][2][4][2], int row0, bool is_ctx, int rowb  , int axis, int j0,
;                                                              bf16_t* dst, int ld, int c1, int dx2, float sc, int cz  ) const {
;     ...
;                 if (!is_ctx) { const int t = row - rowb, pos = axis ? (t & 63) : (t >> 6); const f32x4* tp = (const f32x4*)(rope + (size_t)(pos * NQ + j0) * 2);
; #pragma unroll
;                     for (int q = 0; q < 4; ++q) { const f32x4 cs = tp[q];
; #pragma unroll
;                         for (int hh = 0; hh < 2; ++hh) { const int e = 2 * q + hh; const float c = hh ? cs[2] : cs[0], s = hh ? cs[3] : cs[1];
;                             const float x1 = acc[ai][0][m][e >> 2][e & 3], x2 = acc[ai][1][m][e >> 2][e & 3];
;                             y1[e] = (x1 * c - x2 * s) * sc; y2[e] = (x2 * c + x1 * s) * sc; } }
;                 } else {
; #pragma unroll
;                     for (int e = 0; e < 8; ++e) { y1[e] = acc[ai][0][m][e >> 2][e & 3] * sc; y2[e] = acc[ai][1][m][e >> 2][e & 3] * sc; }
;                 }
;                 bf16_t* rp = dst + (size_t)row * ld;
;                 *(u32x4*)(rp + c1) = pack8(y1); *(u32x4*)(rp + c1 + dx2) = pack8(y2);
.LBB0_373:
	v_ashrrev_i32_e32 v131, 31, v130
	v_readlane_b32 s14, v255, 3
	v_lshlrev_b64 v[130:131], 11, v[130:131]
	v_readlane_b32 s15, v255, 4
	v_cvt_pk_bf16_f32 v172, v142, v143
	v_cvt_pk_bf16_f32 v173, v168, v169
	v_lshl_add_u64 v[130:131], s[14:15], 0, v[130:131]
	v_cvt_pk_bf16_f32 v174, v170, v171
	v_cvt_pk_bf16_f32 v175, v140, v141
	v_lshl_add_u64 v[140:141], v[128:129], 1, v[130:131]
	v_cvt_pk_bf16_f32 v130, v132, v133
	v_cvt_pk_bf16_f32 v131, v134, v135
	v_cvt_pk_bf16_f32 v132, v136, v137
	v_cvt_pk_bf16_f32 v133, v138, v139
	flat_store_dwordx4 v[140:141], v[172:175]
	flat_store_dwordx4 v[140:141], v[130:133] offset:32
	s_and_b64 vcc, exec, s[12:13]
	s_mov_b64 s[14:15], -1
	v_add_u32_e32 v130, 0x90, v166
	s_cbranch_vccnz .LBB0_375
	v_subrev_u32_e32 v131, s61, v130
	v_and_b32_e32 v132, 63, v130
	v_ashrrev_i32_e32 v131, 6, v131
	v_cndmask_b32_e64 v131, v132, v131, s[10:11]
	v_lshl_or_b32 v132, v131, 4, v159
	v_ashrrev_i32_e32 v133, 31, v132
	v_lshl_add_u64 v[140:141], v[132:133], 3, s[68:69]
	flat_load_dwordx4 v[132:135], v[140:141]
	flat_load_dwordx4 v[170:173], v[140:141] offset:48
	flat_load_dwordx4 v[208:211], v[140:141] offset:16
	flat_load_dwordx4 v[212:215], v[140:141] offset:32
	s_mov_b64 s[14:15], 0
	s_waitcnt vmcnt(0) lgkmcnt(0)
	v_mov_b32_e32 v142, v132
	v_mov_b32_e32 v143, v134
	v_mov_b32_e32 v134, v133
	v_pk_mul_f32 v[132:133], v[36:37], v[142:143]
	v_pk_mul_f32 v[168:169], v[36:37], v[134:135]
	v_pk_fma_f32 v[132:133], v[44:45], v[134:135], v[132:133]
	v_mov_b32_e32 v134, v208
	v_mov_b32_e32 v135, v209
	v_mov_b32_e32 v136, v210
	v_mov_b32_e32 v137, v211
	v_mul_f32_e32 v184, v42, v171
	v_mul_f32_e32 v182, v34, v171
	v_pk_fma_f32 v[142:143], v[44:45], v[142:143], v[168:169] neg_lo:[0,0,1] neg_hi:[0,0,1]
	s_waitcnt vmcnt(0) lgkmcnt(0)
	v_mov_b32_e32 v174, v134
	v_mov_b32_e32 v175, v136
	v_mov_b32_e32 v136, v135
	v_pk_mul_f32 v[134:135], v[38:39], v[174:175]
	v_pk_mul_f32 v[176:177], v[38:39], v[136:137]
	v_pk_fma_f32 v[134:135], v[46:47], v[136:137], v[134:135]
	v_mov_b32_e32 v136, v212
	v_mov_b32_e32 v137, v213
	v_mov_b32_e32 v138, v214
	v_mov_b32_e32 v139, v215
	v_mul_f32_e32 v140, v42, v170
	v_pk_fma_f32 v[168:169], v[46:47], v[174:175], v[176:177] neg_lo:[0,0,1] neg_hi:[0,0,1]
	v_mov_b32_e32 v174, v35
	v_mov_b32_e32 v175, v43
	s_waitcnt vmcnt(0) lgkmcnt(0)
	v_mov_b32_e32 v178, v136
	v_mov_b32_e32 v179, v138
	v_mov_b32_e32 v138, v137
	v_pk_mul_f32 v[136:137], v[32:33], v[178:179]
	v_pk_mul_f32 v[180:181], v[32:33], v[138:139]
	v_pk_fma_f32 v[136:137], v[40:41], v[138:139], v[136:137]
	v_mov_b32_e32 v138, v34
	v_mov_b32_e32 v139, v42
	v_pk_fma_f32 v[138:139], v[138:139], v[170:171], v[184:185] op_sel_hi:[1,1,0]
	v_mov_b32_e32 v170, v43
	v_mov_b32_e32 v171, v35
	v_pk_mul_f32 v[170:171], v[170:171], v[172:173]
	v_pk_mul_f32 v[172:173], v[174:175], v[172:173]
	v_mov_b32_e32 v141, v170
	v_mov_b32_e32 v183, v171
	v_pk_fma_f32 v[170:171], v[40:41], v[178:179], v[180:181] neg_lo:[0,0,1] neg_hi:[0,0,1]
	v_pk_add_f32 v[140:141], v[140:141], v[182:183] neg_lo:[0,1] neg_hi:[0,1]
	v_add_f32_e32 v139, v173, v172

; __device__ __forceinline__ u32x4 pack8(const float* v) { u32x4 w; w.x = cvt_pk_bf16(v[0], v[1]); w.y = cvt_pk_bf16(v[2], v[3]); w.z = cvt_pk_bf16(v[4], v[5]); w.w = cvt_pk_bf16(v[6], v[7]); return w; }
;     template <int NQ> __device__ __forceinline__ void roped(const float* rope, const f32x4 (&acc)[2][2][4][2], int row0, bool is_ctx, int rowb  , int axis, int j0,
;                                                              bf16_t* dst, int ld, int c1, int dx2, float sc, int cz  ) const {
;     ...
;                 if (!is_ctx) { const int t = row - rowb, pos = axis ? (t & 63) : (t >> 6); const f32x4* tp = (const f32x4*)(rope + (size_t)(pos * NQ + j0) * 2);
; #pragma unroll
;                     for (int q = 0; q < 4; ++q) { const f32x4 cs = tp[q];
; #pragma unroll
;                         for (int hh = 0; hh < 2; ++hh) { const int e = 2 * q + hh; const float c = hh ? cs[2] : cs[0], s = hh ? cs[3] : cs[1];
;                             const float x1 = acc[ai][0][m][e >> 2][e & 3], x2 = acc[ai][1][m][e >> 2][e & 3];
;                             y1[e] = (x1 * c - x2 * s) * sc; y2[e] = (x2 * c + x1 * s) * sc; } }
;                 } else {
; #pragma unroll
;                     for (int e = 0; e < 8; ++e) { y1[e] = acc[ai][0][m][e >> 2][e & 3] * sc; y2[e] = acc[ai][1][m][e >> 2][e & 3] * sc; }
;                 }
;                 bf16_t* rp = dst + (size_t)row * ld;
;                 *(u32x4*)(rp + c1) = pack8(y1); *(u32x4*)(rp + c1 + dx2) = pack8(y2);
.LBB0_377:
	v_ashrrev_i32_e32 v131, 31, v130
	v_readlane_b32 s14, v255, 3
	v_lshlrev_b64 v[130:131], 11, v[130:131]
	v_readlane_b32 s15, v255, 4
	v_cvt_pk_bf16_f32 v172, v142, v143
	v_cvt_pk_bf16_f32 v173, v168, v169
	v_lshl_add_u64 v[130:131], s[14:15], 0, v[130:131]
	v_cvt_pk_bf16_f32 v174, v170, v171
	v_cvt_pk_bf16_f32 v175, v140, v141
	v_lshl_add_u64 v[140:141], v[128:129], 1, v[130:131]
	v_cvt_pk_bf16_f32 v130, v132, v133
	v_cvt_pk_bf16_f32 v131, v134, v135
	v_cvt_pk_bf16_f32 v132, v136, v137
	v_cvt_pk_bf16_f32 v133, v138, v139
	flat_store_dwordx4 v[140:141], v[172:175]
	flat_store_dwordx4 v[140:141], v[130:133] offset:32
	s_and_b64 vcc, exec, s[12:13]
	s_mov_b64 s[14:15], -1
	v_add_u32_e32 v130, 0xa0, v166
	s_cbranch_vccnz .LBB0_379
	v_subrev_u32_e32 v131, s61, v130
	v_and_b32_e32 v132, 63, v130
	v_ashrrev_i32_e32 v131, 6, v131
	v_cndmask_b32_e64 v131, v132, v131, s[10:11]
	v_lshl_or_b32 v132, v131, 4, v159
	v_ashrrev_i32_e32 v133, 31, v132
	v_lshl_add_u64 v[140:141], v[132:133], 3, s[68:69]
	flat_load_dwordx4 v[132:135], v[140:141]
	flat_load_dwordx4 v[170:173], v[140:141] offset:48
	flat_load_dwordx4 v[208:211], v[140:141] offset:16
	flat_load_dwordx4 v[212:215], v[140:141] offset:32
	s_mov_b64 s[14:15], 0
	s_waitcnt vmcnt(0) lgkmcnt(0)
	v_mov_b32_e32 v142, v132
	v_mov_b32_e32 v143, v134
	v_mov_b32_e32 v134, v133
	v_pk_mul_f32 v[132:133], v[20:21], v[142:143]
	v_pk_mul_f32 v[168:169], v[20:21], v[134:135]
	v_pk_fma_f32 v[132:133], v[28:29], v[134:135], v[132:133]
	v_mov_b32_e32 v134, v208
	v_mov_b32_e32 v135, v209
	v_mov_b32_e32 v136, v210
	v_mov_b32_e32 v137, v211
	v_mul_f32_e32 v184, v26, v171
	v_mul_f32_e32 v182, v18, v171
	v_pk_fma_f32 v[142:143], v[28:29], v[142:143], v[168:169] neg_lo:[0,0,1] neg_hi:[0,0,1]
	s_waitcnt vmcnt(0) lgkmcnt(0)
	v_mov_b32_e32 v174, v134
	v_mov_b32_e32 v175, v136
	v_mov_b32_e32 v136, v135
	v_pk_mul_f32 v[134:135], v[22:23], v[174:175]
	v_pk_mul_f32 v[176:177], v[22:23], v[136:137]
	v_pk_fma_f32 v[134:135], v[30:31], v[136:137], v[134:135]
	v_mov_b32_e32 v136, v212
	v_mov_b32_e32 v137, v213
	v_mov_b32_e32 v138, v214
	v_mov_b32_e32 v139, v215
	v_mul_f32_e32 v140, v26, v170
	v_pk_fma_f32 v[168:169], v[30:31], v[174:175], v[176:177] neg_lo:[0,0,1] neg_hi:[0,0,1]
	v_mov_b32_e32 v174, v19
	v_mov_b32_e32 v175, v27
	s_waitcnt vmcnt(0) lgkmcnt(0)
	v_mov_b32_e32 v178, v136
	v_mov_b32_e32 v179, v138
	v_mov_b32_e32 v138, v137
	v_pk_mul_f32 v[136:137], v[16:17], v[178:179]
	v_pk_mul_f32 v[180:181], v[16:17], v[138:139]
	v_pk_fma_f32 v[136:137], v[24:25], v[138:139], v[136:137]
	v_mov_b32_e32 v138, v18
	v_mov_b32_e32 v139, v26
	v_pk_fma_f32 v[138:139], v[138:139], v[170:171], v[184:185] op_sel_hi:[1,1,0]
	v_mov_b32_e32 v170, v27
	v_mov_b32_e32 v171, v19
	v_pk_mul_f32 v[170:171], v[170:171], v[172:173]
	v_pk_mul_f32 v[172:173], v[174:175], v[172:173]
	v_mov_b32_e32 v141, v170
	v_mov_b32_e32 v183, v171
	v_pk_fma_f32 v[170:171], v[24:25], v[178:179], v[180:181] neg_lo:[0,0,1] neg_hi:[0,0,1]
	v_pk_add_f32 v[140:141], v[140:141], v[182:183] neg_lo:[0,1] neg_hi:[0,1]
	v_add_f32_e32 v139, v173, v172

; __device__ __forceinline__ u32x4 pack8(const float* v) { u32x4 w; w.x = cvt_pk_bf16(v[0], v[1]); w.y = cvt_pk_bf16(v[2], v[3]); w.z = cvt_pk_bf16(v[4], v[5]); w.w = cvt_pk_bf16(v[6], v[7]); return w; }
;     template <int NQ> __device__ __forceinline__ void roped(const float* rope, const f32x4 (&acc)[2][2][4][2], int row0, bool is_ctx, int rowb  , int axis, int j0,
;                                                              bf16_t* dst, int ld, int c1, int dx2, float sc, int cz  ) const {
;     ...
;                 if (!is_ctx) { const int t = row - rowb, pos = axis ? (t & 63) : (t >> 6); const f32x4* tp = (const f32x4*)(rope + (size_t)(pos * NQ + j0) * 2);
; #pragma unroll
;                     for (int q = 0; q < 4; ++q) { const f32x4 cs = tp[q];
; #pragma unroll
;                         for (int hh = 0; hh < 2; ++hh) { const int e = 2 * q + hh; const float c = hh ? cs[2] : cs[0], s = hh ? cs[3] : cs[1];
;                             const float x1 = acc[ai][0][m][e >> 2][e & 3], x2 = acc[ai][1][m][e >> 2][e & 3];
;                             y1[e] = (x1 * c - x2 * s) * sc; y2[e] = (x2 * c + x1 * s) * sc; } }
;                 } else {
; #pragma unroll
;                     for (int e = 0; e < 8; ++e) { y1[e] = acc[ai][0][m][e >> 2][e & 3] * sc; y2[e] = acc[ai][1][m][e >> 2][e & 3] * sc; }
;                 }
;                 bf16_t* rp = dst + (size_t)row * ld;
;                 *(u32x4*)(rp + c1) = pack8(y1); *(u32x4*)(rp + c1 + dx2) = pack8(y2);
.LBB0_381:
	v_ashrrev_i32_e32 v131, 31, v130
	v_readlane_b32 s14, v255, 3
	v_lshlrev_b64 v[130:131], 11, v[130:131]
	v_readlane_b32 s15, v255, 4
	v_cvt_pk_bf16_f32 v172, v142, v143
	v_cvt_pk_bf16_f32 v173, v168, v169
	v_lshl_add_u64 v[130:131], s[14:15], 0, v[130:131]
	v_cvt_pk_bf16_f32 v174, v170, v171
	v_cvt_pk_bf16_f32 v175, v140, v141
	v_lshl_add_u64 v[140:141], v[128:129], 1, v[130:131]
	v_cvt_pk_bf16_f32 v130, v132, v133
	v_cvt_pk_bf16_f32 v131, v134, v135
	v_cvt_pk_bf16_f32 v132, v136, v137
	v_cvt_pk_bf16_f32 v133, v138, v139
	flat_store_dwordx4 v[140:141], v[172:175]
	flat_store_dwordx4 v[140:141], v[130:133] offset:32
	s_and_b64 vcc, exec, s[12:13]
	s_mov_b64 s[12:13], -1
	v_add_u32_e32 v130, 0xb0, v166
	s_cbranch_vccnz .LBB0_383
	v_subrev_u32_e32 v131, s61, v130
	v_and_b32_e32 v132, 63, v130
	v_ashrrev_i32_e32 v131, 6, v131
	v_cndmask_b32_e64 v131, v132, v131, s[10:11]
	v_lshl_or_b32 v132, v131, 4, v159
	v_ashrrev_i32_e32 v133, 31, v132
	v_lshl_add_u64 v[140:141], v[132:133], 3, s[68:69]
	flat_load_dwordx4 v[132:135], v[140:141]
	flat_load_dwordx4 v[170:173], v[140:141] offset:48
	flat_load_dwordx4 v[208:211], v[140:141] offset:16
	flat_load_dwordx4 v[212:215], v[140:141] offset:32
	s_mov_b64 s[12:13], 0
	s_waitcnt vmcnt(0) lgkmcnt(0)
	v_mov_b32_e32 v142, v132
	v_mov_b32_e32 v143, v134
	v_mov_b32_e32 v134, v133
	v_pk_mul_f32 v[132:133], v[4:5], v[142:143]
	v_pk_mul_f32 v[168:169], v[4:5], v[134:135]
	v_pk_fma_f32 v[132:133], v[12:13], v[134:135], v[132:133]
	v_mov_b32_e32 v134, v208
	v_mov_b32_e32 v135, v209
	v_mov_b32_e32 v136, v210
	v_mov_b32_e32 v137, v211
	v_mul_f32_e32 v184, v10, v171
	v_mul_f32_e32 v182, v2, v171
	v_pk_fma_f32 v[142:143], v[12:13], v[142:143], v[168:169] neg_lo:[0,0,1] neg_hi:[0,0,1]
	s_waitcnt vmcnt(0) lgkmcnt(0)
	v_mov_b32_e32 v174, v134
	v_mov_b32_e32 v175, v136
	v_mov_b32_e32 v136, v135
	v_pk_mul_f32 v[134:135], v[6:7], v[174:175]
	v_pk_mul_f32 v[176:177], v[6:7], v[136:137]
	v_pk_fma_f32 v[134:135], v[14:15], v[136:137], v[134:135]
	v_mov_b32_e32 v136, v212
	v_mov_b32_e32 v137, v213
	v_mov_b32_e32 v138, v214
	v_mov_b32_e32 v139, v215
	v_mul_f32_e32 v140, v10, v170
	v_pk_fma_f32 v[168:169], v[14:15], v[174:175], v[176:177] neg_lo:[0,0,1] neg_hi:[0,0,1]
	v_mov_b32_e32 v174, v3
	v_mov_b32_e32 v175, v11
	s_waitcnt vmcnt(0) lgkmcnt(0)
	v_mov_b32_e32 v178, v136
	v_mov_b32_e32 v179, v138
	v_mov_b32_e32 v138, v137
	v_pk_mul_f32 v[136:137], v[0:1], v[178:179]
	v_pk_mul_f32 v[180:181], v[0:1], v[138:139]
	v_pk_fma_f32 v[136:137], v[8:9], v[138:139], v[136:137]
	v_mov_b32_e32 v138, v2
	v_mov_b32_e32 v139, v10
	v_pk_fma_f32 v[138:139], v[138:139], v[170:171], v[184:185] op_sel_hi:[1,1,0]
	v_mov_b32_e32 v170, v11
	v_mov_b32_e32 v171, v3
	v_pk_mul_f32 v[170:171], v[170:171], v[172:173]
	v_pk_mul_f32 v[172:173], v[174:175], v[172:173]
	v_mov_b32_e32 v141, v170
	v_mov_b32_e32 v183, v171
	v_pk_fma_f32 v[170:171], v[8:9], v[178:179], v[180:181] neg_lo:[0,0,1] neg_hi:[0,0,1]
	v_pk_add_f32 v[140:141], v[140:141], v[182:183] neg_lo:[0,1] neg_hi:[0,1]
	v_add_f32_e32 v139, v173, v172

;     template <int NQ> __device__ __forceinline__ void roped(const float* rope, const f32x4 (&acc)[2][2][4][2], int row0, bool is_ctx, int rowb  , int axis, int j0,
;                                                              bf16_t* dst, int ld, int c1, int dx2, float sc, int cz  ) const {
;     ...
;                 if (!is_ctx) { const int t = row - rowb, pos = axis ? (t & 63) : (t >> 6); const f32x4* tp = (const f32x4*)(rope + (size_t)(pos * NQ + j0) * 2);
; #pragma unroll
;                     for (int q = 0; q < 4; ++q) { const f32x4 cs = tp[q];
; #pragma unroll
;                         for (int hh = 0; hh < 2; ++hh) { const int e = 2 * q + hh; const float c = hh ? cs[2] : cs[0], s = hh ? cs[3] : cs[1];
;                             const float x1 = acc[ai][0][m][e >> 2][e & 3], x2 = acc[ai][1][m][e >> 2][e & 3];
;                             y1[e] = (x1 * c - x2 * s) * sc; y2[e] = (x2 * c + x1 * s) * sc; } }
;     __device__ __forceinline__ void operator()(const f32x4 (&acc)[2][2][4][2], const Unit& u, int wr, int wc, int fr, int fq) const {
;     ...
;                 if (u.pn < 4) { const int ug = u.pn * 4 + wc; roped<16>(rope, acc, row0, is_ctx, rowb, axis, j0, (bf16_t*)BIG, 2048, ug * 128 + (ug & 1) * 64 + axis * 32 + j0, 16, 0.125f, ug * 128 + ((ug & 1) ^ 1) * 64 + axis * 32 + j0); }
.LBB0_386:
	s_and_b64 vcc, exec, s[12:13]
	s_cbranch_vccz .LBB0_436
	v_cmp_gt_u32_e64 s[12:13], 2, v204
	s_mov_b64 s[10:11], -1
	s_and_b64 vcc, exec, s[56:57]
	v_and_b32_e32 v170, 63, v205
	s_cbranch_vccz .LBB0_389
	v_subrev_u32_e32 v128, s61, v166
	v_ashrrev_i32_e32 v128, 6, v128
	v_cndmask_b32_e64 v128, v170, v128, s[12:13]
	v_lshl_or_b32 v128, v128, 4, v159
	v_ashrrev_i32_e32 v129, 31, v128
	v_lshl_add_u64 v[138:139], v[128:129], 3, s[68:69]
	flat_load_dwordx4 v[128:131], v[138:139]
	flat_load_dwordx4 v[172:175], v[138:139] offset:48
	flat_load_dwordx4 v[208:211], v[138:139] offset:16
	flat_load_dwordx4 v[212:215], v[138:139] offset:32
	s_mov_b64 s[10:11], 0
	s_waitcnt vmcnt(0) lgkmcnt(0)
	v_mov_b32_e32 v140, v128
	v_mov_b32_e32 v141, v130
	v_mov_b32_e32 v130, v129
	v_pk_mul_f32 v[132:133], v[116:117], v[140:141]
	v_pk_mul_f32 v[128:129], v[116:117], v[130:131]
	v_pk_fma_f32 v[130:131], v[124:125], v[130:131], v[132:133]
	v_mov_b32_e32 v132, v208
	v_mov_b32_e32 v133, v209
	v_mov_b32_e32 v134, v210
	v_mov_b32_e32 v135, v211
	v_mul_f32_e32 v182, v122, v172
	v_mul_f32_e32 v184, v114, v173
	v_pk_mul_f32 v[130:131], v[130:131], s[78:79] op_sel_hi:[1,0]
	s_waitcnt vmcnt(0) lgkmcnt(0)
	v_mov_b32_e32 v142, v132
	v_mov_b32_e32 v143, v134
	v_mov_b32_e32 v134, v133
	v_pk_mul_f32 v[132:133], v[118:119], v[142:143]
	v_pk_mul_f32 v[176:177], v[118:119], v[134:135]
	v_pk_fma_f32 v[132:133], v[126:127], v[134:135], v[132:133]
	v_mov_b32_e32 v134, v212
	v_mov_b32_e32 v135, v213
	v_mov_b32_e32 v136, v214
	v_mov_b32_e32 v137, v215
	v_pk_mul_f32 v[132:133], v[132:133], s[78:79] op_sel_hi:[1,0]
	v_pk_fma_f32 v[138:139], v[126:127], v[142:143], v[176:177] neg_lo:[0,0,1] neg_hi:[0,0,1]
	s_waitcnt vmcnt(0) lgkmcnt(0)
	v_mov_b32_e32 v178, v134
	v_mov_b32_e32 v179, v136
	v_mov_b32_e32 v136, v135
	v_pk_mul_f32 v[134:135], v[112:113], v[178:179]
	v_pk_mul_f32 v[180:181], v[112:113], v[136:137]
	v_pk_fma_f32 v[134:135], v[120:121], v[136:137], v[134:135]
	v_mov_b32_e32 v136, v114
	v_mov_b32_e32 v137, v122
	v_pk_mul_f32 v[136:137], v[136:137], v[172:173]
	v_pk_mul_f32 v[134:135], v[134:135], s[78:79] op_sel_hi:[1,0]
	v_add_f32_e32 v136, v137, v136
	v_mul_f32_e32 v168, 0x3e000000, v136
	v_mov_b32_e32 v136, v123
	v_mov_b32_e32 v137, v115
	v_pk_mul_f32 v[136:137], v[136:137], v[174:175]
	s_nop 0
	v_mov_b32_e32 v183, v136
	v_mov_b32_e32 v185, v137
	v_pk_fma_f32 v[136:137], v[124:125], v[140:141], v[128:129] neg_lo:[0,0,1] neg_hi:[0,0,1]
	v_mov_b32_e32 v128, v115
	v_mov_b32_e32 v129, v123
	v_pk_mul_f32 v[128:129], v[128:129], v[174:175]
	v_pk_fma_f32 v[140:141], v[120:121], v[178:179], v[180:181] neg_lo:[0,0,1] neg_hi:[0,0,1]
	v_pk_add_f32 v[142:143], v[182:183], v[184:185] neg_lo:[0,1] neg_hi:[0,1]
	v_add_f32_e32 v167, v129, v128

; __device__ __forceinline__ u32x4 pack8(const float* v) { u32x4 w; w.x = cvt_pk_bf16(v[0], v[1]); w.y = cvt_pk_bf16(v[2], v[3]); w.z = cvt_pk_bf16(v[4], v[5]); w.w = cvt_pk_bf16(v[6], v[7]); return w; }
;     template <int NQ> __device__ __forceinline__ void roped(const float* rope, const f32x4 (&acc)[2][2][4][2], int row0, bool is_ctx, int rowb  , int axis, int j0,
;                                                              bf16_t* dst, int ld, int c1, int dx2, float sc, int cz  ) const {
;     ...
;                 if (!is_ctx) { const int t = row - rowb, pos = axis ? (t & 63) : (t >> 6); const f32x4* tp = (const f32x4*)(rope + (size_t)(pos * NQ + j0) * 2);
; #pragma unroll
;                     for (int q = 0; q < 4; ++q) { const f32x4 cs = tp[q];
; #pragma unroll
;                         for (int hh = 0; hh < 2; ++hh) { const int e = 2 * q + hh; const float c = hh ? cs[2] : cs[0], s = hh ? cs[3] : cs[1];
;                             const float x1 = acc[ai][0][m][e >> 2][e & 3], x2 = acc[ai][1][m][e >> 2][e & 3];
;                             y1[e] = (x1 * c - x2 * s) * sc; y2[e] = (x2 * c + x1 * s) * sc; } }
;                 } else {
; #pragma unroll
;                     for (int e = 0; e < 8; ++e) { y1[e] = acc[ai][0][m][e >> 2][e & 3] * sc; y2[e] = acc[ai][1][m][e >> 2][e & 3] * sc; }
;                 }
;                 bf16_t* rp = dst + (size_t)row * ld;
;                 *(u32x4*)(rp + c1) = pack8(y1); *(u32x4*)(rp + c1 + dx2) = pack8(y2);
;                 if (cz >= 0) { const u32x4 z = {0u, 0u, 0u, 0u}; *(u32x4*)(rp + cz) = z; *(u32x4*)(rp + cz + dx2) = z; }
.LBB0_393:
	s_or_b64 exec, exec, s[14:15]
	v_cndmask_b32_e64 v131, 0, 1, s[56:57]
	v_add_u32_e32 v130, 16, v166
	v_cmp_ne_u32_e64 s[14:15], 1, v131
	s_andn2_b64 vcc, exec, s[56:57]
	s_mov_b64 s[38:39], -1
	s_cbranch_vccnz .LBB0_395
	v_subrev_u32_e32 v131, s61, v130
	v_and_b32_e32 v132, 63, v130
	v_ashrrev_i32_e32 v131, 6, v131
	v_cndmask_b32_e64 v131, v132, v131, s[12:13]
	v_lshl_or_b32 v132, v131, 4, v159
	v_ashrrev_i32_e32 v133, 31, v132
	v_lshl_add_u64 v[140:141], v[132:133], 3, s[68:69]
	flat_load_dwordx4 v[132:135], v[140:141]
	flat_load_dwordx4 v[172:175], v[140:141] offset:48
	flat_load_dwordx4 v[208:211], v[140:141] offset:16
	flat_load_dwordx4 v[212:215], v[140:141] offset:32
	s_mov_b64 s[38:39], 0
	s_waitcnt vmcnt(0) lgkmcnt(0)
	v_mov_b32_e32 v142, v132
	v_mov_b32_e32 v143, v134
	v_mov_b32_e32 v134, v133
	v_pk_mul_f32 v[132:133], v[100:101], v[142:143]
	v_pk_mul_f32 v[168:169], v[100:101], v[134:135]
	v_pk_fma_f32 v[132:133], v[108:109], v[134:135], v[132:133]
	v_mov_b32_e32 v134, v208
	v_mov_b32_e32 v135, v209
	v_mov_b32_e32 v136, v210
	v_mov_b32_e32 v137, v211
	v_mul_f32_e32 v184, v106, v172
	v_mul_f32_e32 v206, v98, v173
	v_pk_mul_f32 v[132:133], v[132:133], s[78:79] op_sel_hi:[1,0]
	s_waitcnt vmcnt(0) lgkmcnt(0)
	v_mov_b32_e32 v176, v134
	v_mov_b32_e32 v177, v136
	v_mov_b32_e32 v136, v135
	v_pk_mul_f32 v[134:135], v[102:103], v[176:177]
	v_pk_mul_f32 v[178:179], v[102:103], v[136:137]
	v_pk_fma_f32 v[134:135], v[110:111], v[136:137], v[134:135]
	v_mov_b32_e32 v136, v212
	v_mov_b32_e32 v137, v213
	v_mov_b32_e32 v138, v214
	v_mov_b32_e32 v139, v215
	v_pk_mul_f32 v[134:135], v[134:135], s[78:79] op_sel_hi:[1,0]
	v_pk_fma_f32 v[140:141], v[110:111], v[176:177], v[178:179] neg_lo:[0,0,1] neg_hi:[0,0,1]
	s_waitcnt vmcnt(0) lgkmcnt(0)
	v_mov_b32_e32 v180, v136
	v_mov_b32_e32 v181, v138
	v_mov_b32_e32 v138, v137
	v_pk_mul_f32 v[136:137], v[96:97], v[180:181]
	v_pk_mul_f32 v[182:183], v[96:97], v[138:139]
	v_pk_fma_f32 v[136:137], v[104:105], v[138:139], v[136:137]
	v_mov_b32_e32 v138, v98
	v_mov_b32_e32 v139, v106
	v_pk_mul_f32 v[138:139], v[138:139], v[172:173]
	v_mov_b32_e32 v172, v99
	v_add_f32_e32 v131, v139, v138
	v_mov_b32_e32 v138, v107
	v_mov_b32_e32 v139, v99
	v_pk_mul_f32 v[138:139], v[138:139], v[174:175]
	v_mov_b32_e32 v173, v107
	v_mov_b32_e32 v185, v138
	v_mov_b32_e32 v207, v139
	v_pk_mul_f32 v[172:173], v[172:173], v[174:175]
	v_pk_mul_f32 v[136:137], v[136:137], s[78:79] op_sel_hi:[1,0]
	v_mul_f32_e32 v167, 0x3e000000, v131
	v_pk_fma_f32 v[138:139], v[108:109], v[142:143], v[168:169] neg_lo:[0,0,1] neg_hi:[0,0,1]
	v_pk_fma_f32 v[142:143], v[104:105], v[180:181], v[182:183] neg_lo:[0,0,1] neg_hi:[0,0,1]
	v_pk_add_f32 v[168:169], v[184:185], v[206:207] neg_lo:[0,1] neg_hi:[0,1]
	v_add_f32_e32 v131, v173, v172

; __device__ __forceinline__ u32x4 pack8(const float* v) { u32x4 w; w.x = cvt_pk_bf16(v[0], v[1]); w.y = cvt_pk_bf16(v[2], v[3]); w.z = cvt_pk_bf16(v[4], v[5]); w.w = cvt_pk_bf16(v[6], v[7]); return w; }
;     template <int NQ> __device__ __forceinline__ void roped(const float* rope, const f32x4 (&acc)[2][2][4][2], int row0, bool is_ctx, int rowb  , int axis, int j0,
;                                                              bf16_t* dst, int ld, int c1, int dx2, float sc, int cz  ) const {
;     ...
;                 if (!is_ctx) { const int t = row - rowb, pos = axis ? (t & 63) : (t >> 6); const f32x4* tp = (const f32x4*)(rope + (size_t)(pos * NQ + j0) * 2);
; #pragma unroll
;                     for (int q = 0; q < 4; ++q) { const f32x4 cs = tp[q];
; #pragma unroll
;                         for (int hh = 0; hh < 2; ++hh) { const int e = 2 * q + hh; const float c = hh ? cs[2] : cs[0], s = hh ? cs[3] : cs[1];
;                             const float x1 = acc[ai][0][m][e >> 2][e & 3], x2 = acc[ai][1][m][e >> 2][e & 3];
;                             y1[e] = (x1 * c - x2 * s) * sc; y2[e] = (x2 * c + x1 * s) * sc; } }
;                 } else {
; #pragma unroll
;                     for (int e = 0; e < 8; ++e) { y1[e] = acc[ai][0][m][e >> 2][e & 3] * sc; y2[e] = acc[ai][1][m][e >> 2][e & 3] * sc; }
;                 }
;                 bf16_t* rp = dst + (size_t)row * ld;
;                 *(u32x4*)(rp + c1) = pack8(y1); *(u32x4*)(rp + c1 + dx2) = pack8(y2);
;                 if (cz >= 0) { const u32x4 z = {0u, 0u, 0u, 0u}; *(u32x4*)(rp + cz) = z; *(u32x4*)(rp + cz + dx2) = z; }
.LBB0_399:
	s_or_b64 exec, exec, s[56:57]
	v_add_u32_e32 v130, 32, v166
	s_and_b64 vcc, exec, s[14:15]
	s_mov_b64 s[38:39], -1
	s_cbranch_vccnz .LBB0_401
	v_subrev_u32_e32 v131, s61, v130
	v_and_b32_e32 v132, 63, v130
	v_ashrrev_i32_e32 v131, 6, v131
	v_cndmask_b32_e64 v131, v132, v131, s[12:13]
	v_lshl_or_b32 v132, v131, 4, v159
	v_ashrrev_i32_e32 v133, 31, v132
	v_lshl_add_u64 v[140:141], v[132:133], 3, s[68:69]
	flat_load_dwordx4 v[132:135], v[140:141]
	flat_load_dwordx4 v[172:175], v[140:141] offset:48
	flat_load_dwordx4 v[208:211], v[140:141] offset:16
	flat_load_dwordx4 v[212:215], v[140:141] offset:32
	s_mov_b64 s[38:39], 0
	s_waitcnt vmcnt(0) lgkmcnt(0)
	v_mov_b32_e32 v142, v132
	v_mov_b32_e32 v143, v134
	v_mov_b32_e32 v134, v133
	v_pk_mul_f32 v[132:133], v[84:85], v[142:143]
	v_pk_mul_f32 v[168:169], v[84:85], v[134:135]
	v_pk_fma_f32 v[132:133], v[92:93], v[134:135], v[132:133]
	v_mov_b32_e32 v134, v208
	v_mov_b32_e32 v135, v209
	v_mov_b32_e32 v136, v210
	v_mov_b32_e32 v137, v211
	v_mul_f32_e32 v184, v90, v172
	v_mul_f32_e32 v206, v82, v173
	v_pk_mul_f32 v[132:133], v[132:133], s[78:79] op_sel_hi:[1,0]
	s_waitcnt vmcnt(0) lgkmcnt(0)
	v_mov_b32_e32 v176, v134
	v_mov_b32_e32 v177, v136
	v_mov_b32_e32 v136, v135
	v_pk_mul_f32 v[134:135], v[86:87], v[176:177]
	v_pk_mul_f32 v[178:179], v[86:87], v[136:137]
	v_pk_fma_f32 v[134:135], v[94:95], v[136:137], v[134:135]
	v_mov_b32_e32 v136, v212
	v_mov_b32_e32 v137, v213
	v_mov_b32_e32 v138, v214
	v_mov_b32_e32 v139, v215
	v_pk_mul_f32 v[134:135], v[134:135], s[78:79] op_sel_hi:[1,0]
	v_pk_fma_f32 v[140:141], v[94:95], v[176:177], v[178:179] neg_lo:[0,0,1] neg_hi:[0,0,1]
	s_waitcnt vmcnt(0) lgkmcnt(0)
	v_mov_b32_e32 v180, v136
	v_mov_b32_e32 v181, v138
	v_mov_b32_e32 v138, v137
	v_pk_mul_f32 v[136:137], v[80:81], v[180:181]
	v_pk_mul_f32 v[182:183], v[80:81], v[138:139]
	v_pk_fma_f32 v[136:137], v[88:89], v[138:139], v[136:137]
	v_mov_b32_e32 v138, v82
	v_mov_b32_e32 v139, v90
	v_pk_mul_f32 v[138:139], v[138:139], v[172:173]
	v_mov_b32_e32 v172, v83
	v_add_f32_e32 v131, v139, v138
	v_mov_b32_e32 v138, v91
	v_mov_b32_e32 v139, v83
	v_pk_mul_f32 v[138:139], v[138:139], v[174:175]
	v_mov_b32_e32 v173, v91
	v_mov_b32_e32 v185, v138
	v_mov_b32_e32 v207, v139
	v_pk_mul_f32 v[172:173], v[172:173], v[174:175]
	v_pk_mul_f32 v[136:137], v[136:137], s[78:79] op_sel_hi:[1,0]
	v_mul_f32_e32 v167, 0x3e000000, v131
	v_pk_fma_f32 v[138:139], v[92:93], v[142:143], v[168:169] neg_lo:[0,0,1] neg_hi:[0,0,1]
	v_pk_fma_f32 v[142:143], v[88:89], v[180:181], v[182:183] neg_lo:[0,0,1] neg_hi:[0,0,1]
	v_pk_add_f32 v[168:169], v[184:185], v[206:207] neg_lo:[0,1] neg_hi:[0,1]
	v_add_f32_e32 v131, v173, v172

; __device__ __forceinline__ u32x4 pack8(const float* v) { u32x4 w; w.x = cvt_pk_bf16(v[0], v[1]); w.y = cvt_pk_bf16(v[2], v[3]); w.z = cvt_pk_bf16(v[4], v[5]); w.w = cvt_pk_bf16(v[6], v[7]); return w; }
;     template <int NQ> __device__ __forceinline__ void roped(const float* rope, const f32x4 (&acc)[2][2][4][2], int row0, bool is_ctx, int rowb  , int axis, int j0,
;                                                              bf16_t* dst, int ld, int c1, int dx2, float sc, int cz  ) const {
;     ...
;                 if (!is_ctx) { const int t = row - rowb, pos = axis ? (t & 63) : (t >> 6); const f32x4* tp = (const f32x4*)(rope + (size_t)(pos * NQ + j0) * 2);
; #pragma unroll
;                     for (int q = 0; q < 4; ++q) { const f32x4 cs = tp[q];
; #pragma unroll
;                         for (int hh = 0; hh < 2; ++hh) { const int e = 2 * q + hh; const float c = hh ? cs[2] : cs[0], s = hh ? cs[3] : cs[1];
;                             const float x1 = acc[ai][0][m][e >> 2][e & 3], x2 = acc[ai][1][m][e >> 2][e & 3];
;                             y1[e] = (x1 * c - x2 * s) * sc; y2[e] = (x2 * c + x1 * s) * sc; } }
;                 } else {
; #pragma unroll
;                     for (int e = 0; e < 8; ++e) { y1[e] = acc[ai][0][m][e >> 2][e & 3] * sc; y2[e] = acc[ai][1][m][e >> 2][e & 3] * sc; }
;                 }
;                 bf16_t* rp = dst + (size_t)row * ld;
;                 *(u32x4*)(rp + c1) = pack8(y1); *(u32x4*)(rp + c1 + dx2) = pack8(y2);
;                 if (cz >= 0) { const u32x4 z = {0u, 0u, 0u, 0u}; *(u32x4*)(rp + cz) = z; *(u32x4*)(rp + cz + dx2) = z; }
.LBB0_405:
	s_or_b64 exec, exec, s[56:57]
	v_add_u32_e32 v130, 48, v166
	s_and_b64 vcc, exec, s[14:15]
	s_mov_b64 s[38:39], -1
	s_cbranch_vccnz .LBB0_407
	v_subrev_u32_e32 v131, s61, v130
	v_and_b32_e32 v132, 63, v130
	v_ashrrev_i32_e32 v131, 6, v131
	v_cndmask_b32_e64 v131, v132, v131, s[12:13]
	v_lshl_or_b32 v132, v131, 4, v159
	v_ashrrev_i32_e32 v133, 31, v132
	v_lshl_add_u64 v[140:141], v[132:133], 3, s[68:69]
	flat_load_dwordx4 v[132:135], v[140:141]
	flat_load_dwordx4 v[172:175], v[140:141] offset:48
	flat_load_dwordx4 v[208:211], v[140:141] offset:16
	flat_load_dwordx4 v[212:215], v[140:141] offset:32
	s_mov_b64 s[38:39], 0
	s_waitcnt vmcnt(0) lgkmcnt(0)
	v_mov_b32_e32 v142, v132
	v_mov_b32_e32 v143, v134
	v_mov_b32_e32 v134, v133
	v_pk_mul_f32 v[132:133], v[68:69], v[142:143]
	v_pk_mul_f32 v[168:169], v[68:69], v[134:135]
	v_pk_fma_f32 v[132:133], v[76:77], v[134:135], v[132:133]
	v_mov_b32_e32 v134, v208
	v_mov_b32_e32 v135, v209
	v_mov_b32_e32 v136, v210
	v_mov_b32_e32 v137, v211
	v_mul_f32_e32 v184, v74, v172
	v_mul_f32_e32 v206, v66, v173
	v_pk_mul_f32 v[132:133], v[132:133], s[78:79] op_sel_hi:[1,0]
	s_waitcnt vmcnt(0) lgkmcnt(0)
	v_mov_b32_e32 v176, v134
	v_mov_b32_e32 v177, v136
	v_mov_b32_e32 v136, v135
	v_pk_mul_f32 v[134:135], v[70:71], v[176:177]
	v_pk_mul_f32 v[178:179], v[70:71], v[136:137]
	v_pk_fma_f32 v[134:135], v[78:79], v[136:137], v[134:135]
	v_mov_b32_e32 v136, v212
	v_mov_b32_e32 v137, v213
	v_mov_b32_e32 v138, v214
	v_mov_b32_e32 v139, v215
	v_pk_mul_f32 v[134:135], v[134:135], s[78:79] op_sel_hi:[1,0]
	v_pk_fma_f32 v[140:141], v[78:79], v[176:177], v[178:179] neg_lo:[0,0,1] neg_hi:[0,0,1]
	s_waitcnt vmcnt(0) lgkmcnt(0)
	v_mov_b32_e32 v180, v136
	v_mov_b32_e32 v181, v138
	v_mov_b32_e32 v138, v137
	v_pk_mul_f32 v[136:137], v[64:65], v[180:181]
	v_pk_mul_f32 v[182:183], v[64:65], v[138:139]
	v_pk_fma_f32 v[136:137], v[72:73], v[138:139], v[136:137]
	v_mov_b32_e32 v138, v66
	v_mov_b32_e32 v139, v74
	v_pk_mul_f32 v[138:139], v[138:139], v[172:173]
	v_mov_b32_e32 v172, v67
	v_add_f32_e32 v131, v139, v138
	v_mov_b32_e32 v138, v75
	v_mov_b32_e32 v139, v67
	v_pk_mul_f32 v[138:139], v[138:139], v[174:175]
	v_mov_b32_e32 v173, v75
	v_mov_b32_e32 v185, v138
	v_mov_b32_e32 v207, v139
	v_pk_mul_f32 v[172:173], v[172:173], v[174:175]
	v_pk_mul_f32 v[136:137], v[136:137], s[78:79] op_sel_hi:[1,0]
	v_mul_f32_e32 v167, 0x3e000000, v131
	v_pk_fma_f32 v[138:139], v[76:77], v[142:143], v[168:169] neg_lo:[0,0,1] neg_hi:[0,0,1]
	v_pk_fma_f32 v[142:143], v[72:73], v[180:181], v[182:183] neg_lo:[0,0,1] neg_hi:[0,0,1]
	v_pk_add_f32 v[168:169], v[184:185], v[206:207] neg_lo:[0,1] neg_hi:[0,1]
	v_add_f32_e32 v131, v173, v172

; __device__ __forceinline__ u32x4 pack8(const float* v) { u32x4 w; w.x = cvt_pk_bf16(v[0], v[1]); w.y = cvt_pk_bf16(v[2], v[3]); w.z = cvt_pk_bf16(v[4], v[5]); w.w = cvt_pk_bf16(v[6], v[7]); return w; }
;     template <int NQ> __device__ __forceinline__ void roped(const float* rope, const f32x4 (&acc)[2][2][4][2], int row0, bool is_ctx, int rowb  , int axis, int j0,
;                                                              bf16_t* dst, int ld, int c1, int dx2, float sc, int cz  ) const {
;     ...
;                 if (!is_ctx) { const int t = row - rowb, pos = axis ? (t & 63) : (t >> 6); const f32x4* tp = (const f32x4*)(rope + (size_t)(pos * NQ + j0) * 2);
; #pragma unroll
;                     for (int q = 0; q < 4; ++q) { const f32x4 cs = tp[q];
; #pragma unroll
;                         for (int hh = 0; hh < 2; ++hh) { const int e = 2 * q + hh; const float c = hh ? cs[2] : cs[0], s = hh ? cs[3] : cs[1];
;                             const float x1 = acc[ai][0][m][e >> 2][e & 3], x2 = acc[ai][1][m][e >> 2][e & 3];
;                             y1[e] = (x1 * c - x2 * s) * sc; y2[e] = (x2 * c + x1 * s) * sc; } }
;                 } else {
; #pragma unroll
;                     for (int e = 0; e < 8; ++e) { y1[e] = acc[ai][0][m][e >> 2][e & 3] * sc; y2[e] = acc[ai][1][m][e >> 2][e & 3] * sc; }
;                 }
;                 bf16_t* rp = dst + (size_t)row * ld;
;                 *(u32x4*)(rp + c1) = pack8(y1); *(u32x4*)(rp + c1 + dx2) = pack8(y2);
;                 if (cz >= 0) { const u32x4 z = {0u, 0u, 0u, 0u}; *(u32x4*)(rp + cz) = z; *(u32x4*)(rp + cz + dx2) = z; }
.LBB0_411:
	s_or_b64 exec, exec, s[56:57]
	v_add_u32_e32 v130, 0x80, v166
	s_and_b64 vcc, exec, s[14:15]
	s_mov_b64 s[38:39], -1
	s_cbranch_vccnz .LBB0_413
	v_subrev_u32_e32 v131, s61, v130
	v_ashrrev_i32_e32 v131, 6, v131
	v_cndmask_b32_e64 v131, v170, v131, s[12:13]
	v_lshl_or_b32 v132, v131, 4, v159
	v_ashrrev_i32_e32 v133, 31, v132
	v_lshl_add_u64 v[140:141], v[132:133], 3, s[68:69]
	flat_load_dwordx4 v[132:135], v[140:141]
	flat_load_dwordx4 v[168:171], v[140:141] offset:48
	flat_load_dwordx4 v[208:211], v[140:141] offset:16
	flat_load_dwordx4 v[212:215], v[140:141] offset:32
	s_mov_b64 s[38:39], 0
	s_waitcnt vmcnt(0) lgkmcnt(0)
	v_mov_b32_e32 v142, v132
	v_mov_b32_e32 v143, v134
	v_mov_b32_e32 v134, v133
	v_pk_mul_f32 v[132:133], v[52:53], v[142:143]
	v_pk_mul_f32 v[172:173], v[52:53], v[134:135]
	v_pk_fma_f32 v[132:133], v[60:61], v[134:135], v[132:133]
	v_mov_b32_e32 v134, v208
	v_mov_b32_e32 v135, v209
	v_mov_b32_e32 v136, v210
	v_mov_b32_e32 v137, v211
	v_mul_f32_e32 v182, v58, v168
	v_mul_f32_e32 v184, v50, v169
	v_pk_mul_f32 v[132:133], v[132:133], s[78:79] op_sel_hi:[1,0]
	s_waitcnt vmcnt(0) lgkmcnt(0)
	v_mov_b32_e32 v174, v134
	v_mov_b32_e32 v175, v136
	v_mov_b32_e32 v136, v135
	v_pk_mul_f32 v[134:135], v[54:55], v[174:175]
	v_pk_mul_f32 v[176:177], v[54:55], v[136:137]
	v_pk_fma_f32 v[134:135], v[62:63], v[136:137], v[134:135]
	v_mov_b32_e32 v136, v212
	v_mov_b32_e32 v137, v213
	v_mov_b32_e32 v138, v214
	v_mov_b32_e32 v139, v215
	v_pk_mul_f32 v[134:135], v[134:135], s[78:79] op_sel_hi:[1,0]
	v_pk_fma_f32 v[140:141], v[62:63], v[174:175], v[176:177] neg_lo:[0,0,1] neg_hi:[0,0,1]
	s_waitcnt vmcnt(0) lgkmcnt(0)
	v_mov_b32_e32 v178, v136
	v_mov_b32_e32 v179, v138
	v_mov_b32_e32 v138, v137
	v_pk_mul_f32 v[136:137], v[48:49], v[178:179]
	v_pk_mul_f32 v[180:181], v[48:49], v[138:139]
	v_pk_fma_f32 v[136:137], v[56:57], v[138:139], v[136:137]
	v_mov_b32_e32 v138, v50
	v_mov_b32_e32 v139, v58
	v_pk_mul_f32 v[138:139], v[138:139], v[168:169]
	v_pk_mul_f32 v[136:137], v[136:137], s[78:79] op_sel_hi:[1,0]
	v_add_f32_e32 v131, v139, v138
	v_mov_b32_e32 v138, v59
	v_mov_b32_e32 v139, v51
	v_pk_mul_f32 v[138:139], v[138:139], v[170:171]
	v_mul_f32_e32 v167, 0x3e000000, v131
	v_mov_b32_e32 v183, v138
	v_mov_b32_e32 v185, v139
	v_pk_fma_f32 v[138:139], v[60:61], v[142:143], v[172:173] neg_lo:[0,0,1] neg_hi:[0,0,1]
	v_mov_b32_e32 v172, v51
	v_mov_b32_e32 v173, v59
	v_pk_mul_f32 v[170:171], v[172:173], v[170:171]
	v_pk_fma_f32 v[142:143], v[56:57], v[178:179], v[180:181] neg_lo:[0,0,1] neg_hi:[0,0,1]
	v_pk_add_f32 v[168:169], v[182:183], v[184:185] neg_lo:[0,1] neg_hi:[0,1]
	v_add_f32_e32 v131, v171, v170

; __device__ __forceinline__ u32x4 pack8(const float* v) { u32x4 w; w.x = cvt_pk_bf16(v[0], v[1]); w.y = cvt_pk_bf16(v[2], v[3]); w.z = cvt_pk_bf16(v[4], v[5]); w.w = cvt_pk_bf16(v[6], v[7]); return w; }
;     template <int NQ> __device__ __forceinline__ void roped(const float* rope, const f32x4 (&acc)[2][2][4][2], int row0, bool is_ctx, int rowb  , int axis, int j0,
;                                                              bf16_t* dst, int ld, int c1, int dx2, float sc, int cz  ) const {
;     ...
;                 if (!is_ctx) { const int t = row - rowb, pos = axis ? (t & 63) : (t >> 6); const f32x4* tp = (const f32x4*)(rope + (size_t)(pos * NQ + j0) * 2);
; #pragma unroll
;                     for (int q = 0; q < 4; ++q) { const f32x4 cs = tp[q];
; #pragma unroll
;                         for (int hh = 0; hh < 2; ++hh) { const int e = 2 * q + hh; const float c = hh ? cs[2] : cs[0], s = hh ? cs[3] : cs[1];
;                             const float x1 = acc[ai][0][m][e >> 2][e & 3], x2 = acc[ai][1][m][e >> 2][e & 3];
;                             y1[e] = (x1 * c - x2 * s) * sc; y2[e] = (x2 * c + x1 * s) * sc; } }
;                 } else {
; #pragma unroll
;                     for (int e = 0; e < 8; ++e) { y1[e] = acc[ai][0][m][e >> 2][e & 3] * sc; y2[e] = acc[ai][1][m][e >> 2][e & 3] * sc; }
;                 }
;                 bf16_t* rp = dst + (size_t)row * ld;
;                 *(u32x4*)(rp + c1) = pack8(y1); *(u32x4*)(rp + c1 + dx2) = pack8(y2);
;                 if (cz >= 0) { const u32x4 z = {0u, 0u, 0u, 0u}; *(u32x4*)(rp + cz) = z; *(u32x4*)(rp + cz + dx2) = z; }
.LBB0_417:
	s_or_b64 exec, exec, s[56:57]
	v_add_u32_e32 v130, 0x90, v166
	s_and_b64 vcc, exec, s[14:15]
	s_mov_b64 s[38:39], -1
	s_cbranch_vccnz .LBB0_419
	v_subrev_u32_e32 v131, s61, v130
	v_and_b32_e32 v132, 63, v130
	v_ashrrev_i32_e32 v131, 6, v131
	v_cndmask_b32_e64 v131, v132, v131, s[12:13]
	v_lshl_or_b32 v132, v131, 4, v159
	v_ashrrev_i32_e32 v133, 31, v132
	v_lshl_add_u64 v[140:141], v[132:133], 3, s[68:69]
	flat_load_dwordx4 v[132:135], v[140:141]
	flat_load_dwordx4 v[168:171], v[140:141] offset:48
	flat_load_dwordx4 v[208:211], v[140:141] offset:16
	flat_load_dwordx4 v[212:215], v[140:141] offset:32
	s_mov_b64 s[38:39], 0
	s_waitcnt vmcnt(0) lgkmcnt(0)
	v_mov_b32_e32 v142, v132
	v_mov_b32_e32 v143, v134
	v_mov_b32_e32 v134, v133
	v_pk_mul_f32 v[132:133], v[36:37], v[142:143]
	v_pk_mul_f32 v[172:173], v[36:37], v[134:135]
	v_pk_fma_f32 v[132:133], v[44:45], v[134:135], v[132:133]
	v_mov_b32_e32 v134, v208
	v_mov_b32_e32 v135, v209
	v_mov_b32_e32 v136, v210
	v_mov_b32_e32 v137, v211
	v_mul_f32_e32 v182, v42, v168
	v_mul_f32_e32 v184, v34, v169
	v_pk_mul_f32 v[132:133], v[132:133], s[78:79] op_sel_hi:[1,0]
	s_waitcnt vmcnt(0) lgkmcnt(0)
	v_mov_b32_e32 v174, v134
	v_mov_b32_e32 v175, v136
	v_mov_b32_e32 v136, v135
	v_pk_mul_f32 v[134:135], v[38:39], v[174:175]
	v_pk_mul_f32 v[176:177], v[38:39], v[136:137]
	v_pk_fma_f32 v[134:135], v[46:47], v[136:137], v[134:135]
	v_mov_b32_e32 v136, v212
	v_mov_b32_e32 v137, v213
	v_mov_b32_e32 v138, v214
	v_mov_b32_e32 v139, v215
	v_pk_mul_f32 v[134:135], v[134:135], s[78:79] op_sel_hi:[1,0]
	v_pk_fma_f32 v[140:141], v[46:47], v[174:175], v[176:177] neg_lo:[0,0,1] neg_hi:[0,0,1]
	s_waitcnt vmcnt(0) lgkmcnt(0)
	v_mov_b32_e32 v178, v136
	v_mov_b32_e32 v179, v138
	v_mov_b32_e32 v138, v137
	v_pk_mul_f32 v[136:137], v[32:33], v[178:179]
	v_pk_mul_f32 v[180:181], v[32:33], v[138:139]
	v_pk_fma_f32 v[136:137], v[40:41], v[138:139], v[136:137]
	v_mov_b32_e32 v138, v34
	v_mov_b32_e32 v139, v42
	v_pk_mul_f32 v[138:139], v[138:139], v[168:169]
	v_pk_mul_f32 v[136:137], v[136:137], s[78:79] op_sel_hi:[1,0]
	v_add_f32_e32 v131, v139, v138
	v_mov_b32_e32 v138, v43
	v_mov_b32_e32 v139, v35
	v_pk_mul_f32 v[138:139], v[138:139], v[170:171]
	v_mul_f32_e32 v167, 0x3e000000, v131
	v_mov_b32_e32 v183, v138
	v_mov_b32_e32 v185, v139
	v_pk_fma_f32 v[138:139], v[44:45], v[142:143], v[172:173] neg_lo:[0,0,1] neg_hi:[0,0,1]
	v_mov_b32_e32 v172, v35
	v_mov_b32_e32 v173, v43
	v_pk_mul_f32 v[170:171], v[172:173], v[170:171]
	v_pk_fma_f32 v[142:143], v[40:41], v[178:179], v[180:181] neg_lo:[0,0,1] neg_hi:[0,0,1]
	v_pk_add_f32 v[168:169], v[182:183], v[184:185] neg_lo:[0,1] neg_hi:[0,1]
	v_add_f32_e32 v131, v171, v170

; __device__ __forceinline__ u32x4 pack8(const float* v) { u32x4 w; w.x = cvt_pk_bf16(v[0], v[1]); w.y = cvt_pk_bf16(v[2], v[3]); w.z = cvt_pk_bf16(v[4], v[5]); w.w = cvt_pk_bf16(v[6], v[7]); return w; }
;     template <int NQ> __device__ __forceinline__ void roped(const float* rope, const f32x4 (&acc)[2][2][4][2], int row0, bool is_ctx, int rowb  , int axis, int j0,
;                                                              bf16_t* dst, int ld, int c1, int dx2, float sc, int cz  ) const {
;     ...
;                 if (!is_ctx) { const int t = row - rowb, pos = axis ? (t & 63) : (t >> 6); const f32x4* tp = (const f32x4*)(rope + (size_t)(pos * NQ + j0) * 2);
; #pragma unroll
;                     for (int q = 0; q < 4; ++q) { const f32x4 cs = tp[q];
; #pragma unroll
;                         for (int hh = 0; hh < 2; ++hh) { const int e = 2 * q + hh; const float c = hh ? cs[2] : cs[0], s = hh ? cs[3] : cs[1];
;                             const float x1 = acc[ai][0][m][e >> 2][e & 3], x2 = acc[ai][1][m][e >> 2][e & 3];
;                             y1[e] = (x1 * c - x2 * s) * sc; y2[e] = (x2 * c + x1 * s) * sc; } }
;                 } else {
; #pragma unroll
;                     for (int e = 0; e < 8; ++e) { y1[e] = acc[ai][0][m][e >> 2][e & 3] * sc; y2[e] = acc[ai][1][m][e >> 2][e & 3] * sc; }
;                 }
;                 bf16_t* rp = dst + (size_t)row * ld;
;                 *(u32x4*)(rp + c1) = pack8(y1); *(u32x4*)(rp + c1 + dx2) = pack8(y2);
;                 if (cz >= 0) { const u32x4 z = {0u, 0u, 0u, 0u}; *(u32x4*)(rp + cz) = z; *(u32x4*)(rp + cz + dx2) = z; }
.LBB0_423:
	s_or_b64 exec, exec, s[56:57]
	v_add_u32_e32 v130, 0xa0, v166
	s_and_b64 vcc, exec, s[14:15]
	s_mov_b64 s[38:39], -1
	s_cbranch_vccnz .LBB0_425
	v_subrev_u32_e32 v131, s61, v130
	v_and_b32_e32 v132, 63, v130
	v_ashrrev_i32_e32 v131, 6, v131
	v_cndmask_b32_e64 v131, v132, v131, s[12:13]
	v_lshl_or_b32 v132, v131, 4, v159
	v_ashrrev_i32_e32 v133, 31, v132
	v_lshl_add_u64 v[140:141], v[132:133], 3, s[68:69]
	flat_load_dwordx4 v[132:135], v[140:141]
	flat_load_dwordx4 v[168:171], v[140:141] offset:48
	flat_load_dwordx4 v[208:211], v[140:141] offset:16
	flat_load_dwordx4 v[212:215], v[140:141] offset:32
	s_mov_b64 s[38:39], 0
	s_waitcnt vmcnt(0) lgkmcnt(0)
	v_mov_b32_e32 v142, v132
	v_mov_b32_e32 v143, v134
	v_mov_b32_e32 v134, v133
	v_pk_mul_f32 v[132:133], v[20:21], v[142:143]
	v_pk_mul_f32 v[172:173], v[20:21], v[134:135]
	v_pk_fma_f32 v[132:133], v[28:29], v[134:135], v[132:133]
	v_mov_b32_e32 v134, v208
	v_mov_b32_e32 v135, v209
	v_mov_b32_e32 v136, v210
	v_mov_b32_e32 v137, v211
	v_mul_f32_e32 v182, v26, v168
	v_mul_f32_e32 v184, v18, v169
	v_pk_mul_f32 v[132:133], v[132:133], s[78:79] op_sel_hi:[1,0]
	s_waitcnt vmcnt(0) lgkmcnt(0)
	v_mov_b32_e32 v174, v134
	v_mov_b32_e32 v175, v136
	v_mov_b32_e32 v136, v135
	v_pk_mul_f32 v[134:135], v[22:23], v[174:175]
	v_pk_mul_f32 v[176:177], v[22:23], v[136:137]
	v_pk_fma_f32 v[134:135], v[30:31], v[136:137], v[134:135]
	v_mov_b32_e32 v136, v212
	v_mov_b32_e32 v137, v213
	v_mov_b32_e32 v138, v214
	v_mov_b32_e32 v139, v215
	v_pk_mul_f32 v[134:135], v[134:135], s[78:79] op_sel_hi:[1,0]
	v_pk_fma_f32 v[140:141], v[30:31], v[174:175], v[176:177] neg_lo:[0,0,1] neg_hi:[0,0,1]
	s_waitcnt vmcnt(0) lgkmcnt(0)
	v_mov_b32_e32 v178, v136
	v_mov_b32_e32 v179, v138
	v_mov_b32_e32 v138, v137
	v_pk_mul_f32 v[136:137], v[16:17], v[178:179]
	v_pk_mul_f32 v[180:181], v[16:17], v[138:139]
	v_pk_fma_f32 v[136:137], v[24:25], v[138:139], v[136:137]
	v_mov_b32_e32 v138, v18
	v_mov_b32_e32 v139, v26
	v_pk_mul_f32 v[138:139], v[138:139], v[168:169]
	v_pk_mul_f32 v[136:137], v[136:137], s[78:79] op_sel_hi:[1,0]
	v_add_f32_e32 v131, v139, v138
	v_mov_b32_e32 v138, v27
	v_mov_b32_e32 v139, v19
	v_pk_mul_f32 v[138:139], v[138:139], v[170:171]
	v_mul_f32_e32 v167, 0x3e000000, v131
	v_mov_b32_e32 v183, v138
	v_mov_b32_e32 v185, v139
	v_pk_fma_f32 v[138:139], v[28:29], v[142:143], v[172:173] neg_lo:[0,0,1] neg_hi:[0,0,1]
	v_mov_b32_e32 v172, v19
	v_mov_b32_e32 v173, v27
	v_pk_mul_f32 v[170:171], v[172:173], v[170:171]
	v_pk_fma_f32 v[142:143], v[24:25], v[178:179], v[180:181] neg_lo:[0,0,1] neg_hi:[0,0,1]
	v_pk_add_f32 v[168:169], v[182:183], v[184:185] neg_lo:[0,1] neg_hi:[0,1]
	v_add_f32_e32 v131, v171, v170

; __device__ __forceinline__ u32x4 pack8(const float* v) { u32x4 w; w.x = cvt_pk_bf16(v[0], v[1]); w.y = cvt_pk_bf16(v[2], v[3]); w.z = cvt_pk_bf16(v[4], v[5]); w.w = cvt_pk_bf16(v[6], v[7]); return w; }
;     template <int NQ> __device__ __forceinline__ void roped(const float* rope, const f32x4 (&acc)[2][2][4][2], int row0, bool is_ctx, int rowb  , int axis, int j0,
;                                                              bf16_t* dst, int ld, int c1, int dx2, float sc, int cz  ) const {
;     ...
;                 if (!is_ctx) { const int t = row - rowb, pos = axis ? (t & 63) : (t >> 6); const f32x4* tp = (const f32x4*)(rope + (size_t)(pos * NQ + j0) * 2);
; #pragma unroll
;                     for (int q = 0; q < 4; ++q) { const f32x4 cs = tp[q];
; #pragma unroll
;                         for (int hh = 0; hh < 2; ++hh) { const int e = 2 * q + hh; const float c = hh ? cs[2] : cs[0], s = hh ? cs[3] : cs[1];
;                             const float x1 = acc[ai][0][m][e >> 2][e & 3], x2 = acc[ai][1][m][e >> 2][e & 3];
;                             y1[e] = (x1 * c - x2 * s) * sc; y2[e] = (x2 * c + x1 * s) * sc; } }
;                 } else {
; #pragma unroll
;                     for (int e = 0; e < 8; ++e) { y1[e] = acc[ai][0][m][e >> 2][e & 3] * sc; y2[e] = acc[ai][1][m][e >> 2][e & 3] * sc; }
;                 }
;                 bf16_t* rp = dst + (size_t)row * ld;
;                 *(u32x4*)(rp + c1) = pack8(y1); *(u32x4*)(rp + c1 + dx2) = pack8(y2);
;                 if (cz >= 0) { const u32x4 z = {0u, 0u, 0u, 0u}; *(u32x4*)(rp + cz) = z; *(u32x4*)(rp + cz + dx2) = z; }
.LBB0_429:
	s_or_b64 exec, exec, s[56:57]
	v_add_u32_e32 v130, 0xb0, v166
	s_and_b64 vcc, exec, s[14:15]
	s_mov_b64 s[14:15], -1
	s_cbranch_vccnz .LBB0_431
	v_subrev_u32_e32 v131, s61, v130
	v_and_b32_e32 v132, 63, v130
	v_ashrrev_i32_e32 v131, 6, v131
	v_cndmask_b32_e64 v131, v132, v131, s[12:13]
	v_lshl_or_b32 v132, v131, 4, v159
	v_ashrrev_i32_e32 v133, 31, v132
	v_lshl_add_u64 v[140:141], v[132:133], 3, s[68:69]
	flat_load_dwordx4 v[132:135], v[140:141]
	flat_load_dwordx4 v[168:171], v[140:141] offset:48
	flat_load_dwordx4 v[208:211], v[140:141] offset:16
	flat_load_dwordx4 v[212:215], v[140:141] offset:32
	s_mov_b64 s[14:15], 0
	s_waitcnt vmcnt(0) lgkmcnt(0)
	v_mov_b32_e32 v142, v132
	v_mov_b32_e32 v143, v134
	v_mov_b32_e32 v134, v133
	v_pk_mul_f32 v[132:133], v[4:5], v[142:143]
	v_pk_mul_f32 v[172:173], v[4:5], v[134:135]
	v_pk_fma_f32 v[132:133], v[12:13], v[134:135], v[132:133]
	v_mov_b32_e32 v134, v208
	v_mov_b32_e32 v135, v209
	v_mov_b32_e32 v136, v210
	v_mov_b32_e32 v137, v211
	v_mul_f32_e32 v182, v10, v168
	v_mul_f32_e32 v184, v2, v169
	v_pk_mul_f32 v[132:133], v[132:133], s[78:79] op_sel_hi:[1,0]
	s_waitcnt vmcnt(0) lgkmcnt(0)
	v_mov_b32_e32 v174, v134
	v_mov_b32_e32 v175, v136
	v_mov_b32_e32 v136, v135
	v_pk_mul_f32 v[134:135], v[6:7], v[174:175]
	v_pk_mul_f32 v[176:177], v[6:7], v[136:137]
	v_pk_fma_f32 v[134:135], v[14:15], v[136:137], v[134:135]
	v_mov_b32_e32 v136, v212
	v_mov_b32_e32 v137, v213
	v_mov_b32_e32 v138, v214
	v_mov_b32_e32 v139, v215
	v_pk_mul_f32 v[134:135], v[134:135], s[78:79] op_sel_hi:[1,0]
	v_pk_fma_f32 v[140:141], v[14:15], v[174:175], v[176:177] neg_lo:[0,0,1] neg_hi:[0,0,1]
	s_waitcnt vmcnt(0) lgkmcnt(0)
	v_mov_b32_e32 v178, v136
	v_mov_b32_e32 v179, v138
	v_mov_b32_e32 v138, v137
	v_pk_mul_f32 v[136:137], v[0:1], v[178:179]
	v_pk_mul_f32 v[180:181], v[0:1], v[138:139]
	v_pk_fma_f32 v[136:137], v[8:9], v[138:139], v[136:137]
	v_mov_b32_e32 v138, v2
	v_mov_b32_e32 v139, v10
	v_pk_mul_f32 v[138:139], v[138:139], v[168:169]
	v_pk_mul_f32 v[136:137], v[136:137], s[78:79] op_sel_hi:[1,0]
	v_add_f32_e32 v131, v139, v138
	v_mov_b32_e32 v138, v11
	v_mov_b32_e32 v139, v3
	v_pk_mul_f32 v[138:139], v[138:139], v[170:171]
	v_mul_f32_e32 v167, 0x3e000000, v131
	v_mov_b32_e32 v183, v138
	v_mov_b32_e32 v185, v139
	v_pk_fma_f32 v[138:139], v[12:13], v[142:143], v[172:173] neg_lo:[0,0,1] neg_hi:[0,0,1]
	v_mov_b32_e32 v172, v3
	v_mov_b32_e32 v173, v11
	v_pk_mul_f32 v[170:171], v[172:173], v[170:171]
	v_pk_fma_f32 v[142:143], v[8:9], v[178:179], v[180:181] neg_lo:[0,0,1] neg_hi:[0,0,1]
	v_pk_add_f32 v[168:169], v[182:183], v[184:185] neg_lo:[0,1] neg_hi:[0,1]
	v_add_f32_e32 v131, v171, v170
